# GEMM K loops: s_setprio 1/0 toggles around the MFMA runs removed (both ping-pong halves at equal priority)
# speedup vs baseline: 1.0100x; 1.0031x over previous
; #define PG8_STAGE(bufoff, gbase, voff) do { _Pragma("unroll") for (int _i = 0; _i < 2; ++_i) \
;     __builtin_amdgcn_global_load_lds((const unsigned*)((const char*)(gbase) + (voff)[_i]), (LAS unsigned*)(lds + (bufoff) + ldsw + _i * 8192), 16, 0, 0); } while (0)
; #define PG8_LDA(dst, b, h) do { _Pragma("unroll") for (int m = 0; m < 4; ++m) _Pragma("unroll") for (int k = 0; k < 2; ++k) dst[m][k] = *(const LAS bf16x8*)(lds + PG8_SA(b, h) + aoff + m * 2048 + k * 1024); } while (0)
; #define PG8_LDB(dst, b, h) do { _Pragma("unroll") for (int n = 0; n < 2; ++n) _Pragma("unroll") for (int k = 0; k < 2; ++k) dst[n][k] = *(const LAS bf16x8*)(lds + PG8_SB(b, h) + boff + n * 2048 + k * 1024); } while (0)
; #define PG8_MMA(ai, bj, At, Bt) do { __builtin_amdgcn_s_setprio(1); _Pragma("unroll") for (int m = 0; m < 4; ++m) _Pragma("unroll") for (int n = 0; n < 2; ++n) _Pragma("unroll") for (int k = 0; k < 2; ++k) \
;     acc[ai][bj][m][n] = __builtin_amdgcn_mfma_f32_16x16x32_bf16(Bt[n][k], At[m][k], acc[ai][bj][m][n], 0, 0, 0); __builtin_amdgcn_s_setprio(0); } while (0)
; #define PG8_WAIT_L(n) asm volatile("s_waitcnt lgkmcnt(" #n ")" ::: "memory")
; #define PG8_BAR __builtin_amdgcn_s_barrier()
; #define PG8_SCHED __builtin_amdgcn_sched_barrier(0)
; template <class Epi, class Sched>
; DI void gemm_phase(LAS unsigned char* lds, const Gemm g, const Sched& S, const Epi& E) {
;     ...
;       PG8_LDB(B0, 0, 0); PG8_SCHED; PG8_LDA(At, 0, 0); PG8_STAGE(PG8_SA(1, 1), a1 + hstep, voffA);
;       PG8_WAIT_L(8); PG8_BAR; PG8_WAIT_L(0); PG8_MMA(0, 0, At, B0); PG8_BAR; PG8_SCHED;
;       PG8_LDB(B1, 0, 1); PG8_STAGE(PG8_SB(0, 0), b2, voffB);
;       PG8_BAR; PG8_WAIT_L(0); PG8_MMA(0, 1, At, B1); PG8_BAR;
;       PG8_LDA(At, 0, 1); PG8_STAGE(PG8_SA(0, 0), a2, voffA);
;       PG8_BAR; PG8_WAIT_L(0); PG8_MMA(1, 0, At, B0); PG8_BAR; PG8_SCHED;
.LBB0_137:
	s_add_i32 s41, s1, 2
	s_add_u32 s18, s16, 0x80
	s_addc_u32 s19, s17, 0
	s_cmp_lg_u32 s40, s1
	s_cselect_b32 s20, s18, 0
	s_cselect_b32 s1, s19, 0
	s_add_u32 s18, s14, s20
	s_addc_u32 s19, s15, s1
	s_add_i32 s42, 16, 0x10000
	v_add_u32_e32 v139, s42, v137
	ds_read_b128 v[140:143], v139
	ds_read_b128 v[144:147], v139 offset:1024
	ds_read_b128 v[150:153], v139 offset:2048
	ds_read_b128 v[154:157], v139 offset:3072
	s_add_u32 s20, s12, s20
	s_addc_u32 s21, s13, s1
	v_lshl_add_u64 v[180:181], v[132:133], 0, s[16:17]
	s_add_i32 m0, s31, 0xc000
	ds_read_b128 v[158:161], v138
	ds_read_b128 v[162:165], v138 offset:1024
	ds_read_b128 v[166:169], v138 offset:2048
	ds_read_b128 v[170:173], v138 offset:3072
	ds_read_b128 v[174:177], v138 offset:4096
	ds_read_b128 v[186:189], v138 offset:5120
	ds_read_b128 v[190:193], v138 offset:6144
	ds_read_b128 v[198:201], v138 offset:7168
	global_load_lds_dwordx4 v[180:181], off
	v_lshl_add_u64 v[180:181], v[134:135], 0, s[16:17]
	s_add_i32 m0, s31, 0xe000
	s_nop 0
	global_load_lds_dwordx4 v[180:181], off
	s_waitcnt lgkmcnt(8)
	s_barrier
	s_waitcnt lgkmcnt(0)
	s_waitcnt lgkmcnt(0)
	v_mfma_f32_16x16x32_bf16 v[126:129], v[140:143], v[158:161], v[126:129]
	v_mfma_f32_16x16x32_bf16 v[122:125], v[150:153], v[158:161], v[122:125]
	v_mfma_f32_16x16x32_bf16 v[110:113], v[140:143], v[166:169], v[110:113]
	v_mfma_f32_16x16x32_bf16 v[106:109], v[150:153], v[166:169], v[106:109]
	v_mfma_f32_16x16x32_bf16 v[94:97], v[140:143], v[174:177], v[94:97]
	v_mfma_f32_16x16x32_bf16 v[90:93], v[150:153], v[174:177], v[90:93]
	v_mfma_f32_16x16x32_bf16 v[78:81], v[140:143], v[190:193], v[78:81]
	v_mfma_f32_16x16x32_bf16 v[74:77], v[150:153], v[190:193], v[74:77]
	v_mfma_f32_16x16x32_bf16 v[126:129], v[144:147], v[162:165], v[126:129]
	v_mfma_f32_16x16x32_bf16 v[122:125], v[154:157], v[162:165], v[122:125]
	v_mfma_f32_16x16x32_bf16 v[110:113], v[144:147], v[170:173], v[110:113]
	v_mfma_f32_16x16x32_bf16 v[106:109], v[154:157], v[170:173], v[106:109]
	v_mfma_f32_16x16x32_bf16 v[94:97], v[144:147], v[186:189], v[94:97]
	v_mfma_f32_16x16x32_bf16 v[90:93], v[154:157], v[186:189], v[90:93]
	v_mfma_f32_16x16x32_bf16 v[78:81], v[144:147], v[198:201], v[78:81]
	v_mfma_f32_16x16x32_bf16 v[74:77], v[154:157], v[198:201], v[74:77]
	s_barrier
	s_add_i32 s1, 16, 0x14000
	s_add_i32 s42, s42, s30
	v_add_u32_e32 v139, s1, v137
	v_lshl_add_u64 v[180:181], s[20:21], 0, v[0:1]
	s_mov_b32 m0, s42
	ds_read_b128 v[202:205], v139
	ds_read_b128 v[206:209], v139 offset:1024
	ds_read_b128 v[214:217], v139 offset:2048
	ds_read_b128 v[218:221], v139 offset:3072
	global_load_lds_dwordx4 v[180:181], off
	v_lshl_add_u64 v[182:183], s[20:21], 0, v[130:131]
	s_add_i32 m0, s42, 0x2000
	s_nop 0
	global_load_lds_dwordx4 v[182:183], off
	s_barrier
	s_waitcnt lgkmcnt(0)
	s_waitcnt lgkmcnt(0)
	v_mfma_f32_16x16x32_bf16 v[118:121], v[202:205], v[158:161], v[118:121]
	v_mfma_f32_16x16x32_bf16 v[114:117], v[214:217], v[158:161], v[114:117]
	v_mfma_f32_16x16x32_bf16 v[102:105], v[202:205], v[166:169], v[102:105]
	v_mfma_f32_16x16x32_bf16 v[98:101], v[214:217], v[166:169], v[98:101]
	v_mfma_f32_16x16x32_bf16 v[86:89], v[202:205], v[174:177], v[86:89]
	v_mfma_f32_16x16x32_bf16 v[82:85], v[214:217], v[174:177], v[82:85]
	v_mfma_f32_16x16x32_bf16 v[70:73], v[202:205], v[190:193], v[70:73]
	v_mfma_f32_16x16x32_bf16 v[66:69], v[214:217], v[190:193], v[66:69]
	v_mfma_f32_16x16x32_bf16 v[118:121], v[206:209], v[162:165], v[118:121]
	v_mfma_f32_16x16x32_bf16 v[114:117], v[218:221], v[162:165], v[114:117]
	v_mfma_f32_16x16x32_bf16 v[102:105], v[206:209], v[170:173], v[102:105]
	v_mfma_f32_16x16x32_bf16 v[98:101], v[218:221], v[170:173], v[98:101]
	v_mfma_f32_16x16x32_bf16 v[86:89], v[206:209], v[186:189], v[86:89]
	v_mfma_f32_16x16x32_bf16 v[82:85], v[218:221], v[186:189], v[82:85]
	v_mfma_f32_16x16x32_bf16 v[70:73], v[206:209], v[198:201], v[70:73]
	v_mfma_f32_16x16x32_bf16 v[66:69], v[218:221], v[198:201], v[66:69]
	s_mov_b32 m0, s31
	v_lshl_add_u64 v[184:185], s[18:19], 0, v[0:1]
	s_barrier
	ds_read_b128 v[158:161], v138 offset:16384
	ds_read_b128 v[162:165], v138 offset:17408
	ds_read_b128 v[166:169], v138 offset:18432
	ds_read_b128 v[170:173], v138 offset:19456
	ds_read_b128 v[174:177], v138 offset:20480
	ds_read_b128 v[186:189], v138 offset:21504
	ds_read_b128 v[190:193], v138 offset:22528
	ds_read_b128 v[198:201], v138 offset:23552
	global_load_lds_dwordx4 v[184:185], off
	v_lshl_add_u64 v[222:223], s[18:19], 0, v[130:131]
	s_mov_b32 m0, s34
	s_nop 0
	global_load_lds_dwordx4 v[222:223], off
	s_barrier
	s_waitcnt lgkmcnt(0)
	s_waitcnt lgkmcnt(0)
	v_mfma_f32_16x16x32_bf16 v[62:65], v[140:143], v[158:161], v[62:65]
	v_mfma_f32_16x16x32_bf16 v[58:61], v[150:153], v[158:161], v[58:61]
	v_mfma_f32_16x16x32_bf16 v[46:49], v[140:143], v[166:169], v[46:49]
	v_mfma_f32_16x16x32_bf16 v[42:45], v[150:153], v[166:169], v[42:45]
	v_mfma_f32_16x16x32_bf16 v[30:33], v[140:143], v[174:177], v[30:33]
	v_mfma_f32_16x16x32_bf16 v[26:29], v[150:153], v[174:177], v[26:29]
	v_mfma_f32_16x16x32_bf16 v[14:17], v[140:143], v[190:193], v[14:17]
	v_mfma_f32_16x16x32_bf16 v[10:13], v[150:153], v[190:193], v[10:13]
	v_mfma_f32_16x16x32_bf16 v[62:65], v[144:147], v[162:165], v[62:65]
	v_mfma_f32_16x16x32_bf16 v[58:61], v[154:157], v[162:165], v[58:61]
	v_mfma_f32_16x16x32_bf16 v[46:49], v[144:147], v[170:173], v[46:49]
	v_mfma_f32_16x16x32_bf16 v[42:45], v[154:157], v[170:173], v[42:45]
	v_mfma_f32_16x16x32_bf16 v[30:33], v[144:147], v[186:189], v[30:33]
	v_mfma_f32_16x16x32_bf16 v[26:29], v[154:157], v[186:189], v[26:29]
	v_mfma_f32_16x16x32_bf16 v[14:17], v[144:147], v[198:201], v[14:17]
	v_mfma_f32_16x16x32_bf16 v[10:13], v[154:157], v[198:201], v[10:13]
	s_barrier
; #define PG8_STAGE(bufoff, gbase, voff) do { _Pragma("unroll") for (int _i = 0; _i < 2; ++_i) \
;     __builtin_amdgcn_global_load_lds((const unsigned*)((const char*)(gbase) + (voff)[_i]), (LAS unsigned*)(lds + (bufoff) + ldsw + _i * 8192), 16, 0, 0); } while (0)
; #define PG8_LDA(dst, b, h) do { _Pragma("unroll") for (int m = 0; m < 4; ++m) _Pragma("unroll") for (int k = 0; k < 2; ++k) dst[m][k] = *(const LAS bf16x8*)(lds + PG8_SA(b, h) + aoff + m * 2048 + k * 1024); } while (0)
; #define PG8_LDB(dst, b, h) do { _Pragma("unroll") for (int n = 0; n < 2; ++n) _Pragma("unroll") for (int k = 0; k < 2; ++k) dst[n][k] = *(const LAS bf16x8*)(lds + PG8_SB(b, h) + boff + n * 2048 + k * 1024); } while (0)
; #define PG8_MMA(ai, bj, At, Bt) do { __builtin_amdgcn_s_setprio(1); _Pragma("unroll") for (int m = 0; m < 4; ++m) _Pragma("unroll") for (int n = 0; n < 2; ++n) _Pragma("unroll") for (int k = 0; k < 2; ++k) \
;     acc[ai][bj][m][n] = __builtin_amdgcn_mfma_f32_16x16x32_bf16(Bt[n][k], At[m][k], acc[ai][bj][m][n], 0, 0, 0); __builtin_amdgcn_s_setprio(0); } while (0)
; #define PG8_WAIT_V(n) asm volatile("s_waitcnt vmcnt(" #n ")" ::: "memory")
; #define PG8_WAIT_L(n) asm volatile("s_waitcnt lgkmcnt(" #n ")" ::: "memory")
; #define PG8_BAR __builtin_amdgcn_s_barrier()
; #define PG8_SCHED __builtin_amdgcn_sched_barrier(0)
; template <class Epi, class Sched>
; DI void gemm_phase(LAS unsigned char* lds, const Gemm g, const Sched& S, const Epi& E) {
;     ...
;       PG8_STAGE(PG8_SB(0, 1), b2 + hstepB, voffB);
;       PG8_WAIT_V(6); PG8_BAR; PG8_MMA(1, 1, At, B1); PG8_BAR;
;       PG8_LDB(B0, 1, 0); PG8_SCHED; PG8_LDA(At, 1, 0); PG8_STAGE(PG8_SA(0, 1), a2 + hstep, voffA);
;       PG8_WAIT_L(8); PG8_BAR; PG8_WAIT_L(0); PG8_MMA(0, 0, At, B0); PG8_BAR; PG8_SCHED;
;       PG8_LDB(B1, 1, 1); PG8_STAGE(PG8_SB(1, 0), b3, voffB);
;       PG8_BAR; PG8_WAIT_L(0); PG8_MMA(0, 1, At, B1); PG8_BAR;
	s_add_u32 s20, s20, s2
	s_addc_u32 s21, s21, s3
	s_add_i32 s1, s1, s30
	v_lshl_add_u64 v[224:225], s[20:21], 0, v[0:1]
	s_mov_b32 m0, s1
	v_lshl_add_u64 v[226:227], s[20:21], 0, v[130:131]
	global_load_lds_dwordx4 v[224:225], off
	s_add_i32 m0, s1, 0x2000
	s_nop 0
	global_load_lds_dwordx4 v[226:227], off
	s_waitcnt vmcnt(6)
	s_barrier
	v_mfma_f32_16x16x32_bf16 v[54:57], v[202:205], v[158:161], v[54:57]
	v_mfma_f32_16x16x32_bf16 v[50:53], v[214:217], v[158:161], v[50:53]
	v_mfma_f32_16x16x32_bf16 v[38:41], v[202:205], v[166:169], v[38:41]
	v_mfma_f32_16x16x32_bf16 v[34:37], v[214:217], v[166:169], v[34:37]
	v_mfma_f32_16x16x32_bf16 v[22:25], v[202:205], v[174:177], v[22:25]
	v_mfma_f32_16x16x32_bf16 v[18:21], v[214:217], v[174:177], v[18:21]
	v_mfma_f32_16x16x32_bf16 v[6:9], v[202:205], v[190:193], v[6:9]
	v_mfma_f32_16x16x32_bf16 v[2:5], v[214:217], v[190:193], v[2:5]
	v_mfma_f32_16x16x32_bf16 v[54:57], v[206:209], v[162:165], v[54:57]
	v_mfma_f32_16x16x32_bf16 v[50:53], v[218:221], v[162:165], v[50:53]
	v_mfma_f32_16x16x32_bf16 v[38:41], v[206:209], v[170:173], v[38:41]
	v_mfma_f32_16x16x32_bf16 v[34:37], v[218:221], v[170:173], v[34:37]
	v_mfma_f32_16x16x32_bf16 v[22:25], v[206:209], v[186:189], v[22:25]
	v_mfma_f32_16x16x32_bf16 v[18:21], v[218:221], v[186:189], v[18:21]
	v_mfma_f32_16x16x32_bf16 v[6:9], v[206:209], v[198:201], v[6:9]
	v_mfma_f32_16x16x32_bf16 v[2:5], v[218:221], v[198:201], v[2:5]
	s_add_i32 s1, 16, 0x18000
	v_add_u32_e32 v139, s1, v137
	s_barrier
	ds_read_b128 v[140:143], v139
	ds_read_b128 v[144:147], v139 offset:1024
	ds_read_b128 v[150:153], v139 offset:2048
	ds_read_b128 v[154:157], v139 offset:3072
	s_add_u32 s18, s18, s2
	s_addc_u32 s19, s19, s3
	s_mov_b32 m0, s35
	v_lshl_add_u64 v[202:203], s[18:19], 0, v[0:1]
	ds_read_b128 v[158:161], v138 offset:32768
	ds_read_b128 v[162:165], v138 offset:33792
	ds_read_b128 v[166:169], v138 offset:34816
	ds_read_b128 v[170:173], v138 offset:35840
	ds_read_b128 v[174:177], v138 offset:36864
	ds_read_b128 v[186:189], v138 offset:37888
	ds_read_b128 v[190:193], v138 offset:38912
	ds_read_b128 v[198:201], v138 offset:39936
	global_load_lds_dwordx4 v[202:203], off
	v_lshl_add_u64 v[202:203], s[18:19], 0, v[130:131]
	s_mov_b32 m0, s36
	s_nop 0
	global_load_lds_dwordx4 v[202:203], off
	s_waitcnt lgkmcnt(8)
	s_barrier
	s_waitcnt lgkmcnt(0)
	s_waitcnt lgkmcnt(0)
	v_mfma_f32_16x16x32_bf16 v[126:129], v[140:143], v[158:161], v[126:129]
	v_mfma_f32_16x16x32_bf16 v[122:125], v[150:153], v[158:161], v[122:125]
	v_mfma_f32_16x16x32_bf16 v[110:113], v[140:143], v[166:169], v[110:113]
	v_mfma_f32_16x16x32_bf16 v[106:109], v[150:153], v[166:169], v[106:109]
	v_mfma_f32_16x16x32_bf16 v[94:97], v[140:143], v[174:177], v[94:97]
	v_mfma_f32_16x16x32_bf16 v[90:93], v[150:153], v[174:177], v[90:93]
	v_mfma_f32_16x16x32_bf16 v[78:81], v[140:143], v[190:193], v[78:81]
	v_mfma_f32_16x16x32_bf16 v[74:77], v[150:153], v[190:193], v[74:77]
	v_mfma_f32_16x16x32_bf16 v[126:129], v[144:147], v[162:165], v[126:129]
	v_mfma_f32_16x16x32_bf16 v[122:125], v[154:157], v[162:165], v[122:125]
	v_mfma_f32_16x16x32_bf16 v[110:113], v[144:147], v[170:173], v[110:113]
	v_mfma_f32_16x16x32_bf16 v[106:109], v[154:157], v[170:173], v[106:109]
	v_mfma_f32_16x16x32_bf16 v[94:97], v[144:147], v[186:189], v[94:97]
	v_mfma_f32_16x16x32_bf16 v[90:93], v[154:157], v[186:189], v[90:93]
	v_mfma_f32_16x16x32_bf16 v[78:81], v[144:147], v[198:201], v[78:81]
	v_mfma_f32_16x16x32_bf16 v[74:77], v[154:157], v[198:201], v[74:77]
	s_barrier
	s_add_i32 s18, 16, 0x1c000
	s_add_i32 s1, s1, s30
	v_add_u32_e32 v139, s18, v137
	v_lshl_add_u64 v[180:181], v[180:181], 0, s[70:71]
	s_mov_b32 m0, s1
	ds_read_b128 v[202:205], v139
	ds_read_b128 v[206:209], v139 offset:1024
	ds_read_b128 v[214:217], v139 offset:2048
	ds_read_b128 v[218:221], v139 offset:3072
	global_load_lds_dwordx4 v[180:181], off
	v_lshl_add_u64 v[180:181], v[182:183], 0, s[70:71]
	s_add_i32 m0, s1, 0x2000
	s_nop 0
	global_load_lds_dwordx4 v[180:181], off
	s_barrier
; #define PG8_STAGE(bufoff, gbase, voff) do { _Pragma("unroll") for (int _i = 0; _i < 2; ++_i) \
;     __builtin_amdgcn_global_load_lds((const unsigned*)((const char*)(gbase) + (voff)[_i]), (LAS unsigned*)(lds + (bufoff) + ldsw + _i * 8192), 16, 0, 0); } while (0)
; #define PG8_LDA(dst, b, h) do { _Pragma("unroll") for (int m = 0; m < 4; ++m) _Pragma("unroll") for (int k = 0; k < 2; ++k) dst[m][k] = *(const LAS bf16x8*)(lds + PG8_SA(b, h) + aoff + m * 2048 + k * 1024); } while (0)
; #define PG8_MMA(ai, bj, At, Bt) do { __builtin_amdgcn_s_setprio(1); _Pragma("unroll") for (int m = 0; m < 4; ++m) _Pragma("unroll") for (int n = 0; n < 2; ++n) _Pragma("unroll") for (int k = 0; k < 2; ++k) \
;     acc[ai][bj][m][n] = __builtin_amdgcn_mfma_f32_16x16x32_bf16(Bt[n][k], At[m][k], acc[ai][bj][m][n], 0, 0, 0); __builtin_amdgcn_s_setprio(0); } while (0)
; #define PG8_WAIT_V(n) asm volatile("s_waitcnt vmcnt(" #n ")" ::: "memory")
; #define PG8_WAIT_L(n) asm volatile("s_waitcnt lgkmcnt(" #n ")" ::: "memory")
; #define PG8_BAR __builtin_amdgcn_s_barrier()
; #define PG8_SCHED __builtin_amdgcn_sched_barrier(0)
; template <class Epi, class Sched>
; DI void gemm_phase(LAS unsigned char* lds, const Gemm g, const Sched& S, const Epi& E) {
;     ...
;       PG8_BAR; PG8_WAIT_L(0); PG8_MMA(0, 1, At, B1); PG8_BAR;
;       PG8_LDA(At, 1, 1); PG8_STAGE(PG8_SA(1, 0), a3, voffA);
;       PG8_BAR; PG8_WAIT_L(0); PG8_MMA(1, 0, At, B0); PG8_BAR; PG8_SCHED;
;       PG8_STAGE(PG8_SB(1, 1), b3 + hstepB, voffB);
;       PG8_WAIT_V(6); PG8_BAR; PG8_MMA(1, 1, At, B1); PG8_BAR;
;     }
	s_waitcnt lgkmcnt(0)
	s_waitcnt lgkmcnt(0)
	v_mfma_f32_16x16x32_bf16 v[118:121], v[202:205], v[158:161], v[118:121]
	v_mfma_f32_16x16x32_bf16 v[114:117], v[214:217], v[158:161], v[114:117]
	v_mfma_f32_16x16x32_bf16 v[102:105], v[202:205], v[166:169], v[102:105]
	v_mfma_f32_16x16x32_bf16 v[98:101], v[214:217], v[166:169], v[98:101]
	v_mfma_f32_16x16x32_bf16 v[86:89], v[202:205], v[174:177], v[86:89]
	v_mfma_f32_16x16x32_bf16 v[82:85], v[214:217], v[174:177], v[82:85]
	v_mfma_f32_16x16x32_bf16 v[70:73], v[202:205], v[190:193], v[70:73]
	v_mfma_f32_16x16x32_bf16 v[66:69], v[214:217], v[190:193], v[66:69]
	v_mfma_f32_16x16x32_bf16 v[118:121], v[206:209], v[162:165], v[118:121]
	v_mfma_f32_16x16x32_bf16 v[114:117], v[218:221], v[162:165], v[114:117]
	v_mfma_f32_16x16x32_bf16 v[102:105], v[206:209], v[170:173], v[102:105]
	v_mfma_f32_16x16x32_bf16 v[98:101], v[218:221], v[170:173], v[98:101]
	v_mfma_f32_16x16x32_bf16 v[86:89], v[206:209], v[186:189], v[86:89]
	v_mfma_f32_16x16x32_bf16 v[82:85], v[218:221], v[186:189], v[82:85]
	v_mfma_f32_16x16x32_bf16 v[70:73], v[206:209], v[198:201], v[70:73]
	v_mfma_f32_16x16x32_bf16 v[66:69], v[218:221], v[198:201], v[66:69]
	s_mov_b32 m0, s37
	v_lshl_add_u64 v[180:181], v[184:185], 0, s[70:71]
	s_barrier
	ds_read_b128 v[158:161], v138 offset:49152
	ds_read_b128 v[162:165], v138 offset:50176
	ds_read_b128 v[166:169], v138 offset:51200
	ds_read_b128 v[170:173], v138 offset:52224
	ds_read_b128 v[174:177], v138 offset:53248
	ds_read_b128 v[186:189], v138 offset:54272
	ds_read_b128 v[190:193], v138 offset:55296
	ds_read_b128 v[198:201], v138 offset:56320
	global_load_lds_dwordx4 v[180:181], off
	v_lshl_add_u64 v[180:181], v[222:223], 0, s[70:71]
	s_mov_b32 m0, s38
	s_nop 0
	global_load_lds_dwordx4 v[180:181], off
	s_barrier
	s_waitcnt lgkmcnt(0)
	s_waitcnt lgkmcnt(0)
	v_mfma_f32_16x16x32_bf16 v[62:65], v[140:143], v[158:161], v[62:65]
	v_mfma_f32_16x16x32_bf16 v[58:61], v[150:153], v[158:161], v[58:61]
	v_mfma_f32_16x16x32_bf16 v[46:49], v[140:143], v[166:169], v[46:49]
	v_mfma_f32_16x16x32_bf16 v[42:45], v[150:153], v[166:169], v[42:45]
	v_mfma_f32_16x16x32_bf16 v[30:33], v[140:143], v[174:177], v[30:33]
	v_mfma_f32_16x16x32_bf16 v[26:29], v[150:153], v[174:177], v[26:29]
	v_mfma_f32_16x16x32_bf16 v[14:17], v[140:143], v[190:193], v[14:17]
	v_mfma_f32_16x16x32_bf16 v[10:13], v[150:153], v[190:193], v[10:13]
	v_mfma_f32_16x16x32_bf16 v[62:65], v[144:147], v[162:165], v[62:65]
	v_mfma_f32_16x16x32_bf16 v[58:61], v[154:157], v[162:165], v[58:61]
	v_mfma_f32_16x16x32_bf16 v[46:49], v[144:147], v[170:173], v[46:49]
	v_mfma_f32_16x16x32_bf16 v[42:45], v[154:157], v[170:173], v[42:45]
	v_mfma_f32_16x16x32_bf16 v[30:33], v[144:147], v[186:189], v[30:33]
	v_mfma_f32_16x16x32_bf16 v[26:29], v[154:157], v[186:189], v[26:29]
	v_mfma_f32_16x16x32_bf16 v[14:17], v[144:147], v[198:201], v[14:17]
	v_mfma_f32_16x16x32_bf16 v[10:13], v[154:157], v[198:201], v[10:13]
	s_barrier
	s_add_i32 s1, s18, s30
	v_lshl_add_u64 v[140:141], v[224:225], 0, s[70:71]
	s_mov_b32 m0, s1
	s_nop 0
	global_load_lds_dwordx4 v[140:141], off
	v_lshl_add_u64 v[140:141], v[226:227], 0, s[70:71]
	s_add_i32 m0, s1, 0x2000
	s_nop 0
	global_load_lds_dwordx4 v[140:141], off
	s_waitcnt vmcnt(6)
	s_barrier
	v_mfma_f32_16x16x32_bf16 v[54:57], v[202:205], v[158:161], v[54:57]
	v_mfma_f32_16x16x32_bf16 v[50:53], v[214:217], v[158:161], v[50:53]
	v_mfma_f32_16x16x32_bf16 v[38:41], v[202:205], v[166:169], v[38:41]
	v_mfma_f32_16x16x32_bf16 v[34:37], v[214:217], v[166:169], v[34:37]
	v_mfma_f32_16x16x32_bf16 v[22:25], v[202:205], v[174:177], v[22:25]
	v_mfma_f32_16x16x32_bf16 v[18:21], v[214:217], v[174:177], v[18:21]
	v_mfma_f32_16x16x32_bf16 v[6:9], v[202:205], v[190:193], v[6:9]
	v_mfma_f32_16x16x32_bf16 v[2:5], v[214:217], v[190:193], v[2:5]
	v_mfma_f32_16x16x32_bf16 v[54:57], v[206:209], v[162:165], v[54:57]
	v_mfma_f32_16x16x32_bf16 v[50:53], v[218:221], v[162:165], v[50:53]
	v_mfma_f32_16x16x32_bf16 v[38:41], v[206:209], v[170:173], v[38:41]
	v_mfma_f32_16x16x32_bf16 v[34:37], v[218:221], v[170:173], v[34:37]
	v_mfma_f32_16x16x32_bf16 v[22:25], v[206:209], v[186:189], v[22:25]
	v_mfma_f32_16x16x32_bf16 v[18:21], v[218:221], v[186:189], v[18:21]
	v_mfma_f32_16x16x32_bf16 v[6:9], v[206:209], v[198:201], v[6:9]
	v_mfma_f32_16x16x32_bf16 v[2:5], v[218:221], v[198:201], v[2:5]
	s_add_u32 s16, s16, 0x100
	s_addc_u32 s17, s17, 0
	s_cmp_ge_i32 s41, s39
	s_mov_b32 s1, s41
	s_barrier
	s_cbranch_scc0 .LBB0_137

; #define PG8_STAGE(bufoff, gbase, voff) do { _Pragma("unroll") for (int _i = 0; _i < 2; ++_i) \
;     __builtin_amdgcn_global_load_lds((const unsigned*)((const char*)(gbase) + (voff)[_i]), (LAS unsigned*)(lds + (bufoff) + ldsw + _i * 8192), 16, 0, 0); } while (0)
; #define PG8_LDA(dst, b, h) do { _Pragma("unroll") for (int m = 0; m < 4; ++m) _Pragma("unroll") for (int k = 0; k < 2; ++k) dst[m][k] = *(const LAS bf16x8*)(lds + PG8_SA(b, h) + aoff + m * 2048 + k * 1024); } while (0)
; #define PG8_LDB(dst, b, h) do { _Pragma("unroll") for (int n = 0; n < 2; ++n) _Pragma("unroll") for (int k = 0; k < 2; ++k) dst[n][k] = *(const LAS bf16x8*)(lds + PG8_SB(b, h) + boff + n * 2048 + k * 1024); } while (0)
; #define PG8_MMA(ai, bj, At, Bt) do { __builtin_amdgcn_s_setprio(1); _Pragma("unroll") for (int m = 0; m < 4; ++m) _Pragma("unroll") for (int n = 0; n < 2; ++n) _Pragma("unroll") for (int k = 0; k < 2; ++k) \
;     acc[ai][bj][m][n] = __builtin_amdgcn_mfma_f32_16x16x32_bf16(Bt[n][k], At[m][k], acc[ai][bj][m][n], 0, 0, 0); __builtin_amdgcn_s_setprio(0); } while (0)
; #define PG8_WAIT_L(n) asm volatile("s_waitcnt lgkmcnt(" #n ")" ::: "memory")
; #define PG8_BAR __builtin_amdgcn_s_barrier()
; #define PG8_SCHED __builtin_amdgcn_sched_barrier(0)
; template <class Epi, class Sched>
; DI void gemm_phase(LAS unsigned char* lds, const Gemm g, const Sched& S, const Epi& E) {
;     ...
;       PG8_LDB(B0, 0, 0); PG8_SCHED; PG8_LDA(At, 0, 0); PG8_STAGE(PG8_SA(1, 1), a1 + hstep, voffA);
;       PG8_WAIT_L(8); PG8_BAR; PG8_WAIT_L(0); PG8_MMA(0, 0, At, B0); PG8_BAR; PG8_SCHED;
;       PG8_LDB(B1, 0, 1); PG8_STAGE(PG8_SB(0, 0), b2, voffB);
;       PG8_BAR; PG8_WAIT_L(0); PG8_MMA(0, 1, At, B1); PG8_BAR;
;       PG8_LDA(At, 0, 1); PG8_STAGE(PG8_SA(0, 0), a2, voffA);
;       PG8_BAR; PG8_WAIT_L(0); PG8_MMA(1, 0, At, B0); PG8_BAR; PG8_SCHED;
.LBB0_153:
	s_add_i32 s36, s16, 2
	s_add_u32 s17, s14, 0xfa800080
	s_addc_u32 s18, s15, -1
	s_cmp_lg_u32 s35, s16
	s_cselect_b32 s19, s18, 0
	s_cselect_b32 s18, s17, 0
	s_add_u32 s16, s12, s18
	s_addc_u32 s17, s13, s19
	s_add_i32 s37, 16, 0x10000
	v_add_u32_e32 v139, s37, v137
	ds_read_b128 v[140:143], v139
	ds_read_b128 v[144:147], v139 offset:1024
	ds_read_b128 v[150:153], v139 offset:2048
	ds_read_b128 v[154:157], v139 offset:3072
	s_add_u32 s18, s2, s18
	s_addc_u32 s19, s3, s19
	v_lshl_add_u64 v[180:181], v[132:133], 0, s[14:15]
	s_add_i32 m0, s24, 0xc000
	ds_read_b128 v[158:161], v138
	ds_read_b128 v[162:165], v138 offset:1024
	ds_read_b128 v[166:169], v138 offset:2048
	ds_read_b128 v[170:173], v138 offset:3072
	ds_read_b128 v[174:177], v138 offset:4096
	ds_read_b128 v[186:189], v138 offset:5120
	ds_read_b128 v[190:193], v138 offset:6144
	ds_read_b128 v[198:201], v138 offset:7168
	global_load_lds_dwordx4 v[180:181], off
	v_lshl_add_u64 v[180:181], v[134:135], 0, s[14:15]
	s_add_i32 m0, s24, 0xe000
	s_nop 0
	global_load_lds_dwordx4 v[180:181], off
	s_waitcnt lgkmcnt(8)
	s_barrier
	s_waitcnt lgkmcnt(0)
	s_waitcnt lgkmcnt(0)
	v_mfma_f32_16x16x32_bf16 v[126:129], v[140:143], v[158:161], v[126:129]
	v_mfma_f32_16x16x32_bf16 v[122:125], v[150:153], v[158:161], v[122:125]
	v_mfma_f32_16x16x32_bf16 v[110:113], v[140:143], v[166:169], v[110:113]
	v_mfma_f32_16x16x32_bf16 v[106:109], v[150:153], v[166:169], v[106:109]
	v_mfma_f32_16x16x32_bf16 v[94:97], v[140:143], v[174:177], v[94:97]
	v_mfma_f32_16x16x32_bf16 v[90:93], v[150:153], v[174:177], v[90:93]
	v_mfma_f32_16x16x32_bf16 v[78:81], v[140:143], v[190:193], v[78:81]
	v_mfma_f32_16x16x32_bf16 v[74:77], v[150:153], v[190:193], v[74:77]
	v_mfma_f32_16x16x32_bf16 v[126:129], v[144:147], v[162:165], v[126:129]
	v_mfma_f32_16x16x32_bf16 v[122:125], v[154:157], v[162:165], v[122:125]
	v_mfma_f32_16x16x32_bf16 v[110:113], v[144:147], v[170:173], v[110:113]
	v_mfma_f32_16x16x32_bf16 v[106:109], v[154:157], v[170:173], v[106:109]
	v_mfma_f32_16x16x32_bf16 v[94:97], v[144:147], v[186:189], v[94:97]
	v_mfma_f32_16x16x32_bf16 v[90:93], v[154:157], v[186:189], v[90:93]
	v_mfma_f32_16x16x32_bf16 v[78:81], v[144:147], v[198:201], v[78:81]
	v_mfma_f32_16x16x32_bf16 v[74:77], v[154:157], v[198:201], v[74:77]
	s_barrier
	s_add_i32 s38, 16, 0x14000
	s_add_i32 s37, s37, s23
	v_add_u32_e32 v139, s38, v137
	v_lshl_add_u64 v[180:181], s[18:19], 0, v[0:1]
	s_mov_b32 m0, s37
	ds_read_b128 v[202:205], v139
	ds_read_b128 v[206:209], v139 offset:1024
	ds_read_b128 v[214:217], v139 offset:2048
	ds_read_b128 v[218:221], v139 offset:3072
	global_load_lds_dwordx4 v[180:181], off
	v_lshl_add_u64 v[182:183], s[18:19], 0, v[130:131]
	s_add_i32 m0, s37, 0x2000
	s_nop 0
	global_load_lds_dwordx4 v[182:183], off
	s_barrier
	s_waitcnt lgkmcnt(0)
	s_waitcnt lgkmcnt(0)
	v_mfma_f32_16x16x32_bf16 v[118:121], v[202:205], v[158:161], v[118:121]
	v_mfma_f32_16x16x32_bf16 v[114:117], v[214:217], v[158:161], v[114:117]
	v_mfma_f32_16x16x32_bf16 v[102:105], v[202:205], v[166:169], v[102:105]
	v_mfma_f32_16x16x32_bf16 v[98:101], v[214:217], v[166:169], v[98:101]
	v_mfma_f32_16x16x32_bf16 v[86:89], v[202:205], v[174:177], v[86:89]
	v_mfma_f32_16x16x32_bf16 v[82:85], v[214:217], v[174:177], v[82:85]
	v_mfma_f32_16x16x32_bf16 v[70:73], v[202:205], v[190:193], v[70:73]
	v_mfma_f32_16x16x32_bf16 v[66:69], v[214:217], v[190:193], v[66:69]
	v_mfma_f32_16x16x32_bf16 v[118:121], v[206:209], v[162:165], v[118:121]
	v_mfma_f32_16x16x32_bf16 v[114:117], v[218:221], v[162:165], v[114:117]
	v_mfma_f32_16x16x32_bf16 v[102:105], v[206:209], v[170:173], v[102:105]
	v_mfma_f32_16x16x32_bf16 v[98:101], v[218:221], v[170:173], v[98:101]
	v_mfma_f32_16x16x32_bf16 v[86:89], v[206:209], v[186:189], v[86:89]
	v_mfma_f32_16x16x32_bf16 v[82:85], v[218:221], v[186:189], v[82:85]
	v_mfma_f32_16x16x32_bf16 v[70:73], v[206:209], v[198:201], v[70:73]
	v_mfma_f32_16x16x32_bf16 v[66:69], v[218:221], v[198:201], v[66:69]
	s_mov_b32 m0, s24
	v_lshl_add_u64 v[184:185], s[16:17], 0, v[0:1]
	s_barrier
	ds_read_b128 v[158:161], v138 offset:16384
	ds_read_b128 v[162:165], v138 offset:17408
	ds_read_b128 v[166:169], v138 offset:18432
	ds_read_b128 v[170:173], v138 offset:19456
	ds_read_b128 v[174:177], v138 offset:20480
	ds_read_b128 v[186:189], v138 offset:21504
	ds_read_b128 v[190:193], v138 offset:22528
	ds_read_b128 v[198:201], v138 offset:23552
	global_load_lds_dwordx4 v[184:185], off
	v_lshl_add_u64 v[222:223], s[16:17], 0, v[130:131]
	s_mov_b32 m0, s25
	s_nop 0
	global_load_lds_dwordx4 v[222:223], off
	s_barrier
	s_waitcnt lgkmcnt(0)
	s_waitcnt lgkmcnt(0)
	v_mfma_f32_16x16x32_bf16 v[62:65], v[140:143], v[158:161], v[62:65]
	v_mfma_f32_16x16x32_bf16 v[58:61], v[150:153], v[158:161], v[58:61]
	v_mfma_f32_16x16x32_bf16 v[46:49], v[140:143], v[166:169], v[46:49]
	v_mfma_f32_16x16x32_bf16 v[42:45], v[150:153], v[166:169], v[42:45]
	v_mfma_f32_16x16x32_bf16 v[30:33], v[140:143], v[174:177], v[30:33]
	v_mfma_f32_16x16x32_bf16 v[26:29], v[150:153], v[174:177], v[26:29]
	v_mfma_f32_16x16x32_bf16 v[14:17], v[140:143], v[190:193], v[14:17]
	v_mfma_f32_16x16x32_bf16 v[10:13], v[150:153], v[190:193], v[10:13]
	v_mfma_f32_16x16x32_bf16 v[62:65], v[144:147], v[162:165], v[62:65]
	v_mfma_f32_16x16x32_bf16 v[58:61], v[154:157], v[162:165], v[58:61]
	v_mfma_f32_16x16x32_bf16 v[46:49], v[144:147], v[170:173], v[46:49]
	v_mfma_f32_16x16x32_bf16 v[42:45], v[154:157], v[170:173], v[42:45]
	v_mfma_f32_16x16x32_bf16 v[30:33], v[144:147], v[186:189], v[30:33]
	v_mfma_f32_16x16x32_bf16 v[26:29], v[154:157], v[186:189], v[26:29]
	v_mfma_f32_16x16x32_bf16 v[14:17], v[144:147], v[198:201], v[14:17]
	v_mfma_f32_16x16x32_bf16 v[10:13], v[154:157], v[198:201], v[10:13]
	s_barrier
; #define PG8_STAGE(bufoff, gbase, voff) do { _Pragma("unroll") for (int _i = 0; _i < 2; ++_i) \
;     __builtin_amdgcn_global_load_lds((const unsigned*)((const char*)(gbase) + (voff)[_i]), (LAS unsigned*)(lds + (bufoff) + ldsw + _i * 8192), 16, 0, 0); } while (0)
; #define PG8_LDA(dst, b, h) do { _Pragma("unroll") for (int m = 0; m < 4; ++m) _Pragma("unroll") for (int k = 0; k < 2; ++k) dst[m][k] = *(const LAS bf16x8*)(lds + PG8_SA(b, h) + aoff + m * 2048 + k * 1024); } while (0)
; #define PG8_LDB(dst, b, h) do { _Pragma("unroll") for (int n = 0; n < 2; ++n) _Pragma("unroll") for (int k = 0; k < 2; ++k) dst[n][k] = *(const LAS bf16x8*)(lds + PG8_SB(b, h) + boff + n * 2048 + k * 1024); } while (0)
; #define PG8_MMA(ai, bj, At, Bt) do { __builtin_amdgcn_s_setprio(1); _Pragma("unroll") for (int m = 0; m < 4; ++m) _Pragma("unroll") for (int n = 0; n < 2; ++n) _Pragma("unroll") for (int k = 0; k < 2; ++k) \
;     acc[ai][bj][m][n] = __builtin_amdgcn_mfma_f32_16x16x32_bf16(Bt[n][k], At[m][k], acc[ai][bj][m][n], 0, 0, 0); __builtin_amdgcn_s_setprio(0); } while (0)
; #define PG8_WAIT_V(n) asm volatile("s_waitcnt vmcnt(" #n ")" ::: "memory")
; #define PG8_WAIT_L(n) asm volatile("s_waitcnt lgkmcnt(" #n ")" ::: "memory")
; #define PG8_BAR __builtin_amdgcn_s_barrier()
; #define PG8_SCHED __builtin_amdgcn_sched_barrier(0)
; template <class Epi, class Sched>
; DI void gemm_phase(LAS unsigned char* lds, const Gemm g, const Sched& S, const Epi& E) {
;     ...
;       PG8_STAGE(PG8_SB(0, 1), b2 + hstepB, voffB);
;       PG8_WAIT_V(6); PG8_BAR; PG8_MMA(1, 1, At, B1); PG8_BAR;
;       PG8_LDB(B0, 1, 0); PG8_SCHED; PG8_LDA(At, 1, 0); PG8_STAGE(PG8_SA(0, 1), a2 + hstep, voffA);
;       PG8_WAIT_L(8); PG8_BAR; PG8_WAIT_L(0); PG8_MMA(0, 0, At, B0); PG8_BAR; PG8_SCHED;
;       PG8_LDB(B1, 1, 1); PG8_STAGE(PG8_SB(1, 0), b3, voffB);
;       PG8_BAR; PG8_WAIT_L(0); PG8_MMA(0, 1, At, B1); PG8_BAR;
	s_add_u32 s18, s18, s0
	s_addc_u32 s19, s19, s1
	s_add_i32 s37, s38, s23
	v_lshl_add_u64 v[224:225], s[18:19], 0, v[0:1]
	s_mov_b32 m0, s37
	v_lshl_add_u64 v[226:227], s[18:19], 0, v[130:131]
	global_load_lds_dwordx4 v[224:225], off
	s_add_i32 m0, s37, 0x2000
	s_nop 0
	global_load_lds_dwordx4 v[226:227], off
	s_waitcnt vmcnt(6)
	s_barrier
	v_mfma_f32_16x16x32_bf16 v[54:57], v[202:205], v[158:161], v[54:57]
	v_mfma_f32_16x16x32_bf16 v[50:53], v[214:217], v[158:161], v[50:53]
	v_mfma_f32_16x16x32_bf16 v[38:41], v[202:205], v[166:169], v[38:41]
	v_mfma_f32_16x16x32_bf16 v[34:37], v[214:217], v[166:169], v[34:37]
	v_mfma_f32_16x16x32_bf16 v[22:25], v[202:205], v[174:177], v[22:25]
	v_mfma_f32_16x16x32_bf16 v[18:21], v[214:217], v[174:177], v[18:21]
	v_mfma_f32_16x16x32_bf16 v[6:9], v[202:205], v[190:193], v[6:9]
	v_mfma_f32_16x16x32_bf16 v[2:5], v[214:217], v[190:193], v[2:5]
	v_mfma_f32_16x16x32_bf16 v[54:57], v[206:209], v[162:165], v[54:57]
	v_mfma_f32_16x16x32_bf16 v[50:53], v[218:221], v[162:165], v[50:53]
	v_mfma_f32_16x16x32_bf16 v[38:41], v[206:209], v[170:173], v[38:41]
	v_mfma_f32_16x16x32_bf16 v[34:37], v[218:221], v[170:173], v[34:37]
	v_mfma_f32_16x16x32_bf16 v[22:25], v[206:209], v[186:189], v[22:25]
	v_mfma_f32_16x16x32_bf16 v[18:21], v[218:221], v[186:189], v[18:21]
	v_mfma_f32_16x16x32_bf16 v[6:9], v[206:209], v[198:201], v[6:9]
	v_mfma_f32_16x16x32_bf16 v[2:5], v[218:221], v[198:201], v[2:5]
	s_add_i32 s18, 16, 0x18000
	v_add_u32_e32 v139, s18, v137
	s_barrier
	ds_read_b128 v[140:143], v139
	ds_read_b128 v[144:147], v139 offset:1024
	ds_read_b128 v[150:153], v139 offset:2048
	ds_read_b128 v[154:157], v139 offset:3072
	s_add_u32 s16, s16, s0
	s_addc_u32 s17, s17, s1
	s_mov_b32 m0, s26
	v_lshl_add_u64 v[202:203], s[16:17], 0, v[0:1]
	ds_read_b128 v[158:161], v138 offset:32768
	ds_read_b128 v[162:165], v138 offset:33792
	ds_read_b128 v[166:169], v138 offset:34816
	ds_read_b128 v[170:173], v138 offset:35840
	ds_read_b128 v[174:177], v138 offset:36864
	ds_read_b128 v[186:189], v138 offset:37888
	ds_read_b128 v[190:193], v138 offset:38912
	ds_read_b128 v[198:201], v138 offset:39936
	global_load_lds_dwordx4 v[202:203], off
	v_lshl_add_u64 v[202:203], s[16:17], 0, v[130:131]
	s_mov_b32 m0, s27
	s_nop 0
	global_load_lds_dwordx4 v[202:203], off
	s_waitcnt lgkmcnt(8)
	s_barrier
	s_waitcnt lgkmcnt(0)
	s_waitcnt lgkmcnt(0)
	v_mfma_f32_16x16x32_bf16 v[126:129], v[140:143], v[158:161], v[126:129]
	v_mfma_f32_16x16x32_bf16 v[122:125], v[150:153], v[158:161], v[122:125]
	v_mfma_f32_16x16x32_bf16 v[110:113], v[140:143], v[166:169], v[110:113]
	v_mfma_f32_16x16x32_bf16 v[106:109], v[150:153], v[166:169], v[106:109]
	v_mfma_f32_16x16x32_bf16 v[94:97], v[140:143], v[174:177], v[94:97]
	v_mfma_f32_16x16x32_bf16 v[90:93], v[150:153], v[174:177], v[90:93]
	v_mfma_f32_16x16x32_bf16 v[78:81], v[140:143], v[190:193], v[78:81]
	v_mfma_f32_16x16x32_bf16 v[74:77], v[150:153], v[190:193], v[74:77]
	v_mfma_f32_16x16x32_bf16 v[126:129], v[144:147], v[162:165], v[126:129]
	v_mfma_f32_16x16x32_bf16 v[122:125], v[154:157], v[162:165], v[122:125]
	v_mfma_f32_16x16x32_bf16 v[110:113], v[144:147], v[170:173], v[110:113]
	v_mfma_f32_16x16x32_bf16 v[106:109], v[154:157], v[170:173], v[106:109]
	v_mfma_f32_16x16x32_bf16 v[94:97], v[144:147], v[186:189], v[94:97]
	v_mfma_f32_16x16x32_bf16 v[90:93], v[154:157], v[186:189], v[90:93]
	v_mfma_f32_16x16x32_bf16 v[78:81], v[144:147], v[198:201], v[78:81]
	v_mfma_f32_16x16x32_bf16 v[74:77], v[154:157], v[198:201], v[74:77]
	s_barrier
	s_add_i32 s16, 16, 0x1c000
	s_add_i32 s17, s18, s23
	v_add_u32_e32 v139, s16, v137
	v_lshl_add_u64 v[180:181], v[180:181], 0, s[70:71]
	s_mov_b32 m0, s17
	ds_read_b128 v[202:205], v139
	ds_read_b128 v[206:209], v139 offset:1024
	ds_read_b128 v[214:217], v139 offset:2048
	ds_read_b128 v[218:221], v139 offset:3072
	global_load_lds_dwordx4 v[180:181], off
	v_lshl_add_u64 v[180:181], v[182:183], 0, s[70:71]
	s_add_i32 m0, s17, 0x2000
	s_nop 0
	global_load_lds_dwordx4 v[180:181], off
	s_barrier
; #define PG8_STAGE(bufoff, gbase, voff) do { _Pragma("unroll") for (int _i = 0; _i < 2; ++_i) \
;     __builtin_amdgcn_global_load_lds((const unsigned*)((const char*)(gbase) + (voff)[_i]), (LAS unsigned*)(lds + (bufoff) + ldsw + _i * 8192), 16, 0, 0); } while (0)
; #define PG8_LDA(dst, b, h) do { _Pragma("unroll") for (int m = 0; m < 4; ++m) _Pragma("unroll") for (int k = 0; k < 2; ++k) dst[m][k] = *(const LAS bf16x8*)(lds + PG8_SA(b, h) + aoff + m * 2048 + k * 1024); } while (0)
; #define PG8_MMA(ai, bj, At, Bt) do { __builtin_amdgcn_s_setprio(1); _Pragma("unroll") for (int m = 0; m < 4; ++m) _Pragma("unroll") for (int n = 0; n < 2; ++n) _Pragma("unroll") for (int k = 0; k < 2; ++k) \
;     acc[ai][bj][m][n] = __builtin_amdgcn_mfma_f32_16x16x32_bf16(Bt[n][k], At[m][k], acc[ai][bj][m][n], 0, 0, 0); __builtin_amdgcn_s_setprio(0); } while (0)
; #define PG8_WAIT_V(n) asm volatile("s_waitcnt vmcnt(" #n ")" ::: "memory")
; #define PG8_WAIT_L(n) asm volatile("s_waitcnt lgkmcnt(" #n ")" ::: "memory")
; #define PG8_BAR __builtin_amdgcn_s_barrier()
; #define PG8_SCHED __builtin_amdgcn_sched_barrier(0)
; template <class Epi, class Sched>
; DI void gemm_phase(LAS unsigned char* lds, const Gemm g, const Sched& S, const Epi& E) {
;     ...
;       PG8_BAR; PG8_WAIT_L(0); PG8_MMA(0, 1, At, B1); PG8_BAR;
;       PG8_LDA(At, 1, 1); PG8_STAGE(PG8_SA(1, 0), a3, voffA);
;       PG8_BAR; PG8_WAIT_L(0); PG8_MMA(1, 0, At, B0); PG8_BAR; PG8_SCHED;
;       PG8_STAGE(PG8_SB(1, 1), b3 + hstepB, voffB);
;       PG8_WAIT_V(6); PG8_BAR; PG8_MMA(1, 1, At, B1); PG8_BAR;
;     }
	s_waitcnt lgkmcnt(0)
	s_waitcnt lgkmcnt(0)
	v_mfma_f32_16x16x32_bf16 v[118:121], v[202:205], v[158:161], v[118:121]
	v_mfma_f32_16x16x32_bf16 v[114:117], v[214:217], v[158:161], v[114:117]
	v_mfma_f32_16x16x32_bf16 v[102:105], v[202:205], v[166:169], v[102:105]
	v_mfma_f32_16x16x32_bf16 v[98:101], v[214:217], v[166:169], v[98:101]
	v_mfma_f32_16x16x32_bf16 v[86:89], v[202:205], v[174:177], v[86:89]
	v_mfma_f32_16x16x32_bf16 v[82:85], v[214:217], v[174:177], v[82:85]
	v_mfma_f32_16x16x32_bf16 v[70:73], v[202:205], v[190:193], v[70:73]
	v_mfma_f32_16x16x32_bf16 v[66:69], v[214:217], v[190:193], v[66:69]
	v_mfma_f32_16x16x32_bf16 v[118:121], v[206:209], v[162:165], v[118:121]
	v_mfma_f32_16x16x32_bf16 v[114:117], v[218:221], v[162:165], v[114:117]
	v_mfma_f32_16x16x32_bf16 v[102:105], v[206:209], v[170:173], v[102:105]
	v_mfma_f32_16x16x32_bf16 v[98:101], v[218:221], v[170:173], v[98:101]
	v_mfma_f32_16x16x32_bf16 v[86:89], v[206:209], v[186:189], v[86:89]
	v_mfma_f32_16x16x32_bf16 v[82:85], v[218:221], v[186:189], v[82:85]
	v_mfma_f32_16x16x32_bf16 v[70:73], v[206:209], v[198:201], v[70:73]
	v_mfma_f32_16x16x32_bf16 v[66:69], v[218:221], v[198:201], v[66:69]
	s_mov_b32 m0, s30
	v_lshl_add_u64 v[180:181], v[184:185], 0, s[70:71]
	s_barrier
	ds_read_b128 v[158:161], v138 offset:49152
	ds_read_b128 v[162:165], v138 offset:50176
	ds_read_b128 v[166:169], v138 offset:51200
	ds_read_b128 v[170:173], v138 offset:52224
	ds_read_b128 v[174:177], v138 offset:53248
	ds_read_b128 v[186:189], v138 offset:54272
	ds_read_b128 v[190:193], v138 offset:55296
	ds_read_b128 v[198:201], v138 offset:56320
	global_load_lds_dwordx4 v[180:181], off
	v_lshl_add_u64 v[180:181], v[222:223], 0, s[70:71]
	s_mov_b32 m0, s31
	s_nop 0
	global_load_lds_dwordx4 v[180:181], off
	s_barrier
	s_waitcnt lgkmcnt(0)
	s_waitcnt lgkmcnt(0)
	v_mfma_f32_16x16x32_bf16 v[62:65], v[140:143], v[158:161], v[62:65]
	v_mfma_f32_16x16x32_bf16 v[58:61], v[150:153], v[158:161], v[58:61]
	v_mfma_f32_16x16x32_bf16 v[46:49], v[140:143], v[166:169], v[46:49]
	v_mfma_f32_16x16x32_bf16 v[42:45], v[150:153], v[166:169], v[42:45]
	v_mfma_f32_16x16x32_bf16 v[30:33], v[140:143], v[174:177], v[30:33]
	v_mfma_f32_16x16x32_bf16 v[26:29], v[150:153], v[174:177], v[26:29]
	v_mfma_f32_16x16x32_bf16 v[14:17], v[140:143], v[190:193], v[14:17]
	v_mfma_f32_16x16x32_bf16 v[10:13], v[150:153], v[190:193], v[10:13]
	v_mfma_f32_16x16x32_bf16 v[62:65], v[144:147], v[162:165], v[62:65]
	v_mfma_f32_16x16x32_bf16 v[58:61], v[154:157], v[162:165], v[58:61]
	v_mfma_f32_16x16x32_bf16 v[46:49], v[144:147], v[170:173], v[46:49]
	v_mfma_f32_16x16x32_bf16 v[42:45], v[154:157], v[170:173], v[42:45]
	v_mfma_f32_16x16x32_bf16 v[30:33], v[144:147], v[186:189], v[30:33]
	v_mfma_f32_16x16x32_bf16 v[26:29], v[154:157], v[186:189], v[26:29]
	v_mfma_f32_16x16x32_bf16 v[14:17], v[144:147], v[198:201], v[14:17]
	v_mfma_f32_16x16x32_bf16 v[10:13], v[154:157], v[198:201], v[10:13]
	s_barrier
	s_add_i32 s16, s16, s23
	v_lshl_add_u64 v[140:141], v[224:225], 0, s[70:71]
	s_mov_b32 m0, s16
	s_nop 0
	global_load_lds_dwordx4 v[140:141], off
	v_lshl_add_u64 v[140:141], v[226:227], 0, s[70:71]
	s_add_i32 m0, s16, 0x2000
	s_nop 0
	global_load_lds_dwordx4 v[140:141], off
	s_waitcnt vmcnt(6)
	s_barrier
	v_mfma_f32_16x16x32_bf16 v[54:57], v[202:205], v[158:161], v[54:57]
	v_mfma_f32_16x16x32_bf16 v[50:53], v[214:217], v[158:161], v[50:53]
	v_mfma_f32_16x16x32_bf16 v[38:41], v[202:205], v[166:169], v[38:41]
	v_mfma_f32_16x16x32_bf16 v[34:37], v[214:217], v[166:169], v[34:37]
	v_mfma_f32_16x16x32_bf16 v[22:25], v[202:205], v[174:177], v[22:25]
	v_mfma_f32_16x16x32_bf16 v[18:21], v[214:217], v[174:177], v[18:21]
	v_mfma_f32_16x16x32_bf16 v[6:9], v[202:205], v[190:193], v[6:9]
	v_mfma_f32_16x16x32_bf16 v[2:5], v[214:217], v[190:193], v[2:5]
	v_mfma_f32_16x16x32_bf16 v[54:57], v[206:209], v[162:165], v[54:57]
	v_mfma_f32_16x16x32_bf16 v[50:53], v[218:221], v[162:165], v[50:53]
	v_mfma_f32_16x16x32_bf16 v[38:41], v[206:209], v[170:173], v[38:41]
	v_mfma_f32_16x16x32_bf16 v[34:37], v[218:221], v[170:173], v[34:37]
	v_mfma_f32_16x16x32_bf16 v[22:25], v[206:209], v[186:189], v[22:25]
	v_mfma_f32_16x16x32_bf16 v[18:21], v[218:221], v[186:189], v[18:21]
	v_mfma_f32_16x16x32_bf16 v[6:9], v[206:209], v[198:201], v[6:9]
	v_mfma_f32_16x16x32_bf16 v[2:5], v[218:221], v[198:201], v[2:5]
	s_add_u32 s14, s14, 0x100
	s_addc_u32 s15, s15, 0
	s_cmp_ge_i32 s36, s34
	s_mov_b32 s16, s36
	s_barrier
	s_cbranch_scc0 .LBB0_153

; #define PG8_STAGE(bufoff, gbase, voff) do { _Pragma("unroll") for (int _i = 0; _i < 2; ++_i) \
;     __builtin_amdgcn_global_load_lds((const unsigned*)((const char*)(gbase) + (voff)[_i]), (LAS unsigned*)(lds + (bufoff) + ldsw + _i * 8192), 16, 0, 0); } while (0)
; #define PG8_LDA(dst, b, h) do { _Pragma("unroll") for (int m = 0; m < 4; ++m) _Pragma("unroll") for (int k = 0; k < 2; ++k) dst[m][k] = *(const LAS bf16x8*)(lds + PG8_SA(b, h) + aoff + m * 2048 + k * 1024); } while (0)
; #define PG8_LDB(dst, b, h) do { _Pragma("unroll") for (int n = 0; n < 2; ++n) _Pragma("unroll") for (int k = 0; k < 2; ++k) dst[n][k] = *(const LAS bf16x8*)(lds + PG8_SB(b, h) + boff + n * 2048 + k * 1024); } while (0)
; #define PG8_MMA(ai, bj, At, Bt) do { __builtin_amdgcn_s_setprio(1); _Pragma("unroll") for (int m = 0; m < 4; ++m) _Pragma("unroll") for (int n = 0; n < 2; ++n) _Pragma("unroll") for (int k = 0; k < 2; ++k) \
;     acc[ai][bj][m][n] = __builtin_amdgcn_mfma_f32_16x16x32_bf16(Bt[n][k], At[m][k], acc[ai][bj][m][n], 0, 0, 0); __builtin_amdgcn_s_setprio(0); } while (0)
; #define PG8_WAIT_L(n) asm volatile("s_waitcnt lgkmcnt(" #n ")" ::: "memory")
; #define PG8_BAR __builtin_amdgcn_s_barrier()
; #define PG8_SCHED __builtin_amdgcn_sched_barrier(0)
; template <class Epi, class Sched>
; DI void gemm_phase(LAS unsigned char* lds, const Gemm g, const Sched& S, const Epi& E) {
;     ...
;     const char* nA = has_next ? (const char*)g.A + (size_t)nxt.pm * tstep : cA; const char* nB = has_next ? (const char*)g.Bt + (size_t)nxt.pn * tstep : cB;
;     for (int t = 0; t < nt; t += 2) {
;       const bool last = (t == nt - 2);
;       const char* a1 = cA + (size_t)(t + 1) * kstep;
;       const char* a2 = last ? nA : cA + (size_t)(t + 2) * kstep; const char* b2 = last ? nB : cB + (size_t)(t + 2) * kstep;
;       const char* a3 = a2 + kstep; const char* b3 = b2 + kstep;
;       PG8_LDB(B0, 0, 0); PG8_SCHED; PG8_LDA(At, 0, 0); PG8_STAGE(PG8_SA(1, 1), a1 + hstep, voffA);
;       PG8_WAIT_L(8); PG8_BAR; PG8_WAIT_L(0); PG8_MMA(0, 0, At, B0); PG8_BAR; PG8_SCHED;
;       PG8_LDB(B1, 0, 1); PG8_STAGE(PG8_SB(0, 0), b2, voffB);
;       PG8_BAR; PG8_WAIT_L(0); PG8_MMA(0, 1, At, B1); PG8_BAR;
;       PG8_LDA(At, 0, 1); PG8_STAGE(PG8_SA(0, 0), a2, voffA);
;       PG8_BAR; PG8_WAIT_L(0); PG8_MMA(1, 0, At, B0); PG8_BAR; PG8_SCHED;
.LBB0_178:
	s_add_i32 s51, s24, 2
	s_add_u32 s26, s22, 0x80
	s_addc_u32 s25, s23, 0
	s_add_i32 s52, 16, 0x10000
	v_add_u32_e32 v156, s52, v141
	ds_read_b128 v[144:147], v156
	ds_read_b128 v[148:151], v156 offset:1024
	ds_read_b128 v[152:155], v156 offset:2048
	ds_read_b128 v[156:159], v156 offset:3072
	s_cmp_eq_u32 s43, s24
	s_cselect_b32 s24, s18, s26
	s_cselect_b32 s25, s19, s25
	s_cselect_b32 s27, s21, s50
	s_cselect_b32 s26, s20, s49
	v_lshl_add_u64 v[176:177], s[22:23], 0, v[136:137]
	s_add_i32 m0, s36, 0xc000
	ds_read_b128 v[160:163], v143
	ds_read_b128 v[164:167], v143 offset:1024
	ds_read_b128 v[168:171], v143 offset:2048
	ds_read_b128 v[172:175], v143 offset:3072
	ds_read_b128 v[186:189], v143 offset:4096
	ds_read_b128 v[190:193], v143 offset:5120
	ds_read_b128 v[198:201], v143 offset:6144
	ds_read_b128 v[202:205], v143 offset:7168
	global_load_lds_dwordx4 v[176:177], off
	v_lshl_add_u64 v[176:177], s[22:23], 0, v[138:139]
	s_add_i32 m0, s36, 0xe000
	s_nop 0
	global_load_lds_dwordx4 v[176:177], off
	s_waitcnt lgkmcnt(8)
	s_barrier
	s_waitcnt lgkmcnt(0)
	s_waitcnt lgkmcnt(0)
	v_mfma_f32_16x16x32_bf16 v[122:125], v[144:147], v[160:163], v[122:125]
	v_mfma_f32_16x16x32_bf16 v[118:121], v[152:155], v[160:163], v[118:121]
	v_mfma_f32_16x16x32_bf16 v[110:113], v[144:147], v[168:171], v[110:113]
	v_mfma_f32_16x16x32_bf16 v[102:105], v[152:155], v[168:171], v[102:105]
	v_mfma_f32_16x16x32_bf16 v[94:97], v[144:147], v[186:189], v[94:97]
	v_mfma_f32_16x16x32_bf16 v[86:89], v[152:155], v[186:189], v[86:89]
	v_mfma_f32_16x16x32_bf16 v[78:81], v[144:147], v[198:201], v[78:81]
	v_mfma_f32_16x16x32_bf16 v[70:73], v[152:155], v[198:201], v[70:73]
	v_mfma_f32_16x16x32_bf16 v[122:125], v[148:151], v[164:167], v[122:125]
	v_mfma_f32_16x16x32_bf16 v[118:121], v[156:159], v[164:167], v[118:121]
	v_mfma_f32_16x16x32_bf16 v[110:113], v[148:151], v[172:175], v[110:113]
	v_mfma_f32_16x16x32_bf16 v[102:105], v[156:159], v[172:175], v[102:105]
	v_mfma_f32_16x16x32_bf16 v[94:97], v[148:151], v[190:193], v[94:97]
	v_mfma_f32_16x16x32_bf16 v[86:89], v[156:159], v[190:193], v[86:89]
	v_mfma_f32_16x16x32_bf16 v[78:81], v[148:151], v[202:205], v[78:81]
	v_mfma_f32_16x16x32_bf16 v[70:73], v[156:159], v[202:205], v[70:73]
	s_barrier
	s_add_i32 s53, 16, 0x14000
	v_add_u32_e32 v176, s53, v141
	s_add_i32 s52, s52, s35
	ds_read_b128 v[206:209], v176
	ds_read_b128 v[214:217], v176 offset:1024
	ds_read_b128 v[218:221], v176 offset:2048
	ds_read_b128 v[222:225], v176 offset:3072
	v_lshl_add_u64 v[176:177], s[26:27], 0, v[0:1]
	s_mov_b32 m0, s52
	v_lshl_add_u64 v[180:181], s[26:27], 0, v[130:131]
	global_load_lds_dwordx4 v[176:177], off
	s_add_i32 m0, s52, 0x2000
	s_nop 0
	global_load_lds_dwordx4 v[180:181], off
	s_barrier
	s_waitcnt lgkmcnt(0)
	s_waitcnt lgkmcnt(0)
	v_mfma_f32_16x16x32_bf16 v[126:129], v[206:209], v[160:163], v[126:129]
	v_mfma_f32_16x16x32_bf16 v[114:117], v[218:221], v[160:163], v[114:117]
	v_mfma_f32_16x16x32_bf16 v[106:109], v[206:209], v[168:171], v[106:109]
	v_mfma_f32_16x16x32_bf16 v[98:101], v[218:221], v[168:171], v[98:101]
	v_mfma_f32_16x16x32_bf16 v[90:93], v[206:209], v[186:189], v[90:93]
	v_mfma_f32_16x16x32_bf16 v[82:85], v[218:221], v[186:189], v[82:85]
	v_mfma_f32_16x16x32_bf16 v[74:77], v[206:209], v[198:201], v[74:77]
	v_mfma_f32_16x16x32_bf16 v[66:69], v[218:221], v[198:201], v[66:69]
	v_mfma_f32_16x16x32_bf16 v[126:129], v[214:217], v[164:167], v[126:129]
	v_mfma_f32_16x16x32_bf16 v[114:117], v[222:225], v[164:167], v[114:117]
	v_mfma_f32_16x16x32_bf16 v[106:109], v[214:217], v[172:175], v[106:109]
	v_mfma_f32_16x16x32_bf16 v[98:101], v[222:225], v[172:175], v[98:101]
	v_mfma_f32_16x16x32_bf16 v[90:93], v[214:217], v[190:193], v[90:93]
	v_mfma_f32_16x16x32_bf16 v[82:85], v[222:225], v[190:193], v[82:85]
	v_mfma_f32_16x16x32_bf16 v[74:77], v[214:217], v[202:205], v[74:77]
	v_mfma_f32_16x16x32_bf16 v[66:69], v[222:225], v[202:205], v[66:69]
	s_mov_b32 m0, s36
	v_lshl_add_u64 v[182:183], s[24:25], 0, v[134:135]
	s_barrier
	ds_read_b128 v[160:163], v143 offset:16384
	ds_read_b128 v[164:167], v143 offset:17408
	ds_read_b128 v[168:171], v143 offset:18432
	ds_read_b128 v[172:175], v143 offset:19456
	ds_read_b128 v[186:189], v143 offset:20480
	ds_read_b128 v[190:193], v143 offset:21504
	ds_read_b128 v[198:201], v143 offset:22528
	ds_read_b128 v[202:205], v143 offset:23552
	global_load_lds_dwordx4 v[182:183], off
	v_lshl_add_u64 v[184:185], s[24:25], 0, v[132:133]
	s_mov_b32 m0, s37
	s_nop 0
	global_load_lds_dwordx4 v[184:185], off
	s_barrier
	s_waitcnt lgkmcnt(0)
	s_waitcnt lgkmcnt(0)
	v_mfma_f32_16x16x32_bf16 v[62:65], v[144:147], v[160:163], v[62:65]
	v_mfma_f32_16x16x32_bf16 v[54:57], v[152:155], v[160:163], v[54:57]
	v_mfma_f32_16x16x32_bf16 v[46:49], v[144:147], v[168:171], v[46:49]
	v_mfma_f32_16x16x32_bf16 v[38:41], v[152:155], v[168:171], v[38:41]
	v_mfma_f32_16x16x32_bf16 v[30:33], v[144:147], v[186:189], v[30:33]
	v_mfma_f32_16x16x32_bf16 v[22:25], v[152:155], v[186:189], v[22:25]
	v_mfma_f32_16x16x32_bf16 v[14:17], v[144:147], v[198:201], v[14:17]
	v_mfma_f32_16x16x32_bf16 v[6:9], v[152:155], v[198:201], v[6:9]
	v_mfma_f32_16x16x32_bf16 v[62:65], v[148:151], v[164:167], v[62:65]
	v_mfma_f32_16x16x32_bf16 v[54:57], v[156:159], v[164:167], v[54:57]
	v_mfma_f32_16x16x32_bf16 v[46:49], v[148:151], v[172:175], v[46:49]
	v_mfma_f32_16x16x32_bf16 v[38:41], v[156:159], v[172:175], v[38:41]
	v_mfma_f32_16x16x32_bf16 v[30:33], v[148:151], v[190:193], v[30:33]
	v_mfma_f32_16x16x32_bf16 v[22:25], v[156:159], v[190:193], v[22:25]
	v_mfma_f32_16x16x32_bf16 v[14:17], v[148:151], v[202:205], v[14:17]
	v_mfma_f32_16x16x32_bf16 v[6:9], v[156:159], v[202:205], v[6:9]
	s_barrier
; #define PG8_STAGE(bufoff, gbase, voff) do { _Pragma("unroll") for (int _i = 0; _i < 2; ++_i) \
;     __builtin_amdgcn_global_load_lds((const unsigned*)((const char*)(gbase) + (voff)[_i]), (LAS unsigned*)(lds + (bufoff) + ldsw + _i * 8192), 16, 0, 0); } while (0)
; #define PG8_LDA(dst, b, h) do { _Pragma("unroll") for (int m = 0; m < 4; ++m) _Pragma("unroll") for (int k = 0; k < 2; ++k) dst[m][k] = *(const LAS bf16x8*)(lds + PG8_SA(b, h) + aoff + m * 2048 + k * 1024); } while (0)
; #define PG8_LDB(dst, b, h) do { _Pragma("unroll") for (int n = 0; n < 2; ++n) _Pragma("unroll") for (int k = 0; k < 2; ++k) dst[n][k] = *(const LAS bf16x8*)(lds + PG8_SB(b, h) + boff + n * 2048 + k * 1024); } while (0)
; #define PG8_MMA(ai, bj, At, Bt) do { __builtin_amdgcn_s_setprio(1); _Pragma("unroll") for (int m = 0; m < 4; ++m) _Pragma("unroll") for (int n = 0; n < 2; ++n) _Pragma("unroll") for (int k = 0; k < 2; ++k) \
;     acc[ai][bj][m][n] = __builtin_amdgcn_mfma_f32_16x16x32_bf16(Bt[n][k], At[m][k], acc[ai][bj][m][n], 0, 0, 0); __builtin_amdgcn_s_setprio(0); } while (0)
; #define PG8_WAIT_V(n) asm volatile("s_waitcnt vmcnt(" #n ")" ::: "memory")
; #define PG8_WAIT_L(n) asm volatile("s_waitcnt lgkmcnt(" #n ")" ::: "memory")
; #define PG8_BAR __builtin_amdgcn_s_barrier()
; #define PG8_SCHED __builtin_amdgcn_sched_barrier(0)
; template <class Epi, class Sched>
; DI void gemm_phase(LAS unsigned char* lds, const Gemm g, const Sched& S, const Epi& E) {
;     ...
;       PG8_STAGE(PG8_SB(0, 1), b2 + hstepB, voffB);
;       PG8_WAIT_V(6); PG8_BAR; PG8_MMA(1, 1, At, B1); PG8_BAR;
;       PG8_LDB(B0, 1, 0); PG8_SCHED; PG8_LDA(At, 1, 0); PG8_STAGE(PG8_SA(0, 1), a2 + hstep, voffA);
;       PG8_WAIT_L(8); PG8_BAR; PG8_WAIT_L(0); PG8_MMA(0, 0, At, B0); PG8_BAR; PG8_SCHED;
;       PG8_LDB(B1, 1, 1); PG8_STAGE(PG8_SB(1, 0), b3, voffB);
;       PG8_BAR; PG8_WAIT_L(0); PG8_MMA(0, 1, At, B1); PG8_BAR;
	s_add_u32 s26, s26, s0
	s_addc_u32 s27, s27, s1
	s_add_i32 s52, s53, s35
	v_lshl_add_u64 v[226:227], s[26:27], 0, v[0:1]
	s_mov_b32 m0, s52
	v_lshl_add_u64 v[228:229], s[26:27], 0, v[130:131]
	global_load_lds_dwordx4 v[226:227], off
	s_add_i32 m0, s52, 0x2000
	s_nop 0
	global_load_lds_dwordx4 v[228:229], off
	s_waitcnt vmcnt(6)
	s_barrier
	v_mfma_f32_16x16x32_bf16 v[58:61], v[206:209], v[160:163], v[58:61]
	v_mfma_f32_16x16x32_bf16 v[50:53], v[218:221], v[160:163], v[50:53]
	v_mfma_f32_16x16x32_bf16 v[42:45], v[206:209], v[168:171], v[42:45]
	v_mfma_f32_16x16x32_bf16 v[34:37], v[218:221], v[168:171], v[34:37]
	v_mfma_f32_16x16x32_bf16 v[26:29], v[206:209], v[186:189], v[26:29]
	v_mfma_f32_16x16x32_bf16 v[18:21], v[218:221], v[186:189], v[18:21]
	v_mfma_f32_16x16x32_bf16 v[10:13], v[206:209], v[198:201], v[10:13]
	v_mfma_f32_16x16x32_bf16 v[2:5], v[218:221], v[198:201], v[2:5]
	v_mfma_f32_16x16x32_bf16 v[58:61], v[214:217], v[164:167], v[58:61]
	v_mfma_f32_16x16x32_bf16 v[50:53], v[222:225], v[164:167], v[50:53]
	v_mfma_f32_16x16x32_bf16 v[42:45], v[214:217], v[172:175], v[42:45]
	v_mfma_f32_16x16x32_bf16 v[34:37], v[222:225], v[172:175], v[34:37]
	v_mfma_f32_16x16x32_bf16 v[26:29], v[214:217], v[190:193], v[26:29]
	v_mfma_f32_16x16x32_bf16 v[18:21], v[222:225], v[190:193], v[18:21]
	v_mfma_f32_16x16x32_bf16 v[10:13], v[214:217], v[202:205], v[10:13]
	v_mfma_f32_16x16x32_bf16 v[2:5], v[222:225], v[202:205], v[2:5]
	s_add_i32 s26, 16, 0x18000
	v_add_u32_e32 v156, s26, v141
	s_barrier
	ds_read_b128 v[144:147], v156
	ds_read_b128 v[148:151], v156 offset:1024
	ds_read_b128 v[152:155], v156 offset:2048
	ds_read_b128 v[156:159], v156 offset:3072
	s_add_u32 s24, s24, s0
	s_addc_u32 s25, s25, s1
	s_mov_b32 m0, s38
	v_lshl_add_u64 v[206:207], s[24:25], 0, v[134:135]
	ds_read_b128 v[160:163], v143 offset:32768
	ds_read_b128 v[164:167], v143 offset:33792
	ds_read_b128 v[168:171], v143 offset:34816
	ds_read_b128 v[172:175], v143 offset:35840
	ds_read_b128 v[186:189], v143 offset:36864
	ds_read_b128 v[190:193], v143 offset:37888
	ds_read_b128 v[198:201], v143 offset:38912
	ds_read_b128 v[202:205], v143 offset:39936
	global_load_lds_dwordx4 v[206:207], off
	v_lshl_add_u64 v[206:207], s[24:25], 0, v[132:133]
	s_mov_b32 m0, s39
	s_nop 0
	global_load_lds_dwordx4 v[206:207], off
	s_waitcnt lgkmcnt(8)
	s_barrier
	s_waitcnt lgkmcnt(0)
	s_waitcnt lgkmcnt(0)
	v_mfma_f32_16x16x32_bf16 v[122:125], v[144:147], v[160:163], v[122:125]
	v_mfma_f32_16x16x32_bf16 v[118:121], v[152:155], v[160:163], v[118:121]
	v_mfma_f32_16x16x32_bf16 v[110:113], v[144:147], v[168:171], v[110:113]
	v_mfma_f32_16x16x32_bf16 v[102:105], v[152:155], v[168:171], v[102:105]
	v_mfma_f32_16x16x32_bf16 v[94:97], v[144:147], v[186:189], v[94:97]
	v_mfma_f32_16x16x32_bf16 v[86:89], v[152:155], v[186:189], v[86:89]
	v_mfma_f32_16x16x32_bf16 v[78:81], v[144:147], v[198:201], v[78:81]
	v_mfma_f32_16x16x32_bf16 v[70:73], v[152:155], v[198:201], v[70:73]
	v_mfma_f32_16x16x32_bf16 v[122:125], v[148:151], v[164:167], v[122:125]
	v_mfma_f32_16x16x32_bf16 v[118:121], v[156:159], v[164:167], v[118:121]
	v_mfma_f32_16x16x32_bf16 v[110:113], v[148:151], v[172:175], v[110:113]
	v_mfma_f32_16x16x32_bf16 v[102:105], v[156:159], v[172:175], v[102:105]
	v_mfma_f32_16x16x32_bf16 v[94:97], v[148:151], v[190:193], v[94:97]
	v_mfma_f32_16x16x32_bf16 v[86:89], v[156:159], v[190:193], v[86:89]
	v_mfma_f32_16x16x32_bf16 v[78:81], v[148:151], v[202:205], v[78:81]
	v_mfma_f32_16x16x32_bf16 v[70:73], v[156:159], v[202:205], v[70:73]
	s_barrier
	s_add_i32 s24, 16, 0x1c000
	s_add_i32 s25, s26, s35
	v_add_u32_e32 v194, s24, v141
	v_lshl_add_u64 v[176:177], v[176:177], 0, s[70:71]
	s_mov_b32 m0, s25
	ds_read_b128 v[206:209], v194
	ds_read_b128 v[214:217], v194 offset:1024
	ds_read_b128 v[218:221], v194 offset:2048
	ds_read_b128 v[222:225], v194 offset:3072
	global_load_lds_dwordx4 v[176:177], off
	v_lshl_add_u64 v[176:177], v[180:181], 0, s[70:71]
	s_add_i32 m0, s25, 0x2000
	s_nop 0
	global_load_lds_dwordx4 v[176:177], off
	s_barrier
;   DI bool next(int i, Unit& o) const { if (i != 0 || !valid) return false; o = u; return true; }
; #define PG8_STAGE(bufoff, gbase, voff) do { _Pragma("unroll") for (int _i = 0; _i < 2; ++_i) \
;     __builtin_amdgcn_global_load_lds((const unsigned*)((const char*)(gbase) + (voff)[_i]), (LAS unsigned*)(lds + (bufoff) + ldsw + _i * 8192), 16, 0, 0); } while (0)
; #define PG8_LDA(dst, b, h) do { _Pragma("unroll") for (int m = 0; m < 4; ++m) _Pragma("unroll") for (int k = 0; k < 2; ++k) dst[m][k] = *(const LAS bf16x8*)(lds + PG8_SA(b, h) + aoff + m * 2048 + k * 1024); } while (0)
; #define PG8_MMA(ai, bj, At, Bt) do { __builtin_amdgcn_s_setprio(1); _Pragma("unroll") for (int m = 0; m < 4; ++m) _Pragma("unroll") for (int n = 0; n < 2; ++n) _Pragma("unroll") for (int k = 0; k < 2; ++k) \
;     acc[ai][bj][m][n] = __builtin_amdgcn_mfma_f32_16x16x32_bf16(Bt[n][k], At[m][k], acc[ai][bj][m][n], 0, 0, 0); __builtin_amdgcn_s_setprio(0); } while (0)
; #define PG8_WAIT_V(n) asm volatile("s_waitcnt vmcnt(" #n ")" ::: "memory")
; #define PG8_WAIT_L(n) asm volatile("s_waitcnt lgkmcnt(" #n ")" ::: "memory")
; #define PG8_BAR __builtin_amdgcn_s_barrier()
; #define PG8_SCHED __builtin_amdgcn_sched_barrier(0)
; template <class Epi, class Sched>
; DI void gemm_phase(LAS unsigned char* lds, const Gemm g, const Sched& S, const Epi& E) {
;     ...
;   for (;;) {
;     const bool has_next = S.next(ui + 1, nxt);
;     const char* nA = has_next ? (const char*)g.A + (size_t)nxt.pm * tstep : cA; const char* nB = has_next ? (const char*)g.Bt + (size_t)nxt.pn * tstep : cB;
;     for (int t = 0; t < nt; t += 2) {
;     ...
;       PG8_BAR; PG8_WAIT_L(0); PG8_MMA(0, 1, At, B1); PG8_BAR;
;       PG8_LDA(At, 1, 1); PG8_STAGE(PG8_SA(1, 0), a3, voffA);
;       PG8_BAR; PG8_WAIT_L(0); PG8_MMA(1, 0, At, B0); PG8_BAR; PG8_SCHED;
;       PG8_STAGE(PG8_SB(1, 1), b3 + hstepB, voffB);
;       PG8_WAIT_V(6); PG8_BAR; PG8_MMA(1, 1, At, B1); PG8_BAR;
;     }
	s_waitcnt lgkmcnt(0)
	s_waitcnt lgkmcnt(0)
	v_mfma_f32_16x16x32_bf16 v[126:129], v[206:209], v[160:163], v[126:129]
	v_mfma_f32_16x16x32_bf16 v[114:117], v[218:221], v[160:163], v[114:117]
	v_mfma_f32_16x16x32_bf16 v[106:109], v[206:209], v[168:171], v[106:109]
	v_mfma_f32_16x16x32_bf16 v[98:101], v[218:221], v[168:171], v[98:101]
	v_mfma_f32_16x16x32_bf16 v[90:93], v[206:209], v[186:189], v[90:93]
	v_mfma_f32_16x16x32_bf16 v[82:85], v[218:221], v[186:189], v[82:85]
	v_mfma_f32_16x16x32_bf16 v[74:77], v[206:209], v[198:201], v[74:77]
	v_mfma_f32_16x16x32_bf16 v[66:69], v[218:221], v[198:201], v[66:69]
	v_mfma_f32_16x16x32_bf16 v[126:129], v[214:217], v[164:167], v[126:129]
	v_mfma_f32_16x16x32_bf16 v[114:117], v[222:225], v[164:167], v[114:117]
	v_mfma_f32_16x16x32_bf16 v[106:109], v[214:217], v[172:175], v[106:109]
	v_mfma_f32_16x16x32_bf16 v[98:101], v[222:225], v[172:175], v[98:101]
	v_mfma_f32_16x16x32_bf16 v[90:93], v[214:217], v[190:193], v[90:93]
	v_mfma_f32_16x16x32_bf16 v[82:85], v[222:225], v[190:193], v[82:85]
	v_mfma_f32_16x16x32_bf16 v[74:77], v[214:217], v[202:205], v[74:77]
	v_mfma_f32_16x16x32_bf16 v[66:69], v[222:225], v[202:205], v[66:69]
	s_mov_b32 m0, s41
	v_lshl_add_u64 v[176:177], v[182:183], 0, s[70:71]
	s_barrier
	ds_read_b128 v[160:163], v143 offset:49152
	ds_read_b128 v[164:167], v143 offset:50176
	ds_read_b128 v[168:171], v143 offset:51200
	ds_read_b128 v[172:175], v143 offset:52224
	ds_read_b128 v[186:189], v143 offset:53248
	ds_read_b128 v[190:193], v143 offset:54272
	ds_read_b128 v[198:201], v143 offset:55296
	ds_read_b128 v[202:205], v143 offset:56320
	global_load_lds_dwordx4 v[176:177], off
	v_lshl_add_u64 v[176:177], v[184:185], 0, s[70:71]
	s_mov_b32 m0, s42
	s_nop 0
	global_load_lds_dwordx4 v[176:177], off
	s_barrier
	s_waitcnt lgkmcnt(0)
	s_waitcnt lgkmcnt(0)
	v_mfma_f32_16x16x32_bf16 v[62:65], v[144:147], v[160:163], v[62:65]
	v_mfma_f32_16x16x32_bf16 v[54:57], v[152:155], v[160:163], v[54:57]
	v_mfma_f32_16x16x32_bf16 v[46:49], v[144:147], v[168:171], v[46:49]
	v_mfma_f32_16x16x32_bf16 v[38:41], v[152:155], v[168:171], v[38:41]
	v_mfma_f32_16x16x32_bf16 v[30:33], v[144:147], v[186:189], v[30:33]
	v_mfma_f32_16x16x32_bf16 v[22:25], v[152:155], v[186:189], v[22:25]
	v_mfma_f32_16x16x32_bf16 v[14:17], v[144:147], v[198:201], v[14:17]
	v_mfma_f32_16x16x32_bf16 v[6:9], v[152:155], v[198:201], v[6:9]
	v_mfma_f32_16x16x32_bf16 v[62:65], v[148:151], v[164:167], v[62:65]
	v_mfma_f32_16x16x32_bf16 v[54:57], v[156:159], v[164:167], v[54:57]
	v_mfma_f32_16x16x32_bf16 v[46:49], v[148:151], v[172:175], v[46:49]
	v_mfma_f32_16x16x32_bf16 v[38:41], v[156:159], v[172:175], v[38:41]
	v_mfma_f32_16x16x32_bf16 v[30:33], v[148:151], v[190:193], v[30:33]
	v_mfma_f32_16x16x32_bf16 v[22:25], v[156:159], v[190:193], v[22:25]
	v_mfma_f32_16x16x32_bf16 v[14:17], v[148:151], v[202:205], v[14:17]
	v_mfma_f32_16x16x32_bf16 v[6:9], v[156:159], v[202:205], v[6:9]
	s_barrier
	s_add_i32 s24, s24, s35
	v_lshl_add_u64 v[144:145], v[226:227], 0, s[70:71]
	s_mov_b32 m0, s24
	s_nop 0
	global_load_lds_dwordx4 v[144:145], off
	v_lshl_add_u64 v[144:145], v[228:229], 0, s[70:71]
	s_add_i32 m0, s24, 0x2000
	s_nop 0
	global_load_lds_dwordx4 v[144:145], off
	s_waitcnt vmcnt(6)
	s_barrier
	v_mfma_f32_16x16x32_bf16 v[58:61], v[206:209], v[160:163], v[58:61]
	v_mfma_f32_16x16x32_bf16 v[50:53], v[218:221], v[160:163], v[50:53]
	v_mfma_f32_16x16x32_bf16 v[42:45], v[206:209], v[168:171], v[42:45]
	v_mfma_f32_16x16x32_bf16 v[34:37], v[218:221], v[168:171], v[34:37]
	v_mfma_f32_16x16x32_bf16 v[26:29], v[206:209], v[186:189], v[26:29]
	v_mfma_f32_16x16x32_bf16 v[18:21], v[218:221], v[186:189], v[18:21]
	v_mfma_f32_16x16x32_bf16 v[10:13], v[206:209], v[198:201], v[10:13]
	v_mfma_f32_16x16x32_bf16 v[2:5], v[218:221], v[198:201], v[2:5]
	v_mfma_f32_16x16x32_bf16 v[58:61], v[214:217], v[164:167], v[58:61]
	v_mfma_f32_16x16x32_bf16 v[50:53], v[222:225], v[164:167], v[50:53]
	v_mfma_f32_16x16x32_bf16 v[42:45], v[214:217], v[172:175], v[42:45]
	v_mfma_f32_16x16x32_bf16 v[34:37], v[222:225], v[172:175], v[34:37]
	v_mfma_f32_16x16x32_bf16 v[26:29], v[214:217], v[190:193], v[26:29]
	v_mfma_f32_16x16x32_bf16 v[18:21], v[222:225], v[190:193], v[18:21]
	v_mfma_f32_16x16x32_bf16 v[10:13], v[214:217], v[202:205], v[10:13]
	v_mfma_f32_16x16x32_bf16 v[2:5], v[222:225], v[202:205], v[2:5]
	s_add_u32 s22, s22, 0x100
	s_addc_u32 s23, s23, 0
	s_add_u32 s49, s49, 0x100
	s_addc_u32 s50, s50, 0
	s_cmp_ge_i32 s51, s40
	s_mov_b32 s24, s51
	s_barrier
	s_cbranch_scc0 .LBB0_178
	s_branch .LBB0_161

; #define PG8_STAGE(bufoff, gbase, voff) do { _Pragma("unroll") for (int _i = 0; _i < 2; ++_i) \
;     __builtin_amdgcn_global_load_lds((const unsigned*)((const char*)(gbase) + (voff)[_i]), (LAS unsigned*)(lds + (bufoff) + ldsw + _i * 8192), 16, 0, 0); } while (0)
; #define PG8_LDA(dst, b, h) do { _Pragma("unroll") for (int m = 0; m < 4; ++m) _Pragma("unroll") for (int k = 0; k < 2; ++k) dst[m][k] = *(const LAS bf16x8*)(lds + PG8_SA(b, h) + aoff + m * 2048 + k * 1024); } while (0)
; #define PG8_LDB(dst, b, h) do { _Pragma("unroll") for (int n = 0; n < 2; ++n) _Pragma("unroll") for (int k = 0; k < 2; ++k) dst[n][k] = *(const LAS bf16x8*)(lds + PG8_SB(b, h) + boff + n * 2048 + k * 1024); } while (0)
; #define PG8_MMA(ai, bj, At, Bt) do { __builtin_amdgcn_s_setprio(1); _Pragma("unroll") for (int m = 0; m < 4; ++m) _Pragma("unroll") for (int n = 0; n < 2; ++n) _Pragma("unroll") for (int k = 0; k < 2; ++k) \
;     acc[ai][bj][m][n] = __builtin_amdgcn_mfma_f32_16x16x32_bf16(Bt[n][k], At[m][k], acc[ai][bj][m][n], 0, 0, 0); __builtin_amdgcn_s_setprio(0); } while (0)
; #define PG8_WAIT_L(n) asm volatile("s_waitcnt lgkmcnt(" #n ")" ::: "memory")
; #define PG8_BAR __builtin_amdgcn_s_barrier()
; #define PG8_SCHED __builtin_amdgcn_sched_barrier(0)
; template <class Epi, class Sched>
; DI void gemm_phase(LAS unsigned char* lds, const Gemm g, const Sched& S, const Epi& E) {
;     ...
;       PG8_LDB(B0, 0, 0); PG8_SCHED; PG8_LDA(At, 0, 0); PG8_STAGE(PG8_SA(1, 1), a1 + hstep, voffA);
;       PG8_WAIT_L(8); PG8_BAR; PG8_WAIT_L(0); PG8_MMA(0, 0, At, B0); PG8_BAR; PG8_SCHED;
;       PG8_LDB(B1, 0, 1); PG8_STAGE(PG8_SB(0, 0), b2, voffB);
;       PG8_BAR; PG8_WAIT_L(0); PG8_MMA(0, 1, At, B1); PG8_BAR;
;       PG8_LDA(At, 0, 1); PG8_STAGE(PG8_SA(0, 0), a2, voffA);
;       PG8_BAR; PG8_WAIT_L(0); PG8_MMA(1, 0, At, B0); PG8_BAR; PG8_SCHED;
.LBB0_191:
	s_add_i32 s34, s16, 2
	s_add_u32 s17, s14, 0xfe000080
	s_addc_u32 s18, s15, -1
	s_cmp_lg_u32 s31, s16
	s_cselect_b32 s19, s18, 0
	s_cselect_b32 s18, s17, 0
	s_add_u32 s16, s12, s18
	s_addc_u32 s17, s13, s19
	s_add_i32 s35, 16, 0x10000
	v_add_u32_e32 v156, s35, v142
	ds_read_b128 v[144:147], v156
	ds_read_b128 v[148:151], v156 offset:1024
	ds_read_b128 v[152:155], v156 offset:2048
	ds_read_b128 v[156:159], v156 offset:3072
	s_add_u32 s18, s2, s18
	s_addc_u32 s19, s3, s19
	v_lshl_add_u64 v[176:177], v[136:137], 0, s[14:15]
	s_add_i32 m0, s23, 0xc000
	ds_read_b128 v[160:163], v143
	ds_read_b128 v[164:167], v143 offset:1024
	ds_read_b128 v[168:171], v143 offset:2048
	ds_read_b128 v[172:175], v143 offset:3072
	ds_read_b128 v[186:189], v143 offset:4096
	ds_read_b128 v[190:193], v143 offset:5120
	ds_read_b128 v[198:201], v143 offset:6144
	ds_read_b128 v[202:205], v143 offset:7168
	global_load_lds_dwordx4 v[176:177], off
	v_lshl_add_u64 v[176:177], v[138:139], 0, s[14:15]
	s_add_i32 m0, s23, 0xe000
	s_nop 0
	global_load_lds_dwordx4 v[176:177], off
	s_waitcnt lgkmcnt(8)
	s_barrier
	s_waitcnt lgkmcnt(0)
	s_waitcnt lgkmcnt(0)
	v_mfma_f32_16x16x32_bf16 v[126:129], v[144:147], v[160:163], v[126:129]
	v_mfma_f32_16x16x32_bf16 v[118:121], v[152:155], v[160:163], v[118:121]
	v_mfma_f32_16x16x32_bf16 v[110:113], v[144:147], v[168:171], v[110:113]
	v_mfma_f32_16x16x32_bf16 v[102:105], v[152:155], v[168:171], v[102:105]
	v_mfma_f32_16x16x32_bf16 v[94:97], v[144:147], v[186:189], v[94:97]
	v_mfma_f32_16x16x32_bf16 v[86:89], v[152:155], v[186:189], v[86:89]
	v_mfma_f32_16x16x32_bf16 v[78:81], v[144:147], v[198:201], v[78:81]
	v_mfma_f32_16x16x32_bf16 v[70:73], v[152:155], v[198:201], v[70:73]
	v_mfma_f32_16x16x32_bf16 v[126:129], v[148:151], v[164:167], v[126:129]
	v_mfma_f32_16x16x32_bf16 v[118:121], v[156:159], v[164:167], v[118:121]
	v_mfma_f32_16x16x32_bf16 v[110:113], v[148:151], v[172:175], v[110:113]
	v_mfma_f32_16x16x32_bf16 v[102:105], v[156:159], v[172:175], v[102:105]
	v_mfma_f32_16x16x32_bf16 v[94:97], v[148:151], v[190:193], v[94:97]
	v_mfma_f32_16x16x32_bf16 v[86:89], v[156:159], v[190:193], v[86:89]
	v_mfma_f32_16x16x32_bf16 v[78:81], v[148:151], v[202:205], v[78:81]
	v_mfma_f32_16x16x32_bf16 v[70:73], v[156:159], v[202:205], v[70:73]
	s_barrier
	s_add_i32 s36, 16, 0x14000
	v_add_u32_e32 v176, s36, v142
	s_add_i32 s35, s35, s22
	ds_read_b128 v[206:209], v176
	ds_read_b128 v[214:217], v176 offset:1024
	ds_read_b128 v[218:221], v176 offset:2048
	ds_read_b128 v[222:225], v176 offset:3072
	v_lshl_add_u64 v[176:177], s[18:19], 0, v[0:1]
	s_mov_b32 m0, s35
	v_lshl_add_u64 v[180:181], s[18:19], 0, v[130:131]
	global_load_lds_dwordx4 v[176:177], off
	s_add_i32 m0, s35, 0x2000
	s_nop 0
	global_load_lds_dwordx4 v[180:181], off
	s_barrier
	s_waitcnt lgkmcnt(0)
	s_waitcnt lgkmcnt(0)
	v_mfma_f32_16x16x32_bf16 v[122:125], v[206:209], v[160:163], v[122:125]
	v_mfma_f32_16x16x32_bf16 v[114:117], v[218:221], v[160:163], v[114:117]
	v_mfma_f32_16x16x32_bf16 v[106:109], v[206:209], v[168:171], v[106:109]
	v_mfma_f32_16x16x32_bf16 v[98:101], v[218:221], v[168:171], v[98:101]
	v_mfma_f32_16x16x32_bf16 v[90:93], v[206:209], v[186:189], v[90:93]
	v_mfma_f32_16x16x32_bf16 v[82:85], v[218:221], v[186:189], v[82:85]
	v_mfma_f32_16x16x32_bf16 v[74:77], v[206:209], v[198:201], v[74:77]
	v_mfma_f32_16x16x32_bf16 v[66:69], v[218:221], v[198:201], v[66:69]
	v_mfma_f32_16x16x32_bf16 v[122:125], v[214:217], v[164:167], v[122:125]
	v_mfma_f32_16x16x32_bf16 v[114:117], v[222:225], v[164:167], v[114:117]
	v_mfma_f32_16x16x32_bf16 v[106:109], v[214:217], v[172:175], v[106:109]
	v_mfma_f32_16x16x32_bf16 v[98:101], v[222:225], v[172:175], v[98:101]
	v_mfma_f32_16x16x32_bf16 v[90:93], v[214:217], v[190:193], v[90:93]
	v_mfma_f32_16x16x32_bf16 v[82:85], v[222:225], v[190:193], v[82:85]
	v_mfma_f32_16x16x32_bf16 v[74:77], v[214:217], v[202:205], v[74:77]
	v_mfma_f32_16x16x32_bf16 v[66:69], v[222:225], v[202:205], v[66:69]
	s_mov_b32 m0, s23
	v_lshl_add_u64 v[182:183], s[16:17], 0, v[134:135]
	s_barrier
	ds_read_b128 v[160:163], v143 offset:16384
	ds_read_b128 v[164:167], v143 offset:17408
	ds_read_b128 v[168:171], v143 offset:18432
	ds_read_b128 v[172:175], v143 offset:19456
	ds_read_b128 v[186:189], v143 offset:20480
	ds_read_b128 v[190:193], v143 offset:21504
	ds_read_b128 v[198:201], v143 offset:22528
	ds_read_b128 v[202:205], v143 offset:23552
	global_load_lds_dwordx4 v[182:183], off
	v_lshl_add_u64 v[184:185], s[16:17], 0, v[132:133]
	s_mov_b32 m0, s24
	s_nop 0
	global_load_lds_dwordx4 v[184:185], off
	s_barrier
	s_waitcnt lgkmcnt(0)
	s_waitcnt lgkmcnt(0)
	v_mfma_f32_16x16x32_bf16 v[62:65], v[144:147], v[160:163], v[62:65]
	v_mfma_f32_16x16x32_bf16 v[54:57], v[152:155], v[160:163], v[54:57]
	v_mfma_f32_16x16x32_bf16 v[46:49], v[144:147], v[168:171], v[46:49]
	v_mfma_f32_16x16x32_bf16 v[38:41], v[152:155], v[168:171], v[38:41]
	v_mfma_f32_16x16x32_bf16 v[30:33], v[144:147], v[186:189], v[30:33]
	v_mfma_f32_16x16x32_bf16 v[22:25], v[152:155], v[186:189], v[22:25]
	v_mfma_f32_16x16x32_bf16 v[14:17], v[144:147], v[198:201], v[14:17]
	v_mfma_f32_16x16x32_bf16 v[6:9], v[152:155], v[198:201], v[6:9]
	v_mfma_f32_16x16x32_bf16 v[62:65], v[148:151], v[164:167], v[62:65]
	v_mfma_f32_16x16x32_bf16 v[54:57], v[156:159], v[164:167], v[54:57]
	v_mfma_f32_16x16x32_bf16 v[46:49], v[148:151], v[172:175], v[46:49]
	v_mfma_f32_16x16x32_bf16 v[38:41], v[156:159], v[172:175], v[38:41]
	v_mfma_f32_16x16x32_bf16 v[30:33], v[148:151], v[190:193], v[30:33]
	v_mfma_f32_16x16x32_bf16 v[22:25], v[156:159], v[190:193], v[22:25]
	v_mfma_f32_16x16x32_bf16 v[14:17], v[148:151], v[202:205], v[14:17]
	v_mfma_f32_16x16x32_bf16 v[6:9], v[156:159], v[202:205], v[6:9]
	s_barrier
; #define PG8_STAGE(bufoff, gbase, voff) do { _Pragma("unroll") for (int _i = 0; _i < 2; ++_i) \
;     __builtin_amdgcn_global_load_lds((const unsigned*)((const char*)(gbase) + (voff)[_i]), (LAS unsigned*)(lds + (bufoff) + ldsw + _i * 8192), 16, 0, 0); } while (0)
; #define PG8_LDA(dst, b, h) do { _Pragma("unroll") for (int m = 0; m < 4; ++m) _Pragma("unroll") for (int k = 0; k < 2; ++k) dst[m][k] = *(const LAS bf16x8*)(lds + PG8_SA(b, h) + aoff + m * 2048 + k * 1024); } while (0)
; #define PG8_LDB(dst, b, h) do { _Pragma("unroll") for (int n = 0; n < 2; ++n) _Pragma("unroll") for (int k = 0; k < 2; ++k) dst[n][k] = *(const LAS bf16x8*)(lds + PG8_SB(b, h) + boff + n * 2048 + k * 1024); } while (0)
; #define PG8_MMA(ai, bj, At, Bt) do { __builtin_amdgcn_s_setprio(1); _Pragma("unroll") for (int m = 0; m < 4; ++m) _Pragma("unroll") for (int n = 0; n < 2; ++n) _Pragma("unroll") for (int k = 0; k < 2; ++k) \
;     acc[ai][bj][m][n] = __builtin_amdgcn_mfma_f32_16x16x32_bf16(Bt[n][k], At[m][k], acc[ai][bj][m][n], 0, 0, 0); __builtin_amdgcn_s_setprio(0); } while (0)
; #define PG8_WAIT_V(n) asm volatile("s_waitcnt vmcnt(" #n ")" ::: "memory")
; #define PG8_WAIT_L(n) asm volatile("s_waitcnt lgkmcnt(" #n ")" ::: "memory")
; #define PG8_BAR __builtin_amdgcn_s_barrier()
; #define PG8_SCHED __builtin_amdgcn_sched_barrier(0)
; template <class Epi, class Sched>
; DI void gemm_phase(LAS unsigned char* lds, const Gemm g, const Sched& S, const Epi& E) {
;     ...
;       PG8_STAGE(PG8_SB(0, 1), b2 + hstepB, voffB);
;       PG8_WAIT_V(6); PG8_BAR; PG8_MMA(1, 1, At, B1); PG8_BAR;
;       PG8_LDB(B0, 1, 0); PG8_SCHED; PG8_LDA(At, 1, 0); PG8_STAGE(PG8_SA(0, 1), a2 + hstep, voffA);
;       PG8_WAIT_L(8); PG8_BAR; PG8_WAIT_L(0); PG8_MMA(0, 0, At, B0); PG8_BAR; PG8_SCHED;
;       PG8_LDB(B1, 1, 1); PG8_STAGE(PG8_SB(1, 0), b3, voffB);
;       PG8_BAR; PG8_WAIT_L(0); PG8_MMA(0, 1, At, B1); PG8_BAR;
	s_add_u32 s18, s18, s0
	s_addc_u32 s19, s19, s1
	s_add_i32 s35, s36, s22
	v_lshl_add_u64 v[226:227], s[18:19], 0, v[0:1]
	s_mov_b32 m0, s35
	v_lshl_add_u64 v[228:229], s[18:19], 0, v[130:131]
	global_load_lds_dwordx4 v[226:227], off
	s_add_i32 m0, s35, 0x2000
	s_nop 0
	global_load_lds_dwordx4 v[228:229], off
	s_waitcnt vmcnt(6)
	s_barrier
	v_mfma_f32_16x16x32_bf16 v[58:61], v[206:209], v[160:163], v[58:61]
	v_mfma_f32_16x16x32_bf16 v[50:53], v[218:221], v[160:163], v[50:53]
	v_mfma_f32_16x16x32_bf16 v[42:45], v[206:209], v[168:171], v[42:45]
	v_mfma_f32_16x16x32_bf16 v[34:37], v[218:221], v[168:171], v[34:37]
	v_mfma_f32_16x16x32_bf16 v[26:29], v[206:209], v[186:189], v[26:29]
	v_mfma_f32_16x16x32_bf16 v[18:21], v[218:221], v[186:189], v[18:21]
	v_mfma_f32_16x16x32_bf16 v[10:13], v[206:209], v[198:201], v[10:13]
	v_mfma_f32_16x16x32_bf16 v[2:5], v[218:221], v[198:201], v[2:5]
	v_mfma_f32_16x16x32_bf16 v[58:61], v[214:217], v[164:167], v[58:61]
	v_mfma_f32_16x16x32_bf16 v[50:53], v[222:225], v[164:167], v[50:53]
	v_mfma_f32_16x16x32_bf16 v[42:45], v[214:217], v[172:175], v[42:45]
	v_mfma_f32_16x16x32_bf16 v[34:37], v[222:225], v[172:175], v[34:37]
	v_mfma_f32_16x16x32_bf16 v[26:29], v[214:217], v[190:193], v[26:29]
	v_mfma_f32_16x16x32_bf16 v[18:21], v[222:225], v[190:193], v[18:21]
	v_mfma_f32_16x16x32_bf16 v[10:13], v[214:217], v[202:205], v[10:13]
	v_mfma_f32_16x16x32_bf16 v[2:5], v[222:225], v[202:205], v[2:5]
	s_add_i32 s18, 16, 0x18000
	v_add_u32_e32 v156, s18, v142
	s_barrier
	ds_read_b128 v[144:147], v156
	ds_read_b128 v[148:151], v156 offset:1024
	ds_read_b128 v[152:155], v156 offset:2048
	ds_read_b128 v[156:159], v156 offset:3072
	s_add_u32 s16, s16, s0
	s_addc_u32 s17, s17, s1
	s_mov_b32 m0, s25
	v_lshl_add_u64 v[206:207], s[16:17], 0, v[134:135]
	ds_read_b128 v[160:163], v143 offset:32768
	ds_read_b128 v[164:167], v143 offset:33792
	ds_read_b128 v[168:171], v143 offset:34816
	ds_read_b128 v[172:175], v143 offset:35840
	ds_read_b128 v[186:189], v143 offset:36864
	ds_read_b128 v[190:193], v143 offset:37888
	ds_read_b128 v[198:201], v143 offset:38912
	ds_read_b128 v[202:205], v143 offset:39936
	global_load_lds_dwordx4 v[206:207], off
	v_lshl_add_u64 v[206:207], s[16:17], 0, v[132:133]
	s_mov_b32 m0, s26
	s_nop 0
	global_load_lds_dwordx4 v[206:207], off
	s_waitcnt lgkmcnt(8)
	s_barrier
	s_waitcnt lgkmcnt(0)
	s_waitcnt lgkmcnt(0)
	v_mfma_f32_16x16x32_bf16 v[126:129], v[144:147], v[160:163], v[126:129]
	v_mfma_f32_16x16x32_bf16 v[118:121], v[152:155], v[160:163], v[118:121]
	v_mfma_f32_16x16x32_bf16 v[110:113], v[144:147], v[168:171], v[110:113]
	v_mfma_f32_16x16x32_bf16 v[102:105], v[152:155], v[168:171], v[102:105]
	v_mfma_f32_16x16x32_bf16 v[94:97], v[144:147], v[186:189], v[94:97]
	v_mfma_f32_16x16x32_bf16 v[86:89], v[152:155], v[186:189], v[86:89]
	v_mfma_f32_16x16x32_bf16 v[78:81], v[144:147], v[198:201], v[78:81]
	v_mfma_f32_16x16x32_bf16 v[70:73], v[152:155], v[198:201], v[70:73]
	v_mfma_f32_16x16x32_bf16 v[126:129], v[148:151], v[164:167], v[126:129]
	v_mfma_f32_16x16x32_bf16 v[118:121], v[156:159], v[164:167], v[118:121]
	v_mfma_f32_16x16x32_bf16 v[110:113], v[148:151], v[172:175], v[110:113]
	v_mfma_f32_16x16x32_bf16 v[102:105], v[156:159], v[172:175], v[102:105]
	v_mfma_f32_16x16x32_bf16 v[94:97], v[148:151], v[190:193], v[94:97]
	v_mfma_f32_16x16x32_bf16 v[86:89], v[156:159], v[190:193], v[86:89]
	v_mfma_f32_16x16x32_bf16 v[78:81], v[148:151], v[202:205], v[78:81]
	v_mfma_f32_16x16x32_bf16 v[70:73], v[156:159], v[202:205], v[70:73]
	s_barrier
	s_add_i32 s16, 16, 0x1c000
	s_add_i32 s17, s18, s22
	v_add_u32_e32 v194, s16, v142
	v_lshl_add_u64 v[176:177], v[176:177], 0, s[70:71]
	s_mov_b32 m0, s17
	ds_read_b128 v[206:209], v194
	ds_read_b128 v[214:217], v194 offset:1024
	ds_read_b128 v[218:221], v194 offset:2048
	ds_read_b128 v[222:225], v194 offset:3072
	global_load_lds_dwordx4 v[176:177], off
	v_lshl_add_u64 v[176:177], v[180:181], 0, s[70:71]
	s_add_i32 m0, s17, 0x2000
	s_nop 0
	global_load_lds_dwordx4 v[176:177], off
	s_barrier
; #define PG8_STAGE(bufoff, gbase, voff) do { _Pragma("unroll") for (int _i = 0; _i < 2; ++_i) \
;     __builtin_amdgcn_global_load_lds((const unsigned*)((const char*)(gbase) + (voff)[_i]), (LAS unsigned*)(lds + (bufoff) + ldsw + _i * 8192), 16, 0, 0); } while (0)
; #define PG8_LDA(dst, b, h) do { _Pragma("unroll") for (int m = 0; m < 4; ++m) _Pragma("unroll") for (int k = 0; k < 2; ++k) dst[m][k] = *(const LAS bf16x8*)(lds + PG8_SA(b, h) + aoff + m * 2048 + k * 1024); } while (0)
; #define PG8_MMA(ai, bj, At, Bt) do { __builtin_amdgcn_s_setprio(1); _Pragma("unroll") for (int m = 0; m < 4; ++m) _Pragma("unroll") for (int n = 0; n < 2; ++n) _Pragma("unroll") for (int k = 0; k < 2; ++k) \
;     acc[ai][bj][m][n] = __builtin_amdgcn_mfma_f32_16x16x32_bf16(Bt[n][k], At[m][k], acc[ai][bj][m][n], 0, 0, 0); __builtin_amdgcn_s_setprio(0); } while (0)
; #define PG8_WAIT_V(n) asm volatile("s_waitcnt vmcnt(" #n ")" ::: "memory")
; #define PG8_WAIT_L(n) asm volatile("s_waitcnt lgkmcnt(" #n ")" ::: "memory")
; #define PG8_BAR __builtin_amdgcn_s_barrier()
; #define PG8_SCHED __builtin_amdgcn_sched_barrier(0)
; template <class Epi, class Sched>
; DI void gemm_phase(LAS unsigned char* lds, const Gemm g, const Sched& S, const Epi& E) {
;     ...
;       PG8_BAR; PG8_WAIT_L(0); PG8_MMA(0, 1, At, B1); PG8_BAR;
;       PG8_LDA(At, 1, 1); PG8_STAGE(PG8_SA(1, 0), a3, voffA);
;       PG8_BAR; PG8_WAIT_L(0); PG8_MMA(1, 0, At, B0); PG8_BAR; PG8_SCHED;
;       PG8_STAGE(PG8_SB(1, 1), b3 + hstepB, voffB);
;       PG8_WAIT_V(6); PG8_BAR; PG8_MMA(1, 1, At, B1); PG8_BAR;
;     }
	s_waitcnt lgkmcnt(0)
	s_waitcnt lgkmcnt(0)
	v_mfma_f32_16x16x32_bf16 v[122:125], v[206:209], v[160:163], v[122:125]
	v_mfma_f32_16x16x32_bf16 v[114:117], v[218:221], v[160:163], v[114:117]
	v_mfma_f32_16x16x32_bf16 v[106:109], v[206:209], v[168:171], v[106:109]
	v_mfma_f32_16x16x32_bf16 v[98:101], v[218:221], v[168:171], v[98:101]
	v_mfma_f32_16x16x32_bf16 v[90:93], v[206:209], v[186:189], v[90:93]
	v_mfma_f32_16x16x32_bf16 v[82:85], v[218:221], v[186:189], v[82:85]
	v_mfma_f32_16x16x32_bf16 v[74:77], v[206:209], v[198:201], v[74:77]
	v_mfma_f32_16x16x32_bf16 v[66:69], v[218:221], v[198:201], v[66:69]
	v_mfma_f32_16x16x32_bf16 v[122:125], v[214:217], v[164:167], v[122:125]
	v_mfma_f32_16x16x32_bf16 v[114:117], v[222:225], v[164:167], v[114:117]
	v_mfma_f32_16x16x32_bf16 v[106:109], v[214:217], v[172:175], v[106:109]
	v_mfma_f32_16x16x32_bf16 v[98:101], v[222:225], v[172:175], v[98:101]
	v_mfma_f32_16x16x32_bf16 v[90:93], v[214:217], v[190:193], v[90:93]
	v_mfma_f32_16x16x32_bf16 v[82:85], v[222:225], v[190:193], v[82:85]
	v_mfma_f32_16x16x32_bf16 v[74:77], v[214:217], v[202:205], v[74:77]
	v_mfma_f32_16x16x32_bf16 v[66:69], v[222:225], v[202:205], v[66:69]
	s_mov_b32 m0, s27
	v_lshl_add_u64 v[176:177], v[182:183], 0, s[70:71]
	s_barrier
	ds_read_b128 v[160:163], v143 offset:49152
	ds_read_b128 v[164:167], v143 offset:50176
	ds_read_b128 v[168:171], v143 offset:51200
	ds_read_b128 v[172:175], v143 offset:52224
	ds_read_b128 v[186:189], v143 offset:53248
	ds_read_b128 v[190:193], v143 offset:54272
	ds_read_b128 v[198:201], v143 offset:55296
	ds_read_b128 v[202:205], v143 offset:56320
	global_load_lds_dwordx4 v[176:177], off
	v_lshl_add_u64 v[176:177], v[184:185], 0, s[70:71]
	s_mov_b32 m0, s29
	s_nop 0
	global_load_lds_dwordx4 v[176:177], off
	s_barrier
	s_waitcnt lgkmcnt(0)
	s_waitcnt lgkmcnt(0)
	v_mfma_f32_16x16x32_bf16 v[62:65], v[144:147], v[160:163], v[62:65]
	v_mfma_f32_16x16x32_bf16 v[54:57], v[152:155], v[160:163], v[54:57]
	v_mfma_f32_16x16x32_bf16 v[46:49], v[144:147], v[168:171], v[46:49]
	v_mfma_f32_16x16x32_bf16 v[38:41], v[152:155], v[168:171], v[38:41]
	v_mfma_f32_16x16x32_bf16 v[30:33], v[144:147], v[186:189], v[30:33]
	v_mfma_f32_16x16x32_bf16 v[22:25], v[152:155], v[186:189], v[22:25]
	v_mfma_f32_16x16x32_bf16 v[14:17], v[144:147], v[198:201], v[14:17]
	v_mfma_f32_16x16x32_bf16 v[6:9], v[152:155], v[198:201], v[6:9]
	v_mfma_f32_16x16x32_bf16 v[62:65], v[148:151], v[164:167], v[62:65]
	v_mfma_f32_16x16x32_bf16 v[54:57], v[156:159], v[164:167], v[54:57]
	v_mfma_f32_16x16x32_bf16 v[46:49], v[148:151], v[172:175], v[46:49]
	v_mfma_f32_16x16x32_bf16 v[38:41], v[156:159], v[172:175], v[38:41]
	v_mfma_f32_16x16x32_bf16 v[30:33], v[148:151], v[190:193], v[30:33]
	v_mfma_f32_16x16x32_bf16 v[22:25], v[156:159], v[190:193], v[22:25]
	v_mfma_f32_16x16x32_bf16 v[14:17], v[148:151], v[202:205], v[14:17]
	v_mfma_f32_16x16x32_bf16 v[6:9], v[156:159], v[202:205], v[6:9]
	s_barrier
	s_add_i32 s16, s16, s22
	v_lshl_add_u64 v[144:145], v[226:227], 0, s[70:71]
	s_mov_b32 m0, s16
	s_nop 0
	global_load_lds_dwordx4 v[144:145], off
	v_lshl_add_u64 v[144:145], v[228:229], 0, s[70:71]
	s_add_i32 m0, s16, 0x2000
	s_nop 0
	global_load_lds_dwordx4 v[144:145], off
	s_waitcnt vmcnt(6)
	s_barrier
	v_mfma_f32_16x16x32_bf16 v[58:61], v[206:209], v[160:163], v[58:61]
	v_mfma_f32_16x16x32_bf16 v[50:53], v[218:221], v[160:163], v[50:53]
	v_mfma_f32_16x16x32_bf16 v[42:45], v[206:209], v[168:171], v[42:45]
	v_mfma_f32_16x16x32_bf16 v[34:37], v[218:221], v[168:171], v[34:37]
	v_mfma_f32_16x16x32_bf16 v[26:29], v[206:209], v[186:189], v[26:29]
	v_mfma_f32_16x16x32_bf16 v[18:21], v[218:221], v[186:189], v[18:21]
	v_mfma_f32_16x16x32_bf16 v[10:13], v[206:209], v[198:201], v[10:13]
	v_mfma_f32_16x16x32_bf16 v[2:5], v[218:221], v[198:201], v[2:5]
	v_mfma_f32_16x16x32_bf16 v[58:61], v[214:217], v[164:167], v[58:61]
	v_mfma_f32_16x16x32_bf16 v[50:53], v[222:225], v[164:167], v[50:53]
	v_mfma_f32_16x16x32_bf16 v[42:45], v[214:217], v[172:175], v[42:45]
	v_mfma_f32_16x16x32_bf16 v[34:37], v[222:225], v[172:175], v[34:37]
	v_mfma_f32_16x16x32_bf16 v[26:29], v[214:217], v[190:193], v[26:29]
	v_mfma_f32_16x16x32_bf16 v[18:21], v[222:225], v[190:193], v[18:21]
	v_mfma_f32_16x16x32_bf16 v[10:13], v[214:217], v[202:205], v[10:13]
	v_mfma_f32_16x16x32_bf16 v[2:5], v[222:225], v[202:205], v[2:5]
	s_add_u32 s14, s14, 0x100
	s_addc_u32 s15, s15, 0
	s_cmp_ge_i32 s34, s30
	s_mov_b32 s16, s34
	s_barrier
	s_cbranch_scc0 .LBB0_191

; #define PG8_STAGE(bufoff, gbase, voff) do { _Pragma("unroll") for (int _i = 0; _i < 2; ++_i) \
;     __builtin_amdgcn_global_load_lds((const unsigned*)((const char*)(gbase) + (voff)[_i]), (LAS unsigned*)(lds + (bufoff) + ldsw + _i * 8192), 16, 0, 0); } while (0)
; #define PG8_LDA(dst, b, h) do { _Pragma("unroll") for (int m = 0; m < 4; ++m) _Pragma("unroll") for (int k = 0; k < 2; ++k) dst[m][k] = *(const LAS bf16x8*)(lds + PG8_SA(b, h) + aoff + m * 2048 + k * 1024); } while (0)
; #define PG8_LDB(dst, b, h) do { _Pragma("unroll") for (int n = 0; n < 2; ++n) _Pragma("unroll") for (int k = 0; k < 2; ++k) dst[n][k] = *(const LAS bf16x8*)(lds + PG8_SB(b, h) + boff + n * 2048 + k * 1024); } while (0)
; #define PG8_MMA(ai, bj, At, Bt) do { __builtin_amdgcn_s_setprio(1); _Pragma("unroll") for (int m = 0; m < 4; ++m) _Pragma("unroll") for (int n = 0; n < 2; ++n) _Pragma("unroll") for (int k = 0; k < 2; ++k) \
;     acc[ai][bj][m][n] = __builtin_amdgcn_mfma_f32_16x16x32_bf16(Bt[n][k], At[m][k], acc[ai][bj][m][n], 0, 0, 0); __builtin_amdgcn_s_setprio(0); } while (0)
; #define PG8_WAIT_L(n) asm volatile("s_waitcnt lgkmcnt(" #n ")" ::: "memory")
; #define PG8_BAR __builtin_amdgcn_s_barrier()
; #define PG8_SCHED __builtin_amdgcn_sched_barrier(0)
; template <class Epi, class Sched>
; DI void gemm_phase(LAS unsigned char* lds, const Gemm g, const Sched& S, const Epi& E) {
;     ...
;       PG8_LDB(B0, 0, 0); PG8_SCHED; PG8_LDA(At, 0, 0); PG8_STAGE(PG8_SA(1, 1), a1 + hstep, voffA);
;       PG8_WAIT_L(8); PG8_BAR; PG8_WAIT_L(0); PG8_MMA(0, 0, At, B0); PG8_BAR; PG8_SCHED;
;       PG8_LDB(B1, 0, 1); PG8_STAGE(PG8_SB(0, 0), b2, voffB);
;       PG8_BAR; PG8_WAIT_L(0); PG8_MMA(0, 1, At, B1); PG8_BAR;
;       PG8_LDA(At, 0, 1); PG8_STAGE(PG8_SA(0, 0), a2, voffA);
;       PG8_BAR; PG8_WAIT_L(0); PG8_MMA(1, 0, At, B0); PG8_BAR; PG8_SCHED;
.LBB0_217:
	s_add_i32 s40, s3, 2
	s_add_u32 s18, s16, 0x80
	s_addc_u32 s19, s17, 0
	s_cmp_lg_u32 s39, s3
	s_cselect_b32 s20, s18, 0
	s_cselect_b32 s3, s19, 0
	s_add_u32 s18, s14, s20
	s_addc_u32 s19, s15, s3
	s_add_i32 s41, 16, 0x10000
	v_add_u32_e32 v139, s41, v137
	ds_read_b128 v[140:143], v139
	ds_read_b128 v[148:151], v139 offset:1024
	ds_read_b128 v[152:155], v139 offset:2048
	ds_read_b128 v[156:159], v139 offset:3072
	s_add_u32 s20, s12, s20
	s_addc_u32 s21, s13, s3
	v_lshl_add_u64 v[144:145], v[132:133], 0, s[16:17]
	s_add_i32 m0, s30, 0xc000
	ds_read_b128 v[160:163], v138
	ds_read_b128 v[164:167], v138 offset:1024
	ds_read_b128 v[168:171], v138 offset:2048
	ds_read_b128 v[172:175], v138 offset:3072
	ds_read_b128 v[186:189], v138 offset:4096
	ds_read_b128 v[190:193], v138 offset:5120
	ds_read_b128 v[198:201], v138 offset:6144
	ds_read_b128 v[202:205], v138 offset:7168
	global_load_lds_dwordx4 v[144:145], off
	v_lshl_add_u64 v[144:145], v[134:135], 0, s[16:17]
	s_add_i32 m0, s30, 0xe000
	s_nop 0
	global_load_lds_dwordx4 v[144:145], off
	s_waitcnt lgkmcnt(8)
	s_barrier
	s_waitcnt lgkmcnt(0)
	s_waitcnt lgkmcnt(0)
	v_mfma_f32_16x16x32_bf16 v[126:129], v[140:143], v[160:163], v[126:129]
	v_mfma_f32_16x16x32_bf16 v[122:125], v[152:155], v[160:163], v[122:125]
	v_mfma_f32_16x16x32_bf16 v[110:113], v[140:143], v[168:171], v[110:113]
	v_mfma_f32_16x16x32_bf16 v[106:109], v[152:155], v[168:171], v[106:109]
	v_mfma_f32_16x16x32_bf16 v[94:97], v[140:143], v[186:189], v[94:97]
	v_mfma_f32_16x16x32_bf16 v[90:93], v[152:155], v[186:189], v[90:93]
	v_mfma_f32_16x16x32_bf16 v[78:81], v[140:143], v[198:201], v[78:81]
	v_mfma_f32_16x16x32_bf16 v[74:77], v[152:155], v[198:201], v[74:77]
	v_mfma_f32_16x16x32_bf16 v[126:129], v[148:151], v[164:167], v[126:129]
	v_mfma_f32_16x16x32_bf16 v[122:125], v[156:159], v[164:167], v[122:125]
	v_mfma_f32_16x16x32_bf16 v[110:113], v[148:151], v[172:175], v[110:113]
	v_mfma_f32_16x16x32_bf16 v[106:109], v[156:159], v[172:175], v[106:109]
	v_mfma_f32_16x16x32_bf16 v[94:97], v[148:151], v[190:193], v[94:97]
	v_mfma_f32_16x16x32_bf16 v[90:93], v[156:159], v[190:193], v[90:93]
	v_mfma_f32_16x16x32_bf16 v[78:81], v[148:151], v[202:205], v[78:81]
	v_mfma_f32_16x16x32_bf16 v[74:77], v[156:159], v[202:205], v[74:77]
	s_barrier
	s_add_i32 s3, 16, 0x14000
	s_add_i32 s41, s41, s29
	v_add_u32_e32 v139, s3, v137
	v_lshl_add_u64 v[144:145], s[20:21], 0, v[0:1]
	s_mov_b32 m0, s41
	ds_read_b128 v[206:209], v139
	ds_read_b128 v[214:217], v139 offset:1024
	ds_read_b128 v[218:221], v139 offset:2048
	ds_read_b128 v[222:225], v139 offset:3072
	global_load_lds_dwordx4 v[144:145], off
	v_lshl_add_u64 v[176:177], s[20:21], 0, v[130:131]
	s_add_i32 m0, s41, 0x2000
	s_nop 0
	global_load_lds_dwordx4 v[176:177], off
	s_barrier
	s_waitcnt lgkmcnt(0)
	s_waitcnt lgkmcnt(0)
	v_mfma_f32_16x16x32_bf16 v[118:121], v[206:209], v[160:163], v[118:121]
	v_mfma_f32_16x16x32_bf16 v[114:117], v[218:221], v[160:163], v[114:117]
	v_mfma_f32_16x16x32_bf16 v[102:105], v[206:209], v[168:171], v[102:105]
	v_mfma_f32_16x16x32_bf16 v[98:101], v[218:221], v[168:171], v[98:101]
	v_mfma_f32_16x16x32_bf16 v[86:89], v[206:209], v[186:189], v[86:89]
	v_mfma_f32_16x16x32_bf16 v[82:85], v[218:221], v[186:189], v[82:85]
	v_mfma_f32_16x16x32_bf16 v[70:73], v[206:209], v[198:201], v[70:73]
	v_mfma_f32_16x16x32_bf16 v[66:69], v[218:221], v[198:201], v[66:69]
	v_mfma_f32_16x16x32_bf16 v[118:121], v[214:217], v[164:167], v[118:121]
	v_mfma_f32_16x16x32_bf16 v[114:117], v[222:225], v[164:167], v[114:117]
	v_mfma_f32_16x16x32_bf16 v[102:105], v[214:217], v[172:175], v[102:105]
	v_mfma_f32_16x16x32_bf16 v[98:101], v[222:225], v[172:175], v[98:101]
	v_mfma_f32_16x16x32_bf16 v[86:89], v[214:217], v[190:193], v[86:89]
	v_mfma_f32_16x16x32_bf16 v[82:85], v[222:225], v[190:193], v[82:85]
	v_mfma_f32_16x16x32_bf16 v[70:73], v[214:217], v[202:205], v[70:73]
	v_mfma_f32_16x16x32_bf16 v[66:69], v[222:225], v[202:205], v[66:69]
	s_mov_b32 m0, s30
	v_lshl_add_u64 v[180:181], s[18:19], 0, v[0:1]
	s_barrier
	ds_read_b128 v[160:163], v138 offset:16384
	ds_read_b128 v[164:167], v138 offset:17408
	ds_read_b128 v[168:171], v138 offset:18432
	ds_read_b128 v[172:175], v138 offset:19456
	ds_read_b128 v[186:189], v138 offset:20480
	ds_read_b128 v[190:193], v138 offset:21504
	ds_read_b128 v[198:201], v138 offset:22528
	ds_read_b128 v[202:205], v138 offset:23552
	global_load_lds_dwordx4 v[180:181], off
	v_lshl_add_u64 v[182:183], s[18:19], 0, v[130:131]
	s_mov_b32 m0, s31
	s_nop 0
	global_load_lds_dwordx4 v[182:183], off
	s_barrier
	s_waitcnt lgkmcnt(0)
	s_waitcnt lgkmcnt(0)
	v_mfma_f32_16x16x32_bf16 v[62:65], v[140:143], v[160:163], v[62:65]
	v_mfma_f32_16x16x32_bf16 v[58:61], v[152:155], v[160:163], v[58:61]
	v_mfma_f32_16x16x32_bf16 v[50:53], v[140:143], v[168:171], v[50:53]
	v_mfma_f32_16x16x32_bf16 v[42:45], v[152:155], v[168:171], v[42:45]
	v_mfma_f32_16x16x32_bf16 v[34:37], v[140:143], v[186:189], v[34:37]
	v_mfma_f32_16x16x32_bf16 v[26:29], v[152:155], v[186:189], v[26:29]
	v_mfma_f32_16x16x32_bf16 v[14:17], v[140:143], v[198:201], v[14:17]
	v_mfma_f32_16x16x32_bf16 v[10:13], v[152:155], v[198:201], v[10:13]
	v_mfma_f32_16x16x32_bf16 v[62:65], v[148:151], v[164:167], v[62:65]
	v_mfma_f32_16x16x32_bf16 v[58:61], v[156:159], v[164:167], v[58:61]
	v_mfma_f32_16x16x32_bf16 v[50:53], v[148:151], v[172:175], v[50:53]
	v_mfma_f32_16x16x32_bf16 v[42:45], v[156:159], v[172:175], v[42:45]
	v_mfma_f32_16x16x32_bf16 v[34:37], v[148:151], v[190:193], v[34:37]
	v_mfma_f32_16x16x32_bf16 v[26:29], v[156:159], v[190:193], v[26:29]
	v_mfma_f32_16x16x32_bf16 v[14:17], v[148:151], v[202:205], v[14:17]
	v_mfma_f32_16x16x32_bf16 v[10:13], v[156:159], v[202:205], v[10:13]
	s_barrier
; #define PG8_STAGE(bufoff, gbase, voff) do { _Pragma("unroll") for (int _i = 0; _i < 2; ++_i) \
;     __builtin_amdgcn_global_load_lds((const unsigned*)((const char*)(gbase) + (voff)[_i]), (LAS unsigned*)(lds + (bufoff) + ldsw + _i * 8192), 16, 0, 0); } while (0)
; #define PG8_LDA(dst, b, h) do { _Pragma("unroll") for (int m = 0; m < 4; ++m) _Pragma("unroll") for (int k = 0; k < 2; ++k) dst[m][k] = *(const LAS bf16x8*)(lds + PG8_SA(b, h) + aoff + m * 2048 + k * 1024); } while (0)
; #define PG8_LDB(dst, b, h) do { _Pragma("unroll") for (int n = 0; n < 2; ++n) _Pragma("unroll") for (int k = 0; k < 2; ++k) dst[n][k] = *(const LAS bf16x8*)(lds + PG8_SB(b, h) + boff + n * 2048 + k * 1024); } while (0)
; #define PG8_MMA(ai, bj, At, Bt) do { __builtin_amdgcn_s_setprio(1); _Pragma("unroll") for (int m = 0; m < 4; ++m) _Pragma("unroll") for (int n = 0; n < 2; ++n) _Pragma("unroll") for (int k = 0; k < 2; ++k) \
;     acc[ai][bj][m][n] = __builtin_amdgcn_mfma_f32_16x16x32_bf16(Bt[n][k], At[m][k], acc[ai][bj][m][n], 0, 0, 0); __builtin_amdgcn_s_setprio(0); } while (0)
; #define PG8_WAIT_V(n) asm volatile("s_waitcnt vmcnt(" #n ")" ::: "memory")
; #define PG8_WAIT_L(n) asm volatile("s_waitcnt lgkmcnt(" #n ")" ::: "memory")
; #define PG8_BAR __builtin_amdgcn_s_barrier()
; #define PG8_SCHED __builtin_amdgcn_sched_barrier(0)
; template <class Epi, class Sched>
; DI void gemm_phase(LAS unsigned char* lds, const Gemm g, const Sched& S, const Epi& E) {
;     ...
;       PG8_STAGE(PG8_SB(0, 1), b2 + hstepB, voffB);
;       PG8_WAIT_V(6); PG8_BAR; PG8_MMA(1, 1, At, B1); PG8_BAR;
;       PG8_LDB(B0, 1, 0); PG8_SCHED; PG8_LDA(At, 1, 0); PG8_STAGE(PG8_SA(0, 1), a2 + hstep, voffA);
;       PG8_WAIT_L(8); PG8_BAR; PG8_WAIT_L(0); PG8_MMA(0, 0, At, B0); PG8_BAR; PG8_SCHED;
;       PG8_LDB(B1, 1, 1); PG8_STAGE(PG8_SB(1, 0), b3, voffB);
;       PG8_BAR; PG8_WAIT_L(0); PG8_MMA(0, 1, At, B1); PG8_BAR;
	s_add_u32 s20, s20, s10
	s_addc_u32 s21, s21, s11
	s_add_i32 s3, s3, s29
	v_lshl_add_u64 v[184:185], s[20:21], 0, v[0:1]
	s_mov_b32 m0, s3
	v_lshl_add_u64 v[226:227], s[20:21], 0, v[130:131]
	global_load_lds_dwordx4 v[184:185], off
	s_add_i32 m0, s3, 0x2000
	s_nop 0
	global_load_lds_dwordx4 v[226:227], off
	s_waitcnt vmcnt(6)
	s_barrier
	v_mfma_f32_16x16x32_bf16 v[54:57], v[206:209], v[160:163], v[54:57]
	v_mfma_f32_16x16x32_bf16 v[46:49], v[218:221], v[160:163], v[46:49]
	v_mfma_f32_16x16x32_bf16 v[38:41], v[206:209], v[168:171], v[38:41]
	v_mfma_f32_16x16x32_bf16 v[30:33], v[218:221], v[168:171], v[30:33]
	v_mfma_f32_16x16x32_bf16 v[22:25], v[206:209], v[186:189], v[22:25]
	v_mfma_f32_16x16x32_bf16 v[18:21], v[218:221], v[186:189], v[18:21]
	v_mfma_f32_16x16x32_bf16 v[6:9], v[206:209], v[198:201], v[6:9]
	v_mfma_f32_16x16x32_bf16 v[2:5], v[218:221], v[198:201], v[2:5]
	v_mfma_f32_16x16x32_bf16 v[54:57], v[214:217], v[164:167], v[54:57]
	v_mfma_f32_16x16x32_bf16 v[46:49], v[222:225], v[164:167], v[46:49]
	v_mfma_f32_16x16x32_bf16 v[38:41], v[214:217], v[172:175], v[38:41]
	v_mfma_f32_16x16x32_bf16 v[30:33], v[222:225], v[172:175], v[30:33]
	v_mfma_f32_16x16x32_bf16 v[22:25], v[214:217], v[190:193], v[22:25]
	v_mfma_f32_16x16x32_bf16 v[18:21], v[222:225], v[190:193], v[18:21]
	v_mfma_f32_16x16x32_bf16 v[6:9], v[214:217], v[202:205], v[6:9]
	v_mfma_f32_16x16x32_bf16 v[2:5], v[222:225], v[202:205], v[2:5]
	s_add_i32 s3, 16, 0x18000
	v_add_u32_e32 v139, s3, v137
	s_barrier
	ds_read_b128 v[140:143], v139
	ds_read_b128 v[148:151], v139 offset:1024
	ds_read_b128 v[152:155], v139 offset:2048
	ds_read_b128 v[156:159], v139 offset:3072
	s_add_u32 s18, s18, s10
	s_addc_u32 s19, s19, s11
	s_mov_b32 m0, s34
	v_lshl_add_u64 v[206:207], s[18:19], 0, v[0:1]
	ds_read_b128 v[160:163], v138 offset:32768
	ds_read_b128 v[164:167], v138 offset:33792
	ds_read_b128 v[168:171], v138 offset:34816
	ds_read_b128 v[172:175], v138 offset:35840
	ds_read_b128 v[186:189], v138 offset:36864
	ds_read_b128 v[190:193], v138 offset:37888
	ds_read_b128 v[198:201], v138 offset:38912
	ds_read_b128 v[202:205], v138 offset:39936
	global_load_lds_dwordx4 v[206:207], off
	v_lshl_add_u64 v[206:207], s[18:19], 0, v[130:131]
	s_mov_b32 m0, s35
	s_nop 0
	global_load_lds_dwordx4 v[206:207], off
	s_waitcnt lgkmcnt(8)
	s_barrier
	s_waitcnt lgkmcnt(0)
	s_waitcnt lgkmcnt(0)
	v_mfma_f32_16x16x32_bf16 v[126:129], v[140:143], v[160:163], v[126:129]
	v_mfma_f32_16x16x32_bf16 v[122:125], v[152:155], v[160:163], v[122:125]
	v_mfma_f32_16x16x32_bf16 v[110:113], v[140:143], v[168:171], v[110:113]
	v_mfma_f32_16x16x32_bf16 v[106:109], v[152:155], v[168:171], v[106:109]
	v_mfma_f32_16x16x32_bf16 v[94:97], v[140:143], v[186:189], v[94:97]
	v_mfma_f32_16x16x32_bf16 v[90:93], v[152:155], v[186:189], v[90:93]
	v_mfma_f32_16x16x32_bf16 v[78:81], v[140:143], v[198:201], v[78:81]
	v_mfma_f32_16x16x32_bf16 v[74:77], v[152:155], v[198:201], v[74:77]
	v_mfma_f32_16x16x32_bf16 v[126:129], v[148:151], v[164:167], v[126:129]
	v_mfma_f32_16x16x32_bf16 v[122:125], v[156:159], v[164:167], v[122:125]
	v_mfma_f32_16x16x32_bf16 v[110:113], v[148:151], v[172:175], v[110:113]
	v_mfma_f32_16x16x32_bf16 v[106:109], v[156:159], v[172:175], v[106:109]
	v_mfma_f32_16x16x32_bf16 v[94:97], v[148:151], v[190:193], v[94:97]
	v_mfma_f32_16x16x32_bf16 v[90:93], v[156:159], v[190:193], v[90:93]
	v_mfma_f32_16x16x32_bf16 v[78:81], v[148:151], v[202:205], v[78:81]
	v_mfma_f32_16x16x32_bf16 v[74:77], v[156:159], v[202:205], v[74:77]
	s_barrier
	s_add_i32 s18, 16, 0x1c000
	s_add_i32 s3, s3, s29
	v_add_u32_e32 v139, s18, v137
	v_lshl_add_u64 v[144:145], v[144:145], 0, s[70:71]
	s_mov_b32 m0, s3
	ds_read_b128 v[206:209], v139
	ds_read_b128 v[214:217], v139 offset:1024
	ds_read_b128 v[218:221], v139 offset:2048
	ds_read_b128 v[222:225], v139 offset:3072
	global_load_lds_dwordx4 v[144:145], off
	v_lshl_add_u64 v[144:145], v[176:177], 0, s[70:71]
	s_add_i32 m0, s3, 0x2000
	s_nop 0
	global_load_lds_dwordx4 v[144:145], off
	s_barrier
; #define PG8_STAGE(bufoff, gbase, voff) do { _Pragma("unroll") for (int _i = 0; _i < 2; ++_i) \
;     __builtin_amdgcn_global_load_lds((const unsigned*)((const char*)(gbase) + (voff)[_i]), (LAS unsigned*)(lds + (bufoff) + ldsw + _i * 8192), 16, 0, 0); } while (0)
; #define PG8_LDA(dst, b, h) do { _Pragma("unroll") for (int m = 0; m < 4; ++m) _Pragma("unroll") for (int k = 0; k < 2; ++k) dst[m][k] = *(const LAS bf16x8*)(lds + PG8_SA(b, h) + aoff + m * 2048 + k * 1024); } while (0)
; #define PG8_MMA(ai, bj, At, Bt) do { __builtin_amdgcn_s_setprio(1); _Pragma("unroll") for (int m = 0; m < 4; ++m) _Pragma("unroll") for (int n = 0; n < 2; ++n) _Pragma("unroll") for (int k = 0; k < 2; ++k) \
;     acc[ai][bj][m][n] = __builtin_amdgcn_mfma_f32_16x16x32_bf16(Bt[n][k], At[m][k], acc[ai][bj][m][n], 0, 0, 0); __builtin_amdgcn_s_setprio(0); } while (0)
; #define PG8_WAIT_V(n) asm volatile("s_waitcnt vmcnt(" #n ")" ::: "memory")
; #define PG8_WAIT_L(n) asm volatile("s_waitcnt lgkmcnt(" #n ")" ::: "memory")
; #define PG8_BAR __builtin_amdgcn_s_barrier()
; #define PG8_SCHED __builtin_amdgcn_sched_barrier(0)
; template <class Epi, class Sched>
; DI void gemm_phase(LAS unsigned char* lds, const Gemm g, const Sched& S, const Epi& E) {
;     ...
;       PG8_BAR; PG8_WAIT_L(0); PG8_MMA(0, 1, At, B1); PG8_BAR;
;       PG8_LDA(At, 1, 1); PG8_STAGE(PG8_SA(1, 0), a3, voffA);
;       PG8_BAR; PG8_WAIT_L(0); PG8_MMA(1, 0, At, B0); PG8_BAR; PG8_SCHED;
;       PG8_STAGE(PG8_SB(1, 1), b3 + hstepB, voffB);
;       PG8_WAIT_V(6); PG8_BAR; PG8_MMA(1, 1, At, B1); PG8_BAR;
;     }
	s_waitcnt lgkmcnt(0)
	s_waitcnt lgkmcnt(0)
	v_mfma_f32_16x16x32_bf16 v[118:121], v[206:209], v[160:163], v[118:121]
	v_mfma_f32_16x16x32_bf16 v[114:117], v[218:221], v[160:163], v[114:117]
	v_mfma_f32_16x16x32_bf16 v[102:105], v[206:209], v[168:171], v[102:105]
	v_mfma_f32_16x16x32_bf16 v[98:101], v[218:221], v[168:171], v[98:101]
	v_mfma_f32_16x16x32_bf16 v[86:89], v[206:209], v[186:189], v[86:89]
	v_mfma_f32_16x16x32_bf16 v[82:85], v[218:221], v[186:189], v[82:85]
	v_mfma_f32_16x16x32_bf16 v[70:73], v[206:209], v[198:201], v[70:73]
	v_mfma_f32_16x16x32_bf16 v[66:69], v[218:221], v[198:201], v[66:69]
	v_mfma_f32_16x16x32_bf16 v[118:121], v[214:217], v[164:167], v[118:121]
	v_mfma_f32_16x16x32_bf16 v[114:117], v[222:225], v[164:167], v[114:117]
	v_mfma_f32_16x16x32_bf16 v[102:105], v[214:217], v[172:175], v[102:105]
	v_mfma_f32_16x16x32_bf16 v[98:101], v[222:225], v[172:175], v[98:101]
	v_mfma_f32_16x16x32_bf16 v[86:89], v[214:217], v[190:193], v[86:89]
	v_mfma_f32_16x16x32_bf16 v[82:85], v[222:225], v[190:193], v[82:85]
	v_mfma_f32_16x16x32_bf16 v[70:73], v[214:217], v[202:205], v[70:73]
	v_mfma_f32_16x16x32_bf16 v[66:69], v[222:225], v[202:205], v[66:69]
	s_mov_b32 m0, s36
	v_lshl_add_u64 v[144:145], v[180:181], 0, s[70:71]
	s_barrier
	ds_read_b128 v[160:163], v138 offset:49152
	ds_read_b128 v[164:167], v138 offset:50176
	ds_read_b128 v[168:171], v138 offset:51200
	ds_read_b128 v[172:175], v138 offset:52224
	ds_read_b128 v[186:189], v138 offset:53248
	ds_read_b128 v[190:193], v138 offset:54272
	ds_read_b128 v[198:201], v138 offset:55296
	ds_read_b128 v[202:205], v138 offset:56320
	global_load_lds_dwordx4 v[144:145], off
	v_lshl_add_u64 v[144:145], v[182:183], 0, s[70:71]
	s_mov_b32 m0, s37
	s_nop 0
	global_load_lds_dwordx4 v[144:145], off
	s_barrier
	s_waitcnt lgkmcnt(0)
	s_waitcnt lgkmcnt(0)
	v_mfma_f32_16x16x32_bf16 v[62:65], v[140:143], v[160:163], v[62:65]
	v_mfma_f32_16x16x32_bf16 v[58:61], v[152:155], v[160:163], v[58:61]
	v_mfma_f32_16x16x32_bf16 v[50:53], v[140:143], v[168:171], v[50:53]
	v_mfma_f32_16x16x32_bf16 v[42:45], v[152:155], v[168:171], v[42:45]
	v_mfma_f32_16x16x32_bf16 v[34:37], v[140:143], v[186:189], v[34:37]
	v_mfma_f32_16x16x32_bf16 v[26:29], v[152:155], v[186:189], v[26:29]
	v_mfma_f32_16x16x32_bf16 v[14:17], v[140:143], v[198:201], v[14:17]
	v_mfma_f32_16x16x32_bf16 v[10:13], v[152:155], v[198:201], v[10:13]
	v_mfma_f32_16x16x32_bf16 v[62:65], v[148:151], v[164:167], v[62:65]
	v_mfma_f32_16x16x32_bf16 v[58:61], v[156:159], v[164:167], v[58:61]
	v_mfma_f32_16x16x32_bf16 v[50:53], v[148:151], v[172:175], v[50:53]
	v_mfma_f32_16x16x32_bf16 v[42:45], v[156:159], v[172:175], v[42:45]
	v_mfma_f32_16x16x32_bf16 v[34:37], v[148:151], v[190:193], v[34:37]
	v_mfma_f32_16x16x32_bf16 v[26:29], v[156:159], v[190:193], v[26:29]
	v_mfma_f32_16x16x32_bf16 v[14:17], v[148:151], v[202:205], v[14:17]
	v_mfma_f32_16x16x32_bf16 v[10:13], v[156:159], v[202:205], v[10:13]
	s_barrier
	s_add_i32 s3, s18, s29
	v_lshl_add_u64 v[140:141], v[184:185], 0, s[70:71]
	s_mov_b32 m0, s3
	s_nop 0
	global_load_lds_dwordx4 v[140:141], off
	v_lshl_add_u64 v[140:141], v[226:227], 0, s[70:71]
	s_add_i32 m0, s3, 0x2000
	s_nop 0
	global_load_lds_dwordx4 v[140:141], off
	s_waitcnt vmcnt(6)
	s_barrier
	v_mfma_f32_16x16x32_bf16 v[54:57], v[206:209], v[160:163], v[54:57]
	v_mfma_f32_16x16x32_bf16 v[46:49], v[218:221], v[160:163], v[46:49]
	v_mfma_f32_16x16x32_bf16 v[38:41], v[206:209], v[168:171], v[38:41]
	v_mfma_f32_16x16x32_bf16 v[30:33], v[218:221], v[168:171], v[30:33]
	v_mfma_f32_16x16x32_bf16 v[22:25], v[206:209], v[186:189], v[22:25]
	v_mfma_f32_16x16x32_bf16 v[18:21], v[218:221], v[186:189], v[18:21]
	v_mfma_f32_16x16x32_bf16 v[6:9], v[206:209], v[198:201], v[6:9]
	v_mfma_f32_16x16x32_bf16 v[2:5], v[218:221], v[198:201], v[2:5]
	v_mfma_f32_16x16x32_bf16 v[54:57], v[214:217], v[164:167], v[54:57]
	v_mfma_f32_16x16x32_bf16 v[46:49], v[222:225], v[164:167], v[46:49]
	v_mfma_f32_16x16x32_bf16 v[38:41], v[214:217], v[172:175], v[38:41]
	v_mfma_f32_16x16x32_bf16 v[30:33], v[222:225], v[172:175], v[30:33]
	v_mfma_f32_16x16x32_bf16 v[22:25], v[214:217], v[190:193], v[22:25]
	v_mfma_f32_16x16x32_bf16 v[18:21], v[222:225], v[190:193], v[18:21]
	v_mfma_f32_16x16x32_bf16 v[6:9], v[214:217], v[202:205], v[6:9]
	v_mfma_f32_16x16x32_bf16 v[2:5], v[222:225], v[202:205], v[2:5]
	s_add_u32 s16, s16, 0x100
	s_addc_u32 s17, s17, 0
	s_cmp_ge_i32 s40, s38
	s_mov_b32 s3, s40
	s_barrier
	s_cbranch_scc0 .LBB0_217

; #define PG8_STAGE(bufoff, gbase, voff) do { _Pragma("unroll") for (int _i = 0; _i < 2; ++_i) \
;     __builtin_amdgcn_global_load_lds((const unsigned*)((const char*)(gbase) + (voff)[_i]), (LAS unsigned*)(lds + (bufoff) + ldsw + _i * 8192), 16, 0, 0); } while (0)
; #define PG8_LDA(dst, b, h) do { _Pragma("unroll") for (int m = 0; m < 4; ++m) _Pragma("unroll") for (int k = 0; k < 2; ++k) dst[m][k] = *(const LAS bf16x8*)(lds + PG8_SA(b, h) + aoff + m * 2048 + k * 1024); } while (0)
; #define PG8_LDB(dst, b, h) do { _Pragma("unroll") for (int n = 0; n < 2; ++n) _Pragma("unroll") for (int k = 0; k < 2; ++k) dst[n][k] = *(const LAS bf16x8*)(lds + PG8_SB(b, h) + boff + n * 2048 + k * 1024); } while (0)
; #define PG8_MMA(ai, bj, At, Bt) do { __builtin_amdgcn_s_setprio(1); _Pragma("unroll") for (int m = 0; m < 4; ++m) _Pragma("unroll") for (int n = 0; n < 2; ++n) _Pragma("unroll") for (int k = 0; k < 2; ++k) \
;     acc[ai][bj][m][n] = __builtin_amdgcn_mfma_f32_16x16x32_bf16(Bt[n][k], At[m][k], acc[ai][bj][m][n], 0, 0, 0); __builtin_amdgcn_s_setprio(0); } while (0)
; #define PG8_WAIT_L(n) asm volatile("s_waitcnt lgkmcnt(" #n ")" ::: "memory")
; #define PG8_BAR __builtin_amdgcn_s_barrier()
; #define PG8_SCHED __builtin_amdgcn_sched_barrier(0)
; template <class Epi, class Sched>
; DI void gemm_phase(LAS unsigned char* lds, const Gemm g, const Sched& S, const Epi& E) {
;     ...
;       PG8_LDB(B0, 0, 0); PG8_SCHED; PG8_LDA(At, 0, 0); PG8_STAGE(PG8_SA(1, 1), a1 + hstep, voffA);
;       PG8_WAIT_L(8); PG8_BAR; PG8_WAIT_L(0); PG8_MMA(0, 0, At, B0); PG8_BAR; PG8_SCHED;
;       PG8_LDB(B1, 0, 1); PG8_STAGE(PG8_SB(0, 0), b2, voffB);
;       PG8_BAR; PG8_WAIT_L(0); PG8_MMA(0, 1, At, B1); PG8_BAR;
;       PG8_LDA(At, 0, 1); PG8_STAGE(PG8_SA(0, 0), a2, voffA);
;       PG8_BAR; PG8_WAIT_L(0); PG8_MMA(1, 0, At, B0); PG8_BAR; PG8_SCHED;
.LBB0_491:
	s_add_i32 s26, s8, 2
	s_add_u32 s9, s6, 0xfe000080
	s_addc_u32 s10, s7, -1
	s_cmp_lg_u32 s25, s8
	s_cselect_b32 s11, s10, 0
	s_cselect_b32 s10, s9, 0
	s_add_u32 s8, s4, s10
	s_addc_u32 s9, s5, s11
	s_add_i32 s27, 16, 0x10000
	v_add_u32_e32 v139, s27, v133
	ds_read_b128 v[140:143], v139
	ds_read_b128 v[148:151], v139 offset:1024
	ds_read_b128 v[152:155], v139 offset:2048
	ds_read_b128 v[156:159], v139 offset:3072
	s_add_u32 s10, s2, s10
	s_addc_u32 s11, s3, s11
	v_lshl_add_u64 v[144:145], v[128:129], 0, s[6:7]
	s_add_i32 m0, s18, 0xc000
	ds_read_b128 v[160:163], v138
	ds_read_b128 v[164:167], v138 offset:1024
	ds_read_b128 v[168:171], v138 offset:2048
	ds_read_b128 v[172:175], v138 offset:3072
	ds_read_b128 v[186:189], v138 offset:4096
	ds_read_b128 v[190:193], v138 offset:5120
	ds_read_b128 v[198:201], v138 offset:6144
	ds_read_b128 v[202:205], v138 offset:7168
	global_load_lds_dwordx4 v[144:145], off
	v_lshl_add_u64 v[144:145], v[130:131], 0, s[6:7]
	s_add_i32 m0, s18, 0xe000
	s_nop 0
	global_load_lds_dwordx4 v[144:145], off
	s_waitcnt lgkmcnt(8)
	s_barrier
	s_waitcnt lgkmcnt(0)
	s_waitcnt lgkmcnt(0)
	v_mfma_f32_16x16x32_bf16 v[134:137], v[140:143], v[160:163], v[134:137]
	v_mfma_f32_16x16x32_bf16 v[122:125], v[152:155], v[160:163], v[122:125]
	v_mfma_f32_16x16x32_bf16 v[110:113], v[140:143], v[168:171], v[110:113]
	v_mfma_f32_16x16x32_bf16 v[106:109], v[152:155], v[168:171], v[106:109]
	v_mfma_f32_16x16x32_bf16 v[94:97], v[140:143], v[186:189], v[94:97]
	v_mfma_f32_16x16x32_bf16 v[90:93], v[152:155], v[186:189], v[90:93]
	v_mfma_f32_16x16x32_bf16 v[78:81], v[140:143], v[198:201], v[78:81]
	v_mfma_f32_16x16x32_bf16 v[74:77], v[152:155], v[198:201], v[74:77]
	v_mfma_f32_16x16x32_bf16 v[134:137], v[148:151], v[164:167], v[134:137]
	v_mfma_f32_16x16x32_bf16 v[122:125], v[156:159], v[164:167], v[122:125]
	v_mfma_f32_16x16x32_bf16 v[110:113], v[148:151], v[172:175], v[110:113]
	v_mfma_f32_16x16x32_bf16 v[106:109], v[156:159], v[172:175], v[106:109]
	v_mfma_f32_16x16x32_bf16 v[94:97], v[148:151], v[190:193], v[94:97]
	v_mfma_f32_16x16x32_bf16 v[90:93], v[156:159], v[190:193], v[90:93]
	v_mfma_f32_16x16x32_bf16 v[78:81], v[148:151], v[202:205], v[78:81]
	v_mfma_f32_16x16x32_bf16 v[74:77], v[156:159], v[202:205], v[74:77]
	s_barrier
	s_add_i32 s28, 16, 0x14000
	s_add_i32 s27, s27, s17
	v_add_u32_e32 v139, s28, v133
	v_lshl_add_u64 v[144:145], s[10:11], 0, v[0:1]
	s_mov_b32 m0, s27
	ds_read_b128 v[206:209], v139
	ds_read_b128 v[214:217], v139 offset:1024
	ds_read_b128 v[218:221], v139 offset:2048
	ds_read_b128 v[222:225], v139 offset:3072
	global_load_lds_dwordx4 v[144:145], off
	v_lshl_add_u64 v[176:177], s[10:11], 0, v[126:127]
	s_add_i32 m0, s27, 0x2000
	s_nop 0
	global_load_lds_dwordx4 v[176:177], off
	s_barrier
	s_waitcnt lgkmcnt(0)
	s_waitcnt lgkmcnt(0)
	v_mfma_f32_16x16x32_bf16 v[118:121], v[206:209], v[160:163], v[118:121]
	v_mfma_f32_16x16x32_bf16 v[114:117], v[218:221], v[160:163], v[114:117]
	v_mfma_f32_16x16x32_bf16 v[102:105], v[206:209], v[168:171], v[102:105]
	v_mfma_f32_16x16x32_bf16 v[98:101], v[218:221], v[168:171], v[98:101]
	v_mfma_f32_16x16x32_bf16 v[86:89], v[206:209], v[186:189], v[86:89]
	v_mfma_f32_16x16x32_bf16 v[82:85], v[218:221], v[186:189], v[82:85]
	v_mfma_f32_16x16x32_bf16 v[70:73], v[206:209], v[198:201], v[70:73]
	v_mfma_f32_16x16x32_bf16 v[66:69], v[218:221], v[198:201], v[66:69]
	v_mfma_f32_16x16x32_bf16 v[118:121], v[214:217], v[164:167], v[118:121]
	v_mfma_f32_16x16x32_bf16 v[114:117], v[222:225], v[164:167], v[114:117]
	v_mfma_f32_16x16x32_bf16 v[102:105], v[214:217], v[172:175], v[102:105]
	v_mfma_f32_16x16x32_bf16 v[98:101], v[222:225], v[172:175], v[98:101]
	v_mfma_f32_16x16x32_bf16 v[86:89], v[214:217], v[190:193], v[86:89]
	v_mfma_f32_16x16x32_bf16 v[82:85], v[222:225], v[190:193], v[82:85]
	v_mfma_f32_16x16x32_bf16 v[70:73], v[214:217], v[202:205], v[70:73]
	v_mfma_f32_16x16x32_bf16 v[66:69], v[222:225], v[202:205], v[66:69]
	s_mov_b32 m0, s18
	v_lshl_add_u64 v[180:181], s[8:9], 0, v[0:1]
	s_barrier
	ds_read_b128 v[160:163], v138 offset:16384
	ds_read_b128 v[164:167], v138 offset:17408
	ds_read_b128 v[168:171], v138 offset:18432
	ds_read_b128 v[172:175], v138 offset:19456
	ds_read_b128 v[186:189], v138 offset:20480
	ds_read_b128 v[190:193], v138 offset:21504
	ds_read_b128 v[198:201], v138 offset:22528
	ds_read_b128 v[202:205], v138 offset:23552
	global_load_lds_dwordx4 v[180:181], off
	v_lshl_add_u64 v[182:183], s[8:9], 0, v[126:127]
	s_mov_b32 m0, s19
	s_nop 0
	global_load_lds_dwordx4 v[182:183], off
	s_barrier
	s_waitcnt lgkmcnt(0)
	s_waitcnt lgkmcnt(0)
	v_mfma_f32_16x16x32_bf16 v[62:65], v[140:143], v[160:163], v[62:65]
	v_mfma_f32_16x16x32_bf16 v[58:61], v[152:155], v[160:163], v[58:61]
	v_mfma_f32_16x16x32_bf16 v[50:53], v[140:143], v[168:171], v[50:53]
	v_mfma_f32_16x16x32_bf16 v[42:45], v[152:155], v[168:171], v[42:45]
	v_mfma_f32_16x16x32_bf16 v[34:37], v[140:143], v[186:189], v[34:37]
	v_mfma_f32_16x16x32_bf16 v[26:29], v[152:155], v[186:189], v[26:29]
	v_mfma_f32_16x16x32_bf16 v[18:21], v[140:143], v[198:201], v[18:21]
	v_mfma_f32_16x16x32_bf16 v[10:13], v[152:155], v[198:201], v[10:13]
	v_mfma_f32_16x16x32_bf16 v[62:65], v[148:151], v[164:167], v[62:65]
	v_mfma_f32_16x16x32_bf16 v[58:61], v[156:159], v[164:167], v[58:61]
	v_mfma_f32_16x16x32_bf16 v[50:53], v[148:151], v[172:175], v[50:53]
	v_mfma_f32_16x16x32_bf16 v[42:45], v[156:159], v[172:175], v[42:45]
	v_mfma_f32_16x16x32_bf16 v[34:37], v[148:151], v[190:193], v[34:37]
	v_mfma_f32_16x16x32_bf16 v[26:29], v[156:159], v[190:193], v[26:29]
	v_mfma_f32_16x16x32_bf16 v[18:21], v[148:151], v[202:205], v[18:21]
	v_mfma_f32_16x16x32_bf16 v[10:13], v[156:159], v[202:205], v[10:13]
	s_barrier
; #define PG8_STAGE(bufoff, gbase, voff) do { _Pragma("unroll") for (int _i = 0; _i < 2; ++_i) \
;     __builtin_amdgcn_global_load_lds((const unsigned*)((const char*)(gbase) + (voff)[_i]), (LAS unsigned*)(lds + (bufoff) + ldsw + _i * 8192), 16, 0, 0); } while (0)
; #define PG8_LDA(dst, b, h) do { _Pragma("unroll") for (int m = 0; m < 4; ++m) _Pragma("unroll") for (int k = 0; k < 2; ++k) dst[m][k] = *(const LAS bf16x8*)(lds + PG8_SA(b, h) + aoff + m * 2048 + k * 1024); } while (0)
; #define PG8_LDB(dst, b, h) do { _Pragma("unroll") for (int n = 0; n < 2; ++n) _Pragma("unroll") for (int k = 0; k < 2; ++k) dst[n][k] = *(const LAS bf16x8*)(lds + PG8_SB(b, h) + boff + n * 2048 + k * 1024); } while (0)
; #define PG8_MMA(ai, bj, At, Bt) do { __builtin_amdgcn_s_setprio(1); _Pragma("unroll") for (int m = 0; m < 4; ++m) _Pragma("unroll") for (int n = 0; n < 2; ++n) _Pragma("unroll") for (int k = 0; k < 2; ++k) \
;     acc[ai][bj][m][n] = __builtin_amdgcn_mfma_f32_16x16x32_bf16(Bt[n][k], At[m][k], acc[ai][bj][m][n], 0, 0, 0); __builtin_amdgcn_s_setprio(0); } while (0)
; #define PG8_WAIT_V(n) asm volatile("s_waitcnt vmcnt(" #n ")" ::: "memory")
; #define PG8_WAIT_L(n) asm volatile("s_waitcnt lgkmcnt(" #n ")" ::: "memory")
; #define PG8_BAR __builtin_amdgcn_s_barrier()
; #define PG8_SCHED __builtin_amdgcn_sched_barrier(0)
; template <class Epi, class Sched>
; DI void gemm_phase(LAS unsigned char* lds, const Gemm g, const Sched& S, const Epi& E) {
;     ...
;       PG8_STAGE(PG8_SB(0, 1), b2 + hstepB, voffB);
;       PG8_WAIT_V(6); PG8_BAR; PG8_MMA(1, 1, At, B1); PG8_BAR;
;       PG8_LDB(B0, 1, 0); PG8_SCHED; PG8_LDA(At, 1, 0); PG8_STAGE(PG8_SA(0, 1), a2 + hstep, voffA);
;       PG8_WAIT_L(8); PG8_BAR; PG8_WAIT_L(0); PG8_MMA(0, 0, At, B0); PG8_BAR; PG8_SCHED;
;       PG8_LDB(B1, 1, 1); PG8_STAGE(PG8_SB(1, 0), b3, voffB);
;       PG8_BAR; PG8_WAIT_L(0); PG8_MMA(0, 1, At, B1); PG8_BAR;
	s_add_u32 s10, s10, s0
	s_addc_u32 s11, s11, s1
	s_add_i32 s27, s28, s17
	v_lshl_add_u64 v[184:185], s[10:11], 0, v[0:1]
	s_mov_b32 m0, s27
	v_lshl_add_u64 v[226:227], s[10:11], 0, v[126:127]
	global_load_lds_dwordx4 v[184:185], off
	s_add_i32 m0, s27, 0x2000
	s_nop 0
	global_load_lds_dwordx4 v[226:227], off
	s_waitcnt vmcnt(6)
	s_barrier
	v_mfma_f32_16x16x32_bf16 v[54:57], v[206:209], v[160:163], v[54:57]
	v_mfma_f32_16x16x32_bf16 v[46:49], v[218:221], v[160:163], v[46:49]
	v_mfma_f32_16x16x32_bf16 v[38:41], v[206:209], v[168:171], v[38:41]
	v_mfma_f32_16x16x32_bf16 v[30:33], v[218:221], v[168:171], v[30:33]
	v_mfma_f32_16x16x32_bf16 v[22:25], v[206:209], v[186:189], v[22:25]
	v_mfma_f32_16x16x32_bf16 v[14:17], v[218:221], v[186:189], v[14:17]
	v_mfma_f32_16x16x32_bf16 v[6:9], v[206:209], v[198:201], v[6:9]
	v_mfma_f32_16x16x32_bf16 v[2:5], v[218:221], v[198:201], v[2:5]
	v_mfma_f32_16x16x32_bf16 v[54:57], v[214:217], v[164:167], v[54:57]
	v_mfma_f32_16x16x32_bf16 v[46:49], v[222:225], v[164:167], v[46:49]
	v_mfma_f32_16x16x32_bf16 v[38:41], v[214:217], v[172:175], v[38:41]
	v_mfma_f32_16x16x32_bf16 v[30:33], v[222:225], v[172:175], v[30:33]
	v_mfma_f32_16x16x32_bf16 v[22:25], v[214:217], v[190:193], v[22:25]
	v_mfma_f32_16x16x32_bf16 v[14:17], v[222:225], v[190:193], v[14:17]
	v_mfma_f32_16x16x32_bf16 v[6:9], v[214:217], v[202:205], v[6:9]
	v_mfma_f32_16x16x32_bf16 v[2:5], v[222:225], v[202:205], v[2:5]
	s_add_i32 s10, 16, 0x18000
	v_add_u32_e32 v139, s10, v133
	s_barrier
	ds_read_b128 v[140:143], v139
	ds_read_b128 v[148:151], v139 offset:1024
	ds_read_b128 v[152:155], v139 offset:2048
	ds_read_b128 v[156:159], v139 offset:3072
	s_add_u32 s8, s8, s0
	s_addc_u32 s9, s9, s1
	s_mov_b32 m0, s20
	v_lshl_add_u64 v[206:207], s[8:9], 0, v[0:1]
	ds_read_b128 v[160:163], v138 offset:32768
	ds_read_b128 v[164:167], v138 offset:33792
	ds_read_b128 v[168:171], v138 offset:34816
	ds_read_b128 v[172:175], v138 offset:35840
	ds_read_b128 v[186:189], v138 offset:36864
	ds_read_b128 v[190:193], v138 offset:37888
	ds_read_b128 v[198:201], v138 offset:38912
	ds_read_b128 v[202:205], v138 offset:39936
	global_load_lds_dwordx4 v[206:207], off
	v_lshl_add_u64 v[206:207], s[8:9], 0, v[126:127]
	s_mov_b32 m0, s21
	s_nop 0
	global_load_lds_dwordx4 v[206:207], off
	s_waitcnt lgkmcnt(8)
	s_barrier
	s_waitcnt lgkmcnt(0)
	s_waitcnt lgkmcnt(0)
	v_mfma_f32_16x16x32_bf16 v[134:137], v[140:143], v[160:163], v[134:137]
	v_mfma_f32_16x16x32_bf16 v[122:125], v[152:155], v[160:163], v[122:125]
	v_mfma_f32_16x16x32_bf16 v[110:113], v[140:143], v[168:171], v[110:113]
	v_mfma_f32_16x16x32_bf16 v[106:109], v[152:155], v[168:171], v[106:109]
	v_mfma_f32_16x16x32_bf16 v[94:97], v[140:143], v[186:189], v[94:97]
	v_mfma_f32_16x16x32_bf16 v[90:93], v[152:155], v[186:189], v[90:93]
	v_mfma_f32_16x16x32_bf16 v[78:81], v[140:143], v[198:201], v[78:81]
	v_mfma_f32_16x16x32_bf16 v[74:77], v[152:155], v[198:201], v[74:77]
	v_mfma_f32_16x16x32_bf16 v[134:137], v[148:151], v[164:167], v[134:137]
	v_mfma_f32_16x16x32_bf16 v[122:125], v[156:159], v[164:167], v[122:125]
	v_mfma_f32_16x16x32_bf16 v[110:113], v[148:151], v[172:175], v[110:113]
	v_mfma_f32_16x16x32_bf16 v[106:109], v[156:159], v[172:175], v[106:109]
	v_mfma_f32_16x16x32_bf16 v[94:97], v[148:151], v[190:193], v[94:97]
	v_mfma_f32_16x16x32_bf16 v[90:93], v[156:159], v[190:193], v[90:93]
	v_mfma_f32_16x16x32_bf16 v[78:81], v[148:151], v[202:205], v[78:81]
	v_mfma_f32_16x16x32_bf16 v[74:77], v[156:159], v[202:205], v[74:77]
	s_barrier
	s_add_i32 s8, 16, 0x1c000
	s_add_i32 s9, s10, s17
	v_add_u32_e32 v139, s8, v133
	v_lshl_add_u64 v[144:145], v[144:145], 0, s[70:71]
	s_mov_b32 m0, s9
	ds_read_b128 v[206:209], v139
	ds_read_b128 v[214:217], v139 offset:1024
	ds_read_b128 v[218:221], v139 offset:2048
	ds_read_b128 v[222:225], v139 offset:3072
	global_load_lds_dwordx4 v[144:145], off
	v_lshl_add_u64 v[144:145], v[176:177], 0, s[70:71]
	s_add_i32 m0, s9, 0x2000
	s_nop 0
	global_load_lds_dwordx4 v[144:145], off
	s_barrier
; #define PG8_STAGE(bufoff, gbase, voff) do { _Pragma("unroll") for (int _i = 0; _i < 2; ++_i) \
;     __builtin_amdgcn_global_load_lds((const unsigned*)((const char*)(gbase) + (voff)[_i]), (LAS unsigned*)(lds + (bufoff) + ldsw + _i * 8192), 16, 0, 0); } while (0)
; #define PG8_LDA(dst, b, h) do { _Pragma("unroll") for (int m = 0; m < 4; ++m) _Pragma("unroll") for (int k = 0; k < 2; ++k) dst[m][k] = *(const LAS bf16x8*)(lds + PG8_SA(b, h) + aoff + m * 2048 + k * 1024); } while (0)
; #define PG8_MMA(ai, bj, At, Bt) do { __builtin_amdgcn_s_setprio(1); _Pragma("unroll") for (int m = 0; m < 4; ++m) _Pragma("unroll") for (int n = 0; n < 2; ++n) _Pragma("unroll") for (int k = 0; k < 2; ++k) \
;     acc[ai][bj][m][n] = __builtin_amdgcn_mfma_f32_16x16x32_bf16(Bt[n][k], At[m][k], acc[ai][bj][m][n], 0, 0, 0); __builtin_amdgcn_s_setprio(0); } while (0)
; #define PG8_WAIT_V(n) asm volatile("s_waitcnt vmcnt(" #n ")" ::: "memory")
; #define PG8_WAIT_L(n) asm volatile("s_waitcnt lgkmcnt(" #n ")" ::: "memory")
; #define PG8_BAR __builtin_amdgcn_s_barrier()
; #define PG8_SCHED __builtin_amdgcn_sched_barrier(0)
; template <class Epi, class Sched>
; DI void gemm_phase(LAS unsigned char* lds, const Gemm g, const Sched& S, const Epi& E) {
;     ...
;       PG8_BAR; PG8_WAIT_L(0); PG8_MMA(0, 1, At, B1); PG8_BAR;
;       PG8_LDA(At, 1, 1); PG8_STAGE(PG8_SA(1, 0), a3, voffA);
;       PG8_BAR; PG8_WAIT_L(0); PG8_MMA(1, 0, At, B0); PG8_BAR; PG8_SCHED;
;       PG8_STAGE(PG8_SB(1, 1), b3 + hstepB, voffB);
;       PG8_WAIT_V(6); PG8_BAR; PG8_MMA(1, 1, At, B1); PG8_BAR;
;     }
	s_waitcnt lgkmcnt(0)
	s_waitcnt lgkmcnt(0)
	v_mfma_f32_16x16x32_bf16 v[118:121], v[206:209], v[160:163], v[118:121]
	v_mfma_f32_16x16x32_bf16 v[114:117], v[218:221], v[160:163], v[114:117]
	v_mfma_f32_16x16x32_bf16 v[102:105], v[206:209], v[168:171], v[102:105]
	v_mfma_f32_16x16x32_bf16 v[98:101], v[218:221], v[168:171], v[98:101]
	v_mfma_f32_16x16x32_bf16 v[86:89], v[206:209], v[186:189], v[86:89]
	v_mfma_f32_16x16x32_bf16 v[82:85], v[218:221], v[186:189], v[82:85]
	v_mfma_f32_16x16x32_bf16 v[70:73], v[206:209], v[198:201], v[70:73]
	v_mfma_f32_16x16x32_bf16 v[66:69], v[218:221], v[198:201], v[66:69]
	v_mfma_f32_16x16x32_bf16 v[118:121], v[214:217], v[164:167], v[118:121]
	v_mfma_f32_16x16x32_bf16 v[114:117], v[222:225], v[164:167], v[114:117]
	v_mfma_f32_16x16x32_bf16 v[102:105], v[214:217], v[172:175], v[102:105]
	v_mfma_f32_16x16x32_bf16 v[98:101], v[222:225], v[172:175], v[98:101]
	v_mfma_f32_16x16x32_bf16 v[86:89], v[214:217], v[190:193], v[86:89]
	v_mfma_f32_16x16x32_bf16 v[82:85], v[222:225], v[190:193], v[82:85]
	v_mfma_f32_16x16x32_bf16 v[70:73], v[214:217], v[202:205], v[70:73]
	v_mfma_f32_16x16x32_bf16 v[66:69], v[222:225], v[202:205], v[66:69]
	s_mov_b32 m0, s22
	v_lshl_add_u64 v[144:145], v[180:181], 0, s[70:71]
	s_barrier
	ds_read_b128 v[160:163], v138 offset:49152
	ds_read_b128 v[164:167], v138 offset:50176
	ds_read_b128 v[168:171], v138 offset:51200
	ds_read_b128 v[172:175], v138 offset:52224
	ds_read_b128 v[186:189], v138 offset:53248
	ds_read_b128 v[190:193], v138 offset:54272
	ds_read_b128 v[198:201], v138 offset:55296
	ds_read_b128 v[202:205], v138 offset:56320
	global_load_lds_dwordx4 v[144:145], off
	v_lshl_add_u64 v[144:145], v[182:183], 0, s[70:71]
	s_mov_b32 m0, s23
	s_nop 0
	global_load_lds_dwordx4 v[144:145], off
	s_barrier
	s_waitcnt lgkmcnt(0)
	s_waitcnt lgkmcnt(0)
	v_mfma_f32_16x16x32_bf16 v[62:65], v[140:143], v[160:163], v[62:65]
	v_mfma_f32_16x16x32_bf16 v[58:61], v[152:155], v[160:163], v[58:61]
	v_mfma_f32_16x16x32_bf16 v[50:53], v[140:143], v[168:171], v[50:53]
	v_mfma_f32_16x16x32_bf16 v[42:45], v[152:155], v[168:171], v[42:45]
	v_mfma_f32_16x16x32_bf16 v[34:37], v[140:143], v[186:189], v[34:37]
	v_mfma_f32_16x16x32_bf16 v[26:29], v[152:155], v[186:189], v[26:29]
	v_mfma_f32_16x16x32_bf16 v[18:21], v[140:143], v[198:201], v[18:21]
	v_mfma_f32_16x16x32_bf16 v[10:13], v[152:155], v[198:201], v[10:13]
	v_mfma_f32_16x16x32_bf16 v[62:65], v[148:151], v[164:167], v[62:65]
	v_mfma_f32_16x16x32_bf16 v[58:61], v[156:159], v[164:167], v[58:61]
	v_mfma_f32_16x16x32_bf16 v[50:53], v[148:151], v[172:175], v[50:53]
	v_mfma_f32_16x16x32_bf16 v[42:45], v[156:159], v[172:175], v[42:45]
	v_mfma_f32_16x16x32_bf16 v[34:37], v[148:151], v[190:193], v[34:37]
	v_mfma_f32_16x16x32_bf16 v[26:29], v[156:159], v[190:193], v[26:29]
	v_mfma_f32_16x16x32_bf16 v[18:21], v[148:151], v[202:205], v[18:21]
	v_mfma_f32_16x16x32_bf16 v[10:13], v[156:159], v[202:205], v[10:13]
	s_barrier
	s_add_i32 s8, s8, s17
	v_lshl_add_u64 v[140:141], v[184:185], 0, s[70:71]
	s_mov_b32 m0, s8
	s_nop 0
	global_load_lds_dwordx4 v[140:141], off
	v_lshl_add_u64 v[140:141], v[226:227], 0, s[70:71]
	s_add_i32 m0, s8, 0x2000
	s_nop 0
	global_load_lds_dwordx4 v[140:141], off
	s_waitcnt vmcnt(6)
	s_barrier
	v_mfma_f32_16x16x32_bf16 v[54:57], v[206:209], v[160:163], v[54:57]
	v_mfma_f32_16x16x32_bf16 v[46:49], v[218:221], v[160:163], v[46:49]
	v_mfma_f32_16x16x32_bf16 v[38:41], v[206:209], v[168:171], v[38:41]
	v_mfma_f32_16x16x32_bf16 v[30:33], v[218:221], v[168:171], v[30:33]
	v_mfma_f32_16x16x32_bf16 v[22:25], v[206:209], v[186:189], v[22:25]
	v_mfma_f32_16x16x32_bf16 v[14:17], v[218:221], v[186:189], v[14:17]
	v_mfma_f32_16x16x32_bf16 v[6:9], v[206:209], v[198:201], v[6:9]
	v_mfma_f32_16x16x32_bf16 v[2:5], v[218:221], v[198:201], v[2:5]
	v_mfma_f32_16x16x32_bf16 v[54:57], v[214:217], v[164:167], v[54:57]
	v_mfma_f32_16x16x32_bf16 v[46:49], v[222:225], v[164:167], v[46:49]
	v_mfma_f32_16x16x32_bf16 v[38:41], v[214:217], v[172:175], v[38:41]
	v_mfma_f32_16x16x32_bf16 v[30:33], v[222:225], v[172:175], v[30:33]
	v_mfma_f32_16x16x32_bf16 v[22:25], v[214:217], v[190:193], v[22:25]
	v_mfma_f32_16x16x32_bf16 v[14:17], v[222:225], v[190:193], v[14:17]
	v_mfma_f32_16x16x32_bf16 v[6:9], v[214:217], v[202:205], v[6:9]
	v_mfma_f32_16x16x32_bf16 v[2:5], v[222:225], v[202:205], v[2:5]
	s_add_u32 s6, s6, 0x100
	s_addc_u32 s7, s7, 0
	s_cmp_ge_i32 s26, s24
	s_mov_b32 s8, s26
	s_barrier
	s_cbranch_scc0 .LBB0_491
	s_movk_i32 s27, 0xffd0
	s_movk_i32 s28, 0x2200

; #define PG8_STAGE(bufoff, gbase, voff) do { _Pragma("unroll") for (int _i = 0; _i < 2; ++_i) \
;     __builtin_amdgcn_global_load_lds((const unsigned*)((const char*)(gbase) + (voff)[_i]), (LAS unsigned*)(lds + (bufoff) + ldsw + _i * 8192), 16, 0, 0); } while (0)
; #define PG8_LDA(dst, b, h) do { _Pragma("unroll") for (int m = 0; m < 4; ++m) _Pragma("unroll") for (int k = 0; k < 2; ++k) dst[m][k] = *(const LAS bf16x8*)(lds + PG8_SA(b, h) + aoff + m * 2048 + k * 1024); } while (0)
; #define PG8_LDB(dst, b, h) do { _Pragma("unroll") for (int n = 0; n < 2; ++n) _Pragma("unroll") for (int k = 0; k < 2; ++k) dst[n][k] = *(const LAS bf16x8*)(lds + PG8_SB(b, h) + boff + n * 2048 + k * 1024); } while (0)
; #define PG8_MMA(ai, bj, At, Bt) do { __builtin_amdgcn_s_setprio(1); _Pragma("unroll") for (int m = 0; m < 4; ++m) _Pragma("unroll") for (int n = 0; n < 2; ++n) _Pragma("unroll") for (int k = 0; k < 2; ++k) \
;     acc[ai][bj][m][n] = __builtin_amdgcn_mfma_f32_16x16x32_bf16(Bt[n][k], At[m][k], acc[ai][bj][m][n], 0, 0, 0); __builtin_amdgcn_s_setprio(0); } while (0)
; #define PG8_WAIT_L(n) asm volatile("s_waitcnt lgkmcnt(" #n ")" ::: "memory")
; #define PG8_BAR __builtin_amdgcn_s_barrier()
; #define PG8_SCHED __builtin_amdgcn_sched_barrier(0)
; template <class Epi, class Sched>
; DI void gemm_phase(LAS unsigned char* lds, const Gemm g, const Sched& S, const Epi& E) {
;     ...
;       const bool last = (t == nt - 2);
;       const char* a1 = cA + (size_t)(t + 1) * kstep;
;       const char* a2 = last ? nA : cA + (size_t)(t + 2) * kstep; const char* b2 = last ? nB : cB + (size_t)(t + 2) * kstep;
;       const char* a3 = a2 + kstep; const char* b3 = b2 + kstep;
;       PG8_LDB(B0, 0, 0); PG8_SCHED; PG8_LDA(At, 0, 0); PG8_STAGE(PG8_SA(1, 1), a1 + hstep, voffA);
;       PG8_WAIT_L(8); PG8_BAR; PG8_WAIT_L(0); PG8_MMA(0, 0, At, B0); PG8_BAR; PG8_SCHED;
;       PG8_LDB(B1, 0, 1); PG8_STAGE(PG8_SB(0, 0), b2, voffB);
;       PG8_BAR; PG8_WAIT_L(0); PG8_MMA(0, 1, At, B1); PG8_BAR;
;       PG8_LDA(At, 0, 1); PG8_STAGE(PG8_SA(0, 0), a2, voffA);
;       PG8_BAR; PG8_WAIT_L(0); PG8_MMA(1, 0, At, B0); PG8_BAR; PG8_SCHED;
.LBB0_519:
	s_add_i32 s23, s6, 2
	s_add_u32 s8, s2, 0x80
	s_addc_u32 s7, s3, 0
	s_add_i32 s24, 16, 0x10000
	v_add_u32_e32 v0, s24, v215
	ds_read_b128 v[66:69], v0
	ds_read_b128 v[70:73], v0 offset:1024
	ds_read_b128 v[74:77], v0 offset:2048
	ds_read_b128 v[78:81], v0 offset:3072
	s_cmp_eq_u32 s41, s6
	s_cselect_b32 s6, s0, s8
	s_cselect_b32 s7, s1, s7
	s_cselect_b32 s9, s21, s22
	s_cselect_b32 s8, s20, s11
	v_lshl_add_u64 v[206:207], s[2:3], 0, v[202:203]
	s_add_i32 m0, s30, 0xc000
	ds_read_b128 v[82:85], v216
	ds_read_b128 v[86:89], v216 offset:1024
	ds_read_b128 v[94:97], v216 offset:2048
	ds_read_b128 v[98:101], v216 offset:3072
	ds_read_b128 v[114:117], v216 offset:4096
	ds_read_b128 v[118:121], v216 offset:5120
	ds_read_b128 v[122:125], v216 offset:6144
	ds_read_b128 v[126:129], v216 offset:7168
	global_load_lds_dwordx4 v[206:207], off
	v_lshl_add_u64 v[206:207], s[2:3], 0, v[204:205]
	s_add_i32 m0, s30, 0xe000
	s_nop 0
	global_load_lds_dwordx4 v[206:207], off
	s_waitcnt lgkmcnt(8)
	s_barrier
	s_waitcnt lgkmcnt(0)
	s_waitcnt lgkmcnt(0)
	v_mfma_f32_16x16x32_bf16 v[174:177], v[66:69], v[82:85], v[174:177]
	v_mfma_f32_16x16x32_bf16 v[170:173], v[74:77], v[82:85], v[170:173]
	v_mfma_f32_16x16x32_bf16 v[158:161], v[66:69], v[94:97], v[158:161]
	v_mfma_f32_16x16x32_bf16 v[154:157], v[74:77], v[94:97], v[154:157]
	v_mfma_f32_16x16x32_bf16 v[142:145], v[66:69], v[114:117], v[142:145]
	v_mfma_f32_16x16x32_bf16 v[138:141], v[74:77], v[114:117], v[138:141]
	v_mfma_f32_16x16x32_bf16 v[110:113], v[66:69], v[122:125], v[110:113]
	v_mfma_f32_16x16x32_bf16 v[106:109], v[74:77], v[122:125], v[106:109]
	v_mfma_f32_16x16x32_bf16 v[174:177], v[70:73], v[86:89], v[174:177]
	v_mfma_f32_16x16x32_bf16 v[170:173], v[78:81], v[86:89], v[170:173]
	v_mfma_f32_16x16x32_bf16 v[158:161], v[70:73], v[98:101], v[158:161]
	v_mfma_f32_16x16x32_bf16 v[154:157], v[78:81], v[98:101], v[154:157]
	v_mfma_f32_16x16x32_bf16 v[142:145], v[70:73], v[118:121], v[142:145]
	v_mfma_f32_16x16x32_bf16 v[138:141], v[78:81], v[118:121], v[138:141]
	v_mfma_f32_16x16x32_bf16 v[110:113], v[70:73], v[126:129], v[110:113]
	v_mfma_f32_16x16x32_bf16 v[106:109], v[78:81], v[126:129], v[106:109]
	s_barrier
	s_add_i32 s25, 16, 0x14000
	s_add_i32 s24, s24, s29
	v_add_u32_e32 v0, s25, v215
	v_lshl_add_u64 v[246:247], s[8:9], 0, v[190:191]
	s_mov_b32 m0, s24
	ds_read_b128 v[206:209], v0
	ds_read_b128 v[218:221], v0 offset:1024
	ds_read_b128 v[222:225], v0 offset:2048
	ds_read_b128 v[226:229], v0 offset:3072
	global_load_lds_dwordx4 v[246:247], off
	v_lshl_add_u64 v[248:249], s[8:9], 0, v[186:187]
	s_add_i32 m0, s24, 0x2000
	s_nop 0
	global_load_lds_dwordx4 v[248:249], off
	s_barrier
	s_waitcnt lgkmcnt(0)
	s_waitcnt lgkmcnt(0)
	v_mfma_f32_16x16x32_bf16 v[166:169], v[206:209], v[82:85], v[166:169]
	v_mfma_f32_16x16x32_bf16 v[82:85], v[222:225], v[82:85], v[162:165]
	v_mfma_f32_16x16x32_bf16 v[166:169], v[218:221], v[86:89], v[166:169]
	v_mfma_f32_16x16x32_bf16 v[82:85], v[226:229], v[86:89], v[82:85]
	v_mfma_f32_16x16x32_bf16 v[86:89], v[206:209], v[94:97], v[150:153]
	v_mfma_f32_16x16x32_bf16 v[94:97], v[222:225], v[94:97], v[146:149]
	v_mfma_f32_16x16x32_bf16 v[102:105], v[206:209], v[122:125], v[102:105]
	v_mfma_f32_16x16x32_bf16 v[90:93], v[222:225], v[122:125], v[90:93]
	v_mfma_f32_16x16x32_bf16 v[86:89], v[218:221], v[98:101], v[86:89]
	v_mfma_f32_16x16x32_bf16 v[94:97], v[226:229], v[98:101], v[94:97]
	v_mfma_f32_16x16x32_bf16 v[98:101], v[206:209], v[114:117], v[134:137]
	v_mfma_f32_16x16x32_bf16 v[114:117], v[222:225], v[114:117], v[130:133]
	v_mfma_f32_16x16x32_bf16 v[102:105], v[218:221], v[126:129], v[102:105]
	v_mfma_f32_16x16x32_bf16 v[90:93], v[226:229], v[126:129], v[90:93]
	v_mfma_f32_16x16x32_bf16 v[98:101], v[218:221], v[118:121], v[98:101]
	v_mfma_f32_16x16x32_bf16 v[114:117], v[226:229], v[118:121], v[114:117]
	s_mov_b32 m0, s30
	v_lshl_add_u64 v[250:251], s[6:7], 0, v[192:193]
	s_barrier
	ds_read_b128 v[118:121], v216 offset:16384
	ds_read_b128 v[122:125], v216 offset:17408
	ds_read_b128 v[126:129], v216 offset:18432
	ds_read_b128 v[130:133], v216 offset:19456
	ds_read_b128 v[134:137], v216 offset:20480
	ds_read_b128 v[146:149], v216 offset:21504
	ds_read_b128 v[150:153], v216 offset:22528
	ds_read_b128 v[162:165], v216 offset:23552
	global_load_lds_dwordx4 v[250:251], off
	v_lshl_add_u64 v[180:181], s[6:7], 0, v[188:189]
	s_mov_b32 m0, s31
	s_nop 0
	global_load_lds_dwordx4 v[180:181], off
	s_barrier
	s_waitcnt lgkmcnt(0)
	s_waitcnt lgkmcnt(0)
	v_mfma_f32_16x16x32_bf16 v[62:65], v[66:69], v[118:121], v[62:65]
	v_mfma_f32_16x16x32_bf16 v[58:61], v[74:77], v[118:121], v[58:61]
	v_mfma_f32_16x16x32_bf16 v[46:49], v[66:69], v[126:129], v[46:49]
	v_mfma_f32_16x16x32_bf16 v[42:45], v[74:77], v[126:129], v[42:45]
	v_mfma_f32_16x16x32_bf16 v[30:33], v[66:69], v[134:137], v[30:33]
	v_mfma_f32_16x16x32_bf16 v[26:29], v[74:77], v[134:137], v[26:29]
	v_mfma_f32_16x16x32_bf16 v[14:17], v[66:69], v[150:153], v[14:17]
	v_mfma_f32_16x16x32_bf16 v[10:13], v[74:77], v[150:153], v[10:13]
	v_mfma_f32_16x16x32_bf16 v[62:65], v[70:73], v[122:125], v[62:65]
	v_mfma_f32_16x16x32_bf16 v[58:61], v[78:81], v[122:125], v[58:61]
	v_mfma_f32_16x16x32_bf16 v[46:49], v[70:73], v[130:133], v[46:49]
	v_mfma_f32_16x16x32_bf16 v[42:45], v[78:81], v[130:133], v[42:45]
	v_mfma_f32_16x16x32_bf16 v[30:33], v[70:73], v[146:149], v[30:33]
	v_mfma_f32_16x16x32_bf16 v[26:29], v[78:81], v[146:149], v[26:29]
	v_mfma_f32_16x16x32_bf16 v[14:17], v[70:73], v[162:165], v[14:17]
	v_mfma_f32_16x16x32_bf16 v[10:13], v[78:81], v[162:165], v[10:13]
	s_barrier
; #define PG8_STAGE(bufoff, gbase, voff) do { _Pragma("unroll") for (int _i = 0; _i < 2; ++_i) \
;     __builtin_amdgcn_global_load_lds((const unsigned*)((const char*)(gbase) + (voff)[_i]), (LAS unsigned*)(lds + (bufoff) + ldsw + _i * 8192), 16, 0, 0); } while (0)
; #define PG8_LDA(dst, b, h) do { _Pragma("unroll") for (int m = 0; m < 4; ++m) _Pragma("unroll") for (int k = 0; k < 2; ++k) dst[m][k] = *(const LAS bf16x8*)(lds + PG8_SA(b, h) + aoff + m * 2048 + k * 1024); } while (0)
; #define PG8_LDB(dst, b, h) do { _Pragma("unroll") for (int n = 0; n < 2; ++n) _Pragma("unroll") for (int k = 0; k < 2; ++k) dst[n][k] = *(const LAS bf16x8*)(lds + PG8_SB(b, h) + boff + n * 2048 + k * 1024); } while (0)
; #define PG8_MMA(ai, bj, At, Bt) do { __builtin_amdgcn_s_setprio(1); _Pragma("unroll") for (int m = 0; m < 4; ++m) _Pragma("unroll") for (int n = 0; n < 2; ++n) _Pragma("unroll") for (int k = 0; k < 2; ++k) \
;     acc[ai][bj][m][n] = __builtin_amdgcn_mfma_f32_16x16x32_bf16(Bt[n][k], At[m][k], acc[ai][bj][m][n], 0, 0, 0); __builtin_amdgcn_s_setprio(0); } while (0)
; #define PG8_WAIT_V(n) asm volatile("s_waitcnt vmcnt(" #n ")" ::: "memory")
; #define PG8_WAIT_L(n) asm volatile("s_waitcnt lgkmcnt(" #n ")" ::: "memory")
; #define PG8_BAR __builtin_amdgcn_s_barrier()
; #define PG8_SCHED __builtin_amdgcn_sched_barrier(0)
; template <class Epi, class Sched>
; DI void gemm_phase(LAS unsigned char* lds, const Gemm g, const Sched& S, const Epi& E) {
;     ...
;       PG8_STAGE(PG8_SB(0, 1), b2 + hstepB, voffB);
;       PG8_WAIT_V(6); PG8_BAR; PG8_MMA(1, 1, At, B1); PG8_BAR;
;       PG8_LDB(B0, 1, 0); PG8_SCHED; PG8_LDA(At, 1, 0); PG8_STAGE(PG8_SA(0, 1), a2 + hstep, voffA);
;       PG8_WAIT_L(8); PG8_BAR; PG8_WAIT_L(0); PG8_MMA(0, 0, At, B0); PG8_BAR; PG8_SCHED;
;       PG8_LDB(B1, 1, 1); PG8_STAGE(PG8_SB(1, 0), b3, voffB);
;       PG8_BAR; PG8_WAIT_L(0); PG8_MMA(0, 1, At, B1); PG8_BAR;
	s_add_u32 s8, s8, s14
	s_addc_u32 s9, s9, s15
	s_add_i32 s24, s25, s29
	v_lshl_add_u64 v[182:183], s[8:9], 0, v[190:191]
	s_mov_b32 m0, s24
	v_lshl_add_u64 v[184:185], s[8:9], 0, v[186:187]
	global_load_lds_dwordx4 v[182:183], off
	s_add_i32 m0, s24, 0x2000
	s_nop 0
	global_load_lds_dwordx4 v[184:185], off
	s_waitcnt vmcnt(6)
	s_barrier
	v_mfma_f32_16x16x32_bf16 v[54:57], v[206:209], v[118:121], v[54:57]
	v_mfma_f32_16x16x32_bf16 v[50:53], v[222:225], v[118:121], v[50:53]
	v_mfma_f32_16x16x32_bf16 v[38:41], v[206:209], v[126:129], v[38:41]
	v_mfma_f32_16x16x32_bf16 v[34:37], v[222:225], v[126:129], v[34:37]
	v_mfma_f32_16x16x32_bf16 v[22:25], v[206:209], v[134:137], v[22:25]
	v_mfma_f32_16x16x32_bf16 v[18:21], v[222:225], v[134:137], v[18:21]
	v_mfma_f32_16x16x32_bf16 v[6:9], v[206:209], v[150:153], v[6:9]
	v_mfma_f32_16x16x32_bf16 v[2:5], v[222:225], v[150:153], v[2:5]
	v_mfma_f32_16x16x32_bf16 v[54:57], v[218:221], v[122:125], v[54:57]
	v_mfma_f32_16x16x32_bf16 v[50:53], v[226:229], v[122:125], v[50:53]
	v_mfma_f32_16x16x32_bf16 v[38:41], v[218:221], v[130:133], v[38:41]
	v_mfma_f32_16x16x32_bf16 v[34:37], v[226:229], v[130:133], v[34:37]
	v_mfma_f32_16x16x32_bf16 v[22:25], v[218:221], v[146:149], v[22:25]
	v_mfma_f32_16x16x32_bf16 v[18:21], v[226:229], v[146:149], v[18:21]
	v_mfma_f32_16x16x32_bf16 v[6:9], v[218:221], v[162:165], v[6:9]
	v_mfma_f32_16x16x32_bf16 v[2:5], v[226:229], v[162:165], v[2:5]
	s_add_i32 s8, 16, 0x18000
	v_add_u32_e32 v0, s8, v215
	s_barrier
	ds_read_b128 v[66:69], v0
	ds_read_b128 v[70:73], v0 offset:1024
	ds_read_b128 v[74:77], v0 offset:2048
	ds_read_b128 v[78:81], v0 offset:3072
	s_add_u32 s6, s6, s12
	s_addc_u32 s7, s7, s13
	s_mov_b32 m0, s34
	v_lshl_add_u64 v[134:135], s[6:7], 0, v[192:193]
	ds_read_b128 v[118:121], v216 offset:32768
	ds_read_b128 v[122:125], v216 offset:33792
	ds_read_b128 v[126:129], v216 offset:34816
	ds_read_b128 v[130:133], v216 offset:35840
	ds_read_b128 v[206:209], v216 offset:36864
	ds_read_b128 v[218:221], v216 offset:37888
	ds_read_b128 v[222:225], v216 offset:38912
	ds_read_b128 v[226:229], v216 offset:39936
	global_load_lds_dwordx4 v[134:135], off
	v_lshl_add_u64 v[134:135], s[6:7], 0, v[188:189]
	s_mov_b32 m0, s35
	s_nop 0
	global_load_lds_dwordx4 v[134:135], off
	s_waitcnt lgkmcnt(8)
	s_barrier
	s_waitcnt lgkmcnt(0)
	s_waitcnt lgkmcnt(0)
	v_mfma_f32_16x16x32_bf16 v[134:137], v[66:69], v[118:121], v[174:177]
	v_mfma_f32_16x16x32_bf16 v[174:177], v[70:73], v[122:125], v[134:137]
	v_mfma_f32_16x16x32_bf16 v[134:137], v[74:77], v[118:121], v[170:173]
	v_mfma_f32_16x16x32_bf16 v[170:173], v[78:81], v[122:125], v[134:137]
	v_mfma_f32_16x16x32_bf16 v[134:137], v[66:69], v[126:129], v[158:161]
	v_mfma_f32_16x16x32_bf16 v[158:161], v[70:73], v[130:133], v[134:137]
	v_mfma_f32_16x16x32_bf16 v[134:137], v[74:77], v[126:129], v[154:157]
	v_mfma_f32_16x16x32_bf16 v[154:157], v[78:81], v[130:133], v[134:137]
	v_mfma_f32_16x16x32_bf16 v[134:137], v[66:69], v[206:209], v[142:145]
	v_mfma_f32_16x16x32_bf16 v[142:145], v[70:73], v[218:221], v[134:137]
	v_mfma_f32_16x16x32_bf16 v[134:137], v[74:77], v[206:209], v[138:141]
	v_mfma_f32_16x16x32_bf16 v[110:113], v[66:69], v[222:225], v[110:113]
	v_mfma_f32_16x16x32_bf16 v[106:109], v[74:77], v[222:225], v[106:109]
	v_mfma_f32_16x16x32_bf16 v[138:141], v[78:81], v[218:221], v[134:137]
	v_mfma_f32_16x16x32_bf16 v[110:113], v[70:73], v[226:229], v[110:113]
	v_mfma_f32_16x16x32_bf16 v[106:109], v[78:81], v[226:229], v[106:109]
	s_barrier
	s_add_i32 s6, 16, 0x1c000
	s_add_i32 s7, s8, s29
	v_add_u32_e32 v0, s6, v215
	v_lshl_add_u64 v[134:135], v[246:247], 0, s[70:71]
	s_mov_b32 m0, s7
	ds_read_b128 v[230:233], v0
	ds_read_b128 v[234:237], v0 offset:1024
	ds_read_b128 v[238:241], v0 offset:2048
	ds_read_b128 v[242:245], v0 offset:3072
	global_load_lds_dwordx4 v[134:135], off
	v_lshl_add_u64 v[134:135], v[248:249], 0, s[70:71]
	s_add_i32 m0, s7, 0x2000
	s_nop 0
	global_load_lds_dwordx4 v[134:135], off
	s_barrier
; #define PG8_STAGE(bufoff, gbase, voff) do { _Pragma("unroll") for (int _i = 0; _i < 2; ++_i) \
;     __builtin_amdgcn_global_load_lds((const unsigned*)((const char*)(gbase) + (voff)[_i]), (LAS unsigned*)(lds + (bufoff) + ldsw + _i * 8192), 16, 0, 0); } while (0)
; #define PG8_LDA(dst, b, h) do { _Pragma("unroll") for (int m = 0; m < 4; ++m) _Pragma("unroll") for (int k = 0; k < 2; ++k) dst[m][k] = *(const LAS bf16x8*)(lds + PG8_SA(b, h) + aoff + m * 2048 + k * 1024); } while (0)
; #define PG8_MMA(ai, bj, At, Bt) do { __builtin_amdgcn_s_setprio(1); _Pragma("unroll") for (int m = 0; m < 4; ++m) _Pragma("unroll") for (int n = 0; n < 2; ++n) _Pragma("unroll") for (int k = 0; k < 2; ++k) \
;     acc[ai][bj][m][n] = __builtin_amdgcn_mfma_f32_16x16x32_bf16(Bt[n][k], At[m][k], acc[ai][bj][m][n], 0, 0, 0); __builtin_amdgcn_s_setprio(0); } while (0)
; #define PG8_WAIT_V(n) asm volatile("s_waitcnt vmcnt(" #n ")" ::: "memory")
; #define PG8_WAIT_L(n) asm volatile("s_waitcnt lgkmcnt(" #n ")" ::: "memory")
; #define PG8_BAR __builtin_amdgcn_s_barrier()
; #define PG8_SCHED __builtin_amdgcn_sched_barrier(0)
; template <class Epi, class Sched>
; DI void gemm_phase(LAS unsigned char* lds, const Gemm g, const Sched& S, const Epi& E) {
;     ...
;       PG8_BAR; PG8_WAIT_L(0); PG8_MMA(0, 1, At, B1); PG8_BAR;
;       PG8_LDA(At, 1, 1); PG8_STAGE(PG8_SA(1, 0), a3, voffA);
;       PG8_BAR; PG8_WAIT_L(0); PG8_MMA(1, 0, At, B0); PG8_BAR; PG8_SCHED;
;       PG8_STAGE(PG8_SB(1, 1), b3 + hstepB, voffB);
;       PG8_WAIT_V(6); PG8_BAR; PG8_MMA(1, 1, At, B1); PG8_BAR;
;     }
	s_waitcnt lgkmcnt(0)
	s_waitcnt lgkmcnt(0)
	v_mfma_f32_16x16x32_bf16 v[82:85], v[238:241], v[118:121], v[82:85]
	v_mfma_f32_16x16x32_bf16 v[162:165], v[242:245], v[122:125], v[82:85]
	v_mfma_f32_16x16x32_bf16 v[82:85], v[230:233], v[126:129], v[86:89]
	v_mfma_f32_16x16x32_bf16 v[150:153], v[234:237], v[130:133], v[82:85]
	v_mfma_f32_16x16x32_bf16 v[82:85], v[238:241], v[126:129], v[94:97]
	v_mfma_f32_16x16x32_bf16 v[134:137], v[230:233], v[118:121], v[166:169]
	v_mfma_f32_16x16x32_bf16 v[146:149], v[242:245], v[130:133], v[82:85]
	v_mfma_f32_16x16x32_bf16 v[82:85], v[230:233], v[206:209], v[98:101]
	v_mfma_f32_16x16x32_bf16 v[166:169], v[234:237], v[122:125], v[134:137]
	v_mfma_f32_16x16x32_bf16 v[134:137], v[234:237], v[218:221], v[82:85]
	v_mfma_f32_16x16x32_bf16 v[82:85], v[238:241], v[206:209], v[114:117]
	v_mfma_f32_16x16x32_bf16 v[130:133], v[242:245], v[218:221], v[82:85]
	v_mfma_f32_16x16x32_bf16 v[82:85], v[230:233], v[222:225], v[102:105]
	v_mfma_f32_16x16x32_bf16 v[102:105], v[234:237], v[226:229], v[82:85]
	v_mfma_f32_16x16x32_bf16 v[82:85], v[238:241], v[222:225], v[90:93]
	v_mfma_f32_16x16x32_bf16 v[90:93], v[242:245], v[226:229], v[82:85]
	s_mov_b32 m0, s36
	v_lshl_add_u64 v[206:207], v[250:251], 0, s[70:71]
	s_barrier
	s_nop 2
	ds_read_b128 v[82:85], v216 offset:49152
	ds_read_b128 v[86:89], v216 offset:50176
	ds_read_b128 v[94:97], v216 offset:51200
	ds_read_b128 v[98:101], v216 offset:52224
	ds_read_b128 v[114:117], v216 offset:53248
	ds_read_b128 v[118:121], v216 offset:54272
	ds_read_b128 v[122:125], v216 offset:55296
	ds_read_b128 v[126:129], v216 offset:56320
	global_load_lds_dwordx4 v[206:207], off
	v_lshl_add_u64 v[180:181], v[180:181], 0, s[70:71]
	s_mov_b32 m0, s37
	s_nop 0
	global_load_lds_dwordx4 v[180:181], off
	s_barrier
	s_waitcnt lgkmcnt(0)
	s_waitcnt lgkmcnt(0)
	v_mfma_f32_16x16x32_bf16 v[62:65], v[66:69], v[82:85], v[62:65]
	v_mfma_f32_16x16x32_bf16 v[58:61], v[74:77], v[82:85], v[58:61]
	v_mfma_f32_16x16x32_bf16 v[46:49], v[66:69], v[94:97], v[46:49]
	v_mfma_f32_16x16x32_bf16 v[42:45], v[74:77], v[94:97], v[42:45]
	v_mfma_f32_16x16x32_bf16 v[30:33], v[66:69], v[114:117], v[30:33]
	v_mfma_f32_16x16x32_bf16 v[26:29], v[74:77], v[114:117], v[26:29]
	v_mfma_f32_16x16x32_bf16 v[14:17], v[66:69], v[122:125], v[14:17]
	v_mfma_f32_16x16x32_bf16 v[10:13], v[74:77], v[122:125], v[10:13]
	v_mfma_f32_16x16x32_bf16 v[62:65], v[70:73], v[86:89], v[62:65]
	v_mfma_f32_16x16x32_bf16 v[58:61], v[78:81], v[86:89], v[58:61]
	v_mfma_f32_16x16x32_bf16 v[46:49], v[70:73], v[98:101], v[46:49]
	v_mfma_f32_16x16x32_bf16 v[42:45], v[78:81], v[98:101], v[42:45]
	v_mfma_f32_16x16x32_bf16 v[30:33], v[70:73], v[118:121], v[30:33]
	v_mfma_f32_16x16x32_bf16 v[26:29], v[78:81], v[118:121], v[26:29]
	v_mfma_f32_16x16x32_bf16 v[14:17], v[70:73], v[126:129], v[14:17]
	v_mfma_f32_16x16x32_bf16 v[10:13], v[78:81], v[126:129], v[10:13]
	s_barrier
	s_add_i32 s6, s6, s29
	v_lshl_add_u64 v[66:67], v[182:183], 0, s[70:71]
	s_mov_b32 m0, s6
	s_nop 0
	global_load_lds_dwordx4 v[66:67], off
	v_lshl_add_u64 v[66:67], v[184:185], 0, s[70:71]
	s_add_i32 m0, s6, 0x2000
	s_nop 0
	global_load_lds_dwordx4 v[66:67], off
	s_waitcnt vmcnt(6)
	s_barrier
	v_mfma_f32_16x16x32_bf16 v[54:57], v[230:233], v[82:85], v[54:57]
	v_mfma_f32_16x16x32_bf16 v[50:53], v[238:241], v[82:85], v[50:53]
	v_mfma_f32_16x16x32_bf16 v[38:41], v[230:233], v[94:97], v[38:41]
	v_mfma_f32_16x16x32_bf16 v[34:37], v[238:241], v[94:97], v[34:37]
	v_mfma_f32_16x16x32_bf16 v[22:25], v[230:233], v[114:117], v[22:25]
	v_mfma_f32_16x16x32_bf16 v[18:21], v[238:241], v[114:117], v[18:21]
	v_mfma_f32_16x16x32_bf16 v[6:9], v[230:233], v[122:125], v[6:9]
	v_mfma_f32_16x16x32_bf16 v[2:5], v[238:241], v[122:125], v[2:5]
	v_mfma_f32_16x16x32_bf16 v[54:57], v[234:237], v[86:89], v[54:57]
	v_mfma_f32_16x16x32_bf16 v[50:53], v[242:245], v[86:89], v[50:53]
	v_mfma_f32_16x16x32_bf16 v[38:41], v[234:237], v[98:101], v[38:41]
	v_mfma_f32_16x16x32_bf16 v[34:37], v[242:245], v[98:101], v[34:37]
	v_mfma_f32_16x16x32_bf16 v[22:25], v[234:237], v[118:121], v[22:25]
	v_mfma_f32_16x16x32_bf16 v[18:21], v[242:245], v[118:121], v[18:21]
	v_mfma_f32_16x16x32_bf16 v[6:9], v[234:237], v[126:129], v[6:9]
	v_mfma_f32_16x16x32_bf16 v[2:5], v[242:245], v[126:129], v[2:5]
	s_add_u32 s2, s2, 0x100
	s_addc_u32 s3, s3, 0
	s_add_u32 s11, s11, 0x100
	s_addc_u32 s22, s22, 0
	s_cmp_ge_i32 s23, s39
	s_mov_b32 s6, s23
	s_barrier
	s_cbranch_scc0 .LBB0_519
	v_mov_b64_e32 v[244:245], v[178:179]
	v_mov_b64_e32 v[178:179], 0xff
	v_mov_b64_e32 v[246:247], 0x1ff
	v_mov_b32_e32 v195, v217
	v_mov_b32_e32 v248, v210
	v_mov_b32_e32 v210, v201
	v_mov_b32_e32 v184, v200

; #define PG8_STAGE(bufoff, gbase, voff) do { _Pragma("unroll") for (int _i = 0; _i < 2; ++_i) \
;     __builtin_amdgcn_global_load_lds((const unsigned*)((const char*)(gbase) + (voff)[_i]), (LAS unsigned*)(lds + (bufoff) + ldsw + _i * 8192), 16, 0, 0); } while (0)
; #define PG8_LDA(dst, b, h) do { _Pragma("unroll") for (int m = 0; m < 4; ++m) _Pragma("unroll") for (int k = 0; k < 2; ++k) dst[m][k] = *(const LAS bf16x8*)(lds + PG8_SA(b, h) + aoff + m * 2048 + k * 1024); } while (0)
; #define PG8_LDB(dst, b, h) do { _Pragma("unroll") for (int n = 0; n < 2; ++n) _Pragma("unroll") for (int k = 0; k < 2; ++k) dst[n][k] = *(const LAS bf16x8*)(lds + PG8_SB(b, h) + boff + n * 2048 + k * 1024); } while (0)
; #define PG8_MMA(ai, bj, At, Bt) do { __builtin_amdgcn_s_setprio(1); _Pragma("unroll") for (int m = 0; m < 4; ++m) _Pragma("unroll") for (int n = 0; n < 2; ++n) _Pragma("unroll") for (int k = 0; k < 2; ++k) \
;     acc[ai][bj][m][n] = __builtin_amdgcn_mfma_f32_16x16x32_bf16(Bt[n][k], At[m][k], acc[ai][bj][m][n], 0, 0, 0); __builtin_amdgcn_s_setprio(0); } while (0)
; #define PG8_WAIT_L(n) asm volatile("s_waitcnt lgkmcnt(" #n ")" ::: "memory")
; #define PG8_BAR __builtin_amdgcn_s_barrier()
; #define PG8_SCHED __builtin_amdgcn_sched_barrier(0)
; template <class Epi, class Sched>
; DI void gemm_phase(LAS unsigned char* lds, const Gemm g, const Sched& S, const Epi& E) {
;     ...
;       const bool last = (t == nt - 2);
;       const char* a1 = cA + (size_t)(t + 1) * kstep;
;       const char* a2 = last ? nA : cA + (size_t)(t + 2) * kstep; const char* b2 = last ? nB : cB + (size_t)(t + 2) * kstep;
;       const char* a3 = a2 + kstep; const char* b3 = b2 + kstep;
;       PG8_LDB(B0, 0, 0); PG8_SCHED; PG8_LDA(At, 0, 0); PG8_STAGE(PG8_SA(1, 1), a1 + hstep, voffA);
;       PG8_WAIT_L(8); PG8_BAR; PG8_WAIT_L(0); PG8_MMA(0, 0, At, B0); PG8_BAR; PG8_SCHED;
;       PG8_LDB(B1, 0, 1); PG8_STAGE(PG8_SB(0, 0), b2, voffB);
;       PG8_BAR; PG8_WAIT_L(0); PG8_MMA(0, 1, At, B1); PG8_BAR;
;       PG8_LDA(At, 0, 1); PG8_STAGE(PG8_SA(0, 0), a2, voffA);
;       PG8_BAR; PG8_WAIT_L(0); PG8_MMA(1, 0, At, B0); PG8_BAR; PG8_SCHED;
.LBB0_831:
	s_add_i32 s26, s10, 2
	s_add_u32 s11, s8, 0xfe000080
	s_addc_u32 s12, s9, -1
	s_cmp_lg_u32 s25, s10
	s_cselect_b32 s13, s12, 0
	s_cselect_b32 s12, s11, 0
	s_add_u32 s10, s6, s12
	s_addc_u32 s11, s7, s13
	s_add_i32 s27, 16, 0x10000
	v_add_u32_e32 v146, s27, v92
	ds_read_b128 v[94:97], v146
	ds_read_b128 v[152:155], v146 offset:1024
	ds_read_b128 v[156:159], v146 offset:2048
	ds_read_b128 v[160:163], v146 offset:3072
	s_add_u32 s12, s4, s12
	s_addc_u32 s13, s5, s13
	v_lshl_add_u64 v[146:147], v[88:89], 0, s[8:9]
	s_add_i32 m0, s18, 0xc000
	ds_read_b128 v[164:167], v93
	ds_read_b128 v[168:171], v93 offset:1024
	ds_read_b128 v[172:175], v93 offset:2048
	ds_read_b128 v[186:189], v93 offset:3072
	ds_read_b128 v[190:193], v93 offset:4096
	ds_read_b128 v[198:201], v93 offset:5120
	ds_read_b128 v[202:205], v93 offset:6144
	ds_read_b128 v[206:209], v93 offset:7168
	global_load_lds_dwordx4 v[146:147], off
	v_lshl_add_u64 v[146:147], v[90:91], 0, s[8:9]
	s_add_i32 m0, s18, 0xe000
	s_nop 0
	global_load_lds_dwordx4 v[146:147], off
	s_waitcnt lgkmcnt(8)
	s_barrier
	s_waitcnt lgkmcnt(0)
	s_waitcnt lgkmcnt(0)
	v_mfma_f32_16x16x32_bf16 v[142:145], v[94:97], v[164:167], v[142:145]
	v_mfma_f32_16x16x32_bf16 v[138:141], v[156:159], v[164:167], v[138:141]
	v_mfma_f32_16x16x32_bf16 v[126:129], v[94:97], v[172:175], v[126:129]
	v_mfma_f32_16x16x32_bf16 v[122:125], v[156:159], v[172:175], v[122:125]
	v_mfma_f32_16x16x32_bf16 v[110:113], v[94:97], v[190:193], v[110:113]
	v_mfma_f32_16x16x32_bf16 v[106:109], v[156:159], v[190:193], v[106:109]
	v_mfma_f32_16x16x32_bf16 v[78:81], v[94:97], v[202:205], v[78:81]
	v_mfma_f32_16x16x32_bf16 v[74:77], v[156:159], v[202:205], v[74:77]
	v_mfma_f32_16x16x32_bf16 v[142:145], v[152:155], v[168:171], v[142:145]
	v_mfma_f32_16x16x32_bf16 v[138:141], v[160:163], v[168:171], v[138:141]
	v_mfma_f32_16x16x32_bf16 v[126:129], v[152:155], v[186:189], v[126:129]
	v_mfma_f32_16x16x32_bf16 v[122:125], v[160:163], v[186:189], v[122:125]
	v_mfma_f32_16x16x32_bf16 v[110:113], v[152:155], v[198:201], v[110:113]
	v_mfma_f32_16x16x32_bf16 v[106:109], v[160:163], v[198:201], v[106:109]
	v_mfma_f32_16x16x32_bf16 v[78:81], v[152:155], v[206:209], v[78:81]
	v_mfma_f32_16x16x32_bf16 v[74:77], v[160:163], v[206:209], v[74:77]
	s_barrier
	s_add_i32 s28, 16, 0x14000
	v_add_u32_e32 v146, s28, v92
	s_add_i32 s27, s27, s17
	ds_read_b128 v[214:217], v146
	ds_read_b128 v[218:221], v146 offset:1024
	ds_read_b128 v[222:225], v146 offset:2048
	ds_read_b128 v[226:229], v146 offset:3072
	v_lshl_add_u64 v[146:147], s[12:13], 0, v[0:1]
	s_mov_b32 m0, s27
	v_lshl_add_u64 v[176:177], s[12:13], 0, v[82:83]
	global_load_lds_dwordx4 v[146:147], off
	s_add_i32 m0, s27, 0x2000
	s_nop 0
	global_load_lds_dwordx4 v[176:177], off
	s_barrier
	s_waitcnt lgkmcnt(0)
	s_waitcnt lgkmcnt(0)
	v_mfma_f32_16x16x32_bf16 v[134:137], v[214:217], v[164:167], v[134:137]
	v_mfma_f32_16x16x32_bf16 v[130:133], v[222:225], v[164:167], v[130:133]
	v_mfma_f32_16x16x32_bf16 v[118:121], v[214:217], v[172:175], v[118:121]
	v_mfma_f32_16x16x32_bf16 v[114:117], v[222:225], v[172:175], v[114:117]
	v_mfma_f32_16x16x32_bf16 v[102:105], v[214:217], v[190:193], v[102:105]
	v_mfma_f32_16x16x32_bf16 v[98:101], v[222:225], v[190:193], v[98:101]
	v_mfma_f32_16x16x32_bf16 v[70:73], v[214:217], v[202:205], v[70:73]
	v_mfma_f32_16x16x32_bf16 v[66:69], v[222:225], v[202:205], v[66:69]
	v_mfma_f32_16x16x32_bf16 v[134:137], v[218:221], v[168:171], v[134:137]
	v_mfma_f32_16x16x32_bf16 v[130:133], v[226:229], v[168:171], v[130:133]
	v_mfma_f32_16x16x32_bf16 v[118:121], v[218:221], v[186:189], v[118:121]
	v_mfma_f32_16x16x32_bf16 v[114:117], v[226:229], v[186:189], v[114:117]
	v_mfma_f32_16x16x32_bf16 v[102:105], v[218:221], v[198:201], v[102:105]
	v_mfma_f32_16x16x32_bf16 v[98:101], v[226:229], v[198:201], v[98:101]
	v_mfma_f32_16x16x32_bf16 v[70:73], v[218:221], v[206:209], v[70:73]
	v_mfma_f32_16x16x32_bf16 v[66:69], v[226:229], v[206:209], v[66:69]
	s_mov_b32 m0, s18
	v_lshl_add_u64 v[230:231], s[10:11], 0, v[86:87]
	s_barrier
	ds_read_b128 v[164:167], v93 offset:16384
	ds_read_b128 v[168:171], v93 offset:17408
	ds_read_b128 v[172:175], v93 offset:18432
	ds_read_b128 v[186:189], v93 offset:19456
	ds_read_b128 v[190:193], v93 offset:20480
	ds_read_b128 v[198:201], v93 offset:21504
	ds_read_b128 v[202:205], v93 offset:22528
	ds_read_b128 v[206:209], v93 offset:23552
	global_load_lds_dwordx4 v[230:231], off
	v_lshl_add_u64 v[232:233], s[10:11], 0, v[84:85]
	s_mov_b32 m0, s19
	s_nop 0
	global_load_lds_dwordx4 v[232:233], off
	s_barrier
	s_waitcnt lgkmcnt(0)
	s_waitcnt lgkmcnt(0)
	v_mfma_f32_16x16x32_bf16 v[62:65], v[94:97], v[164:167], v[62:65]
	v_mfma_f32_16x16x32_bf16 v[58:61], v[156:159], v[164:167], v[58:61]
	v_mfma_f32_16x16x32_bf16 v[46:49], v[94:97], v[172:175], v[46:49]
	v_mfma_f32_16x16x32_bf16 v[42:45], v[156:159], v[172:175], v[42:45]
	v_mfma_f32_16x16x32_bf16 v[30:33], v[94:97], v[190:193], v[30:33]
	v_mfma_f32_16x16x32_bf16 v[26:29], v[156:159], v[190:193], v[26:29]
	v_mfma_f32_16x16x32_bf16 v[14:17], v[94:97], v[202:205], v[14:17]
	v_mfma_f32_16x16x32_bf16 v[10:13], v[156:159], v[202:205], v[10:13]
	v_mfma_f32_16x16x32_bf16 v[62:65], v[152:155], v[168:171], v[62:65]
	v_mfma_f32_16x16x32_bf16 v[58:61], v[160:163], v[168:171], v[58:61]
	v_mfma_f32_16x16x32_bf16 v[46:49], v[152:155], v[186:189], v[46:49]
	v_mfma_f32_16x16x32_bf16 v[42:45], v[160:163], v[186:189], v[42:45]
	v_mfma_f32_16x16x32_bf16 v[30:33], v[152:155], v[198:201], v[30:33]
	v_mfma_f32_16x16x32_bf16 v[26:29], v[160:163], v[198:201], v[26:29]
	v_mfma_f32_16x16x32_bf16 v[14:17], v[152:155], v[206:209], v[14:17]
	v_mfma_f32_16x16x32_bf16 v[10:13], v[160:163], v[206:209], v[10:13]
	s_barrier
; #define PG8_STAGE(bufoff, gbase, voff) do { _Pragma("unroll") for (int _i = 0; _i < 2; ++_i) \
;     __builtin_amdgcn_global_load_lds((const unsigned*)((const char*)(gbase) + (voff)[_i]), (LAS unsigned*)(lds + (bufoff) + ldsw + _i * 8192), 16, 0, 0); } while (0)
; #define PG8_LDA(dst, b, h) do { _Pragma("unroll") for (int m = 0; m < 4; ++m) _Pragma("unroll") for (int k = 0; k < 2; ++k) dst[m][k] = *(const LAS bf16x8*)(lds + PG8_SA(b, h) + aoff + m * 2048 + k * 1024); } while (0)
; #define PG8_LDB(dst, b, h) do { _Pragma("unroll") for (int n = 0; n < 2; ++n) _Pragma("unroll") for (int k = 0; k < 2; ++k) dst[n][k] = *(const LAS bf16x8*)(lds + PG8_SB(b, h) + boff + n * 2048 + k * 1024); } while (0)
; #define PG8_MMA(ai, bj, At, Bt) do { __builtin_amdgcn_s_setprio(1); _Pragma("unroll") for (int m = 0; m < 4; ++m) _Pragma("unroll") for (int n = 0; n < 2; ++n) _Pragma("unroll") for (int k = 0; k < 2; ++k) \
;     acc[ai][bj][m][n] = __builtin_amdgcn_mfma_f32_16x16x32_bf16(Bt[n][k], At[m][k], acc[ai][bj][m][n], 0, 0, 0); __builtin_amdgcn_s_setprio(0); } while (0)
; #define PG8_WAIT_V(n) asm volatile("s_waitcnt vmcnt(" #n ")" ::: "memory")
; #define PG8_WAIT_L(n) asm volatile("s_waitcnt lgkmcnt(" #n ")" ::: "memory")
; #define PG8_BAR __builtin_amdgcn_s_barrier()
; #define PG8_SCHED __builtin_amdgcn_sched_barrier(0)
; template <class Epi, class Sched>
; DI void gemm_phase(LAS unsigned char* lds, const Gemm g, const Sched& S, const Epi& E) {
;     ...
;       PG8_STAGE(PG8_SB(0, 1), b2 + hstepB, voffB);
;       PG8_WAIT_V(6); PG8_BAR; PG8_MMA(1, 1, At, B1); PG8_BAR;
;       PG8_LDB(B0, 1, 0); PG8_SCHED; PG8_LDA(At, 1, 0); PG8_STAGE(PG8_SA(0, 1), a2 + hstep, voffA);
;       PG8_WAIT_L(8); PG8_BAR; PG8_WAIT_L(0); PG8_MMA(0, 0, At, B0); PG8_BAR; PG8_SCHED;
;       PG8_LDB(B1, 1, 1); PG8_STAGE(PG8_SB(1, 0), b3, voffB);
;       PG8_BAR; PG8_WAIT_L(0); PG8_MMA(0, 1, At, B1); PG8_BAR;
	s_add_u32 s12, s12, s2
	s_addc_u32 s13, s13, s3
	s_add_i32 s27, s28, s17
	v_lshl_add_u64 v[234:235], s[12:13], 0, v[0:1]
	s_mov_b32 m0, s27
	v_lshl_add_u64 v[236:237], s[12:13], 0, v[82:83]
	global_load_lds_dwordx4 v[234:235], off
	s_add_i32 m0, s27, 0x2000
	s_nop 0
	global_load_lds_dwordx4 v[236:237], off
	s_waitcnt vmcnt(6)
	s_barrier
	v_mfma_f32_16x16x32_bf16 v[54:57], v[214:217], v[164:167], v[54:57]
	v_mfma_f32_16x16x32_bf16 v[50:53], v[222:225], v[164:167], v[50:53]
	v_mfma_f32_16x16x32_bf16 v[38:41], v[214:217], v[172:175], v[38:41]
	v_mfma_f32_16x16x32_bf16 v[34:37], v[222:225], v[172:175], v[34:37]
	v_mfma_f32_16x16x32_bf16 v[22:25], v[214:217], v[190:193], v[22:25]
	v_mfma_f32_16x16x32_bf16 v[18:21], v[222:225], v[190:193], v[18:21]
	v_mfma_f32_16x16x32_bf16 v[6:9], v[214:217], v[202:205], v[6:9]
	v_mfma_f32_16x16x32_bf16 v[2:5], v[222:225], v[202:205], v[2:5]
	v_mfma_f32_16x16x32_bf16 v[54:57], v[218:221], v[168:171], v[54:57]
	v_mfma_f32_16x16x32_bf16 v[50:53], v[226:229], v[168:171], v[50:53]
	v_mfma_f32_16x16x32_bf16 v[38:41], v[218:221], v[186:189], v[38:41]
	v_mfma_f32_16x16x32_bf16 v[34:37], v[226:229], v[186:189], v[34:37]
	v_mfma_f32_16x16x32_bf16 v[22:25], v[218:221], v[198:201], v[22:25]
	v_mfma_f32_16x16x32_bf16 v[18:21], v[226:229], v[198:201], v[18:21]
	v_mfma_f32_16x16x32_bf16 v[6:9], v[218:221], v[206:209], v[6:9]
	v_mfma_f32_16x16x32_bf16 v[2:5], v[226:229], v[206:209], v[2:5]
	s_add_i32 s12, 16, 0x18000
	v_add_u32_e32 v149, s12, v92
	s_barrier
	ds_read_b128 v[94:97], v149
	ds_read_b128 v[152:155], v149 offset:1024
	ds_read_b128 v[156:159], v149 offset:2048
	ds_read_b128 v[160:163], v149 offset:3072
	s_add_u32 s10, s10, s0
	s_addc_u32 s11, s11, s1
	s_mov_b32 m0, s20
	v_lshl_add_u64 v[214:215], s[10:11], 0, v[86:87]
	ds_read_b128 v[164:167], v93 offset:32768
	ds_read_b128 v[168:171], v93 offset:33792
	ds_read_b128 v[172:175], v93 offset:34816
	ds_read_b128 v[186:189], v93 offset:35840
	ds_read_b128 v[190:193], v93 offset:36864
	ds_read_b128 v[198:201], v93 offset:37888
	ds_read_b128 v[202:205], v93 offset:38912
	ds_read_b128 v[206:209], v93 offset:39936
	global_load_lds_dwordx4 v[214:215], off
	v_lshl_add_u64 v[214:215], s[10:11], 0, v[84:85]
	s_mov_b32 m0, s21
	s_nop 0
	global_load_lds_dwordx4 v[214:215], off
	s_waitcnt lgkmcnt(8)
	s_barrier
	s_waitcnt lgkmcnt(0)
	s_waitcnt lgkmcnt(0)
	v_mfma_f32_16x16x32_bf16 v[142:145], v[94:97], v[164:167], v[142:145]
	v_mfma_f32_16x16x32_bf16 v[138:141], v[156:159], v[164:167], v[138:141]
	v_mfma_f32_16x16x32_bf16 v[126:129], v[94:97], v[172:175], v[126:129]
	v_mfma_f32_16x16x32_bf16 v[122:125], v[156:159], v[172:175], v[122:125]
	v_mfma_f32_16x16x32_bf16 v[110:113], v[94:97], v[190:193], v[110:113]
	v_mfma_f32_16x16x32_bf16 v[106:109], v[156:159], v[190:193], v[106:109]
	v_mfma_f32_16x16x32_bf16 v[78:81], v[94:97], v[202:205], v[78:81]
	v_mfma_f32_16x16x32_bf16 v[74:77], v[156:159], v[202:205], v[74:77]
	v_mfma_f32_16x16x32_bf16 v[142:145], v[152:155], v[168:171], v[142:145]
	v_mfma_f32_16x16x32_bf16 v[138:141], v[160:163], v[168:171], v[138:141]
	v_mfma_f32_16x16x32_bf16 v[126:129], v[152:155], v[186:189], v[126:129]
	v_mfma_f32_16x16x32_bf16 v[122:125], v[160:163], v[186:189], v[122:125]
	v_mfma_f32_16x16x32_bf16 v[110:113], v[152:155], v[198:201], v[110:113]
	v_mfma_f32_16x16x32_bf16 v[106:109], v[160:163], v[198:201], v[106:109]
	v_mfma_f32_16x16x32_bf16 v[78:81], v[152:155], v[206:209], v[78:81]
	v_mfma_f32_16x16x32_bf16 v[74:77], v[160:163], v[206:209], v[74:77]
	s_barrier
	s_add_i32 s10, 16, 0x1c000
	s_add_i32 s11, s12, s17
	v_add_u32_e32 v149, s10, v92
	v_lshl_add_u64 v[146:147], v[146:147], 0, s[70:71]
	s_mov_b32 m0, s11
	ds_read_b128 v[214:217], v149
	ds_read_b128 v[218:221], v149 offset:1024
	ds_read_b128 v[222:225], v149 offset:2048
	ds_read_b128 v[226:229], v149 offset:3072
	global_load_lds_dwordx4 v[146:147], off
	v_lshl_add_u64 v[146:147], v[176:177], 0, s[70:71]
	s_add_i32 m0, s11, 0x2000
	s_nop 0
	global_load_lds_dwordx4 v[146:147], off
	s_barrier
; #define PG8_STAGE(bufoff, gbase, voff) do { _Pragma("unroll") for (int _i = 0; _i < 2; ++_i) \
;     __builtin_amdgcn_global_load_lds((const unsigned*)((const char*)(gbase) + (voff)[_i]), (LAS unsigned*)(lds + (bufoff) + ldsw + _i * 8192), 16, 0, 0); } while (0)
; #define PG8_LDA(dst, b, h) do { _Pragma("unroll") for (int m = 0; m < 4; ++m) _Pragma("unroll") for (int k = 0; k < 2; ++k) dst[m][k] = *(const LAS bf16x8*)(lds + PG8_SA(b, h) + aoff + m * 2048 + k * 1024); } while (0)
; #define PG8_MMA(ai, bj, At, Bt) do { __builtin_amdgcn_s_setprio(1); _Pragma("unroll") for (int m = 0; m < 4; ++m) _Pragma("unroll") for (int n = 0; n < 2; ++n) _Pragma("unroll") for (int k = 0; k < 2; ++k) \
;     acc[ai][bj][m][n] = __builtin_amdgcn_mfma_f32_16x16x32_bf16(Bt[n][k], At[m][k], acc[ai][bj][m][n], 0, 0, 0); __builtin_amdgcn_s_setprio(0); } while (0)
; #define PG8_WAIT_V(n) asm volatile("s_waitcnt vmcnt(" #n ")" ::: "memory")
; #define PG8_WAIT_L(n) asm volatile("s_waitcnt lgkmcnt(" #n ")" ::: "memory")
; #define PG8_BAR __builtin_amdgcn_s_barrier()
; #define PG8_SCHED __builtin_amdgcn_sched_barrier(0)
; template <class Epi, class Sched>
; DI void gemm_phase(LAS unsigned char* lds, const Gemm g, const Sched& S, const Epi& E) {
;     ...
;       PG8_BAR; PG8_WAIT_L(0); PG8_MMA(0, 1, At, B1); PG8_BAR;
;       PG8_LDA(At, 1, 1); PG8_STAGE(PG8_SA(1, 0), a3, voffA);
;       PG8_BAR; PG8_WAIT_L(0); PG8_MMA(1, 0, At, B0); PG8_BAR; PG8_SCHED;
;       PG8_STAGE(PG8_SB(1, 1), b3 + hstepB, voffB);
;       PG8_WAIT_V(6); PG8_BAR; PG8_MMA(1, 1, At, B1); PG8_BAR;
	s_waitcnt lgkmcnt(0)
	s_waitcnt lgkmcnt(0)
	v_mfma_f32_16x16x32_bf16 v[134:137], v[214:217], v[164:167], v[134:137]
	v_mfma_f32_16x16x32_bf16 v[130:133], v[222:225], v[164:167], v[130:133]
	v_mfma_f32_16x16x32_bf16 v[118:121], v[214:217], v[172:175], v[118:121]
	v_mfma_f32_16x16x32_bf16 v[114:117], v[222:225], v[172:175], v[114:117]
	v_mfma_f32_16x16x32_bf16 v[102:105], v[214:217], v[190:193], v[102:105]
	v_mfma_f32_16x16x32_bf16 v[98:101], v[222:225], v[190:193], v[98:101]
	v_mfma_f32_16x16x32_bf16 v[70:73], v[214:217], v[202:205], v[70:73]
	v_mfma_f32_16x16x32_bf16 v[66:69], v[222:225], v[202:205], v[66:69]
	v_mfma_f32_16x16x32_bf16 v[134:137], v[218:221], v[168:171], v[134:137]
	v_mfma_f32_16x16x32_bf16 v[130:133], v[226:229], v[168:171], v[130:133]
	v_mfma_f32_16x16x32_bf16 v[118:121], v[218:221], v[186:189], v[118:121]
	v_mfma_f32_16x16x32_bf16 v[114:117], v[226:229], v[186:189], v[114:117]
	v_mfma_f32_16x16x32_bf16 v[102:105], v[218:221], v[198:201], v[102:105]
	v_mfma_f32_16x16x32_bf16 v[98:101], v[226:229], v[198:201], v[98:101]
	v_mfma_f32_16x16x32_bf16 v[70:73], v[218:221], v[206:209], v[70:73]
	v_mfma_f32_16x16x32_bf16 v[66:69], v[226:229], v[206:209], v[66:69]
	s_mov_b32 m0, s22
	v_lshl_add_u64 v[146:147], v[230:231], 0, s[70:71]
	s_barrier
	ds_read_b128 v[164:167], v93 offset:49152
	ds_read_b128 v[168:171], v93 offset:50176
	ds_read_b128 v[172:175], v93 offset:51200
	ds_read_b128 v[186:189], v93 offset:52224
	ds_read_b128 v[190:193], v93 offset:53248
	ds_read_b128 v[198:201], v93 offset:54272
	ds_read_b128 v[202:205], v93 offset:55296
	ds_read_b128 v[206:209], v93 offset:56320
	global_load_lds_dwordx4 v[146:147], off
	v_lshl_add_u64 v[146:147], v[232:233], 0, s[70:71]
	s_mov_b32 m0, s23
	s_nop 0
	global_load_lds_dwordx4 v[146:147], off
	s_barrier
	s_waitcnt lgkmcnt(0)
	s_waitcnt lgkmcnt(0)
	v_mfma_f32_16x16x32_bf16 v[62:65], v[94:97], v[164:167], v[62:65]
	v_mfma_f32_16x16x32_bf16 v[58:61], v[156:159], v[164:167], v[58:61]
	v_mfma_f32_16x16x32_bf16 v[46:49], v[94:97], v[172:175], v[46:49]
	v_mfma_f32_16x16x32_bf16 v[42:45], v[156:159], v[172:175], v[42:45]
	v_mfma_f32_16x16x32_bf16 v[30:33], v[94:97], v[190:193], v[30:33]
	v_mfma_f32_16x16x32_bf16 v[26:29], v[156:159], v[190:193], v[26:29]
	v_mfma_f32_16x16x32_bf16 v[14:17], v[94:97], v[202:205], v[14:17]
	v_mfma_f32_16x16x32_bf16 v[10:13], v[156:159], v[202:205], v[10:13]
	v_mfma_f32_16x16x32_bf16 v[62:65], v[152:155], v[168:171], v[62:65]
	v_mfma_f32_16x16x32_bf16 v[58:61], v[160:163], v[168:171], v[58:61]
	v_mfma_f32_16x16x32_bf16 v[46:49], v[152:155], v[186:189], v[46:49]
	v_mfma_f32_16x16x32_bf16 v[42:45], v[160:163], v[186:189], v[42:45]
	v_mfma_f32_16x16x32_bf16 v[30:33], v[152:155], v[198:201], v[30:33]
	v_mfma_f32_16x16x32_bf16 v[26:29], v[160:163], v[198:201], v[26:29]
	v_mfma_f32_16x16x32_bf16 v[14:17], v[152:155], v[206:209], v[14:17]
	v_mfma_f32_16x16x32_bf16 v[10:13], v[160:163], v[206:209], v[10:13]
	s_barrier
	s_add_i32 s10, s10, s17
	v_lshl_add_u64 v[94:95], v[234:235], 0, s[70:71]
	s_mov_b32 m0, s10
	s_nop 0
	global_load_lds_dwordx4 v[94:95], off
	v_lshl_add_u64 v[94:95], v[236:237], 0, s[70:71]
	s_add_i32 m0, s10, 0x2000
	s_nop 0
	global_load_lds_dwordx4 v[94:95], off
	s_waitcnt vmcnt(6)
	s_barrier
	v_mfma_f32_16x16x32_bf16 v[54:57], v[214:217], v[164:167], v[54:57]
	v_mfma_f32_16x16x32_bf16 v[50:53], v[222:225], v[164:167], v[50:53]
	v_mfma_f32_16x16x32_bf16 v[38:41], v[214:217], v[172:175], v[38:41]
	v_mfma_f32_16x16x32_bf16 v[34:37], v[222:225], v[172:175], v[34:37]
	v_mfma_f32_16x16x32_bf16 v[22:25], v[214:217], v[190:193], v[22:25]
	v_mfma_f32_16x16x32_bf16 v[18:21], v[222:225], v[190:193], v[18:21]
	v_mfma_f32_16x16x32_bf16 v[6:9], v[214:217], v[202:205], v[6:9]
	v_mfma_f32_16x16x32_bf16 v[2:5], v[222:225], v[202:205], v[2:5]
	v_mfma_f32_16x16x32_bf16 v[54:57], v[218:221], v[168:171], v[54:57]
	v_mfma_f32_16x16x32_bf16 v[50:53], v[226:229], v[168:171], v[50:53]
	v_mfma_f32_16x16x32_bf16 v[38:41], v[218:221], v[186:189], v[38:41]
	v_mfma_f32_16x16x32_bf16 v[34:37], v[226:229], v[186:189], v[34:37]
	v_mfma_f32_16x16x32_bf16 v[22:25], v[218:221], v[198:201], v[22:25]
	v_mfma_f32_16x16x32_bf16 v[18:21], v[226:229], v[198:201], v[18:21]
	v_mfma_f32_16x16x32_bf16 v[6:9], v[218:221], v[206:209], v[6:9]
	v_mfma_f32_16x16x32_bf16 v[2:5], v[226:229], v[206:209], v[2:5]
	s_add_u32 s8, s8, 0x100
	s_addc_u32 s9, s9, 0
	s_cmp_ge_i32 s26, s24
	s_mov_b32 s10, s26
	s_barrier
	s_cbranch_scc0 .LBB0_831
